# FoX attention loop software-pipelined: QK(t) MFMAs interleaved with softmax VALU of tile t-1, PV(t-1) with rowmax of tile t; V in 3-slot LDS ring; lazy O rescale
# speedup vs baseline: 1.0137x; 1.0137x over previous
_Z4mega4Args:
	s_load_dwordx8 s[52:59], s[0:1], 0xa0
	s_load_dwordx8 s[60:67], s[0:1], 0x80
	s_load_dword s3, s[0:1], 0xc0
	s_add_u32 s6, s0, 0xb8
	v_and_b32_e32 v255, 0x3ff, v0
	s_addc_u32 s7, s1, 0
	v_cmp_gt_u32_e32 vcc, 4, v255
	s_waitcnt lgkmcnt(0)
	v_writelane_b32 v254, s3, 0
	s_and_saveexec_b64 s[4:5], vcc
	v_lshl_add_u32 v1, v255, 2, 0
	v_add_u32_e32 v1, 0x23000, v1
	v_mov_b32_e32 v2, 0
	ds_write_b32 v1, v2
	s_or_b64 exec, exec, s[4:5]
	s_and_b32 s3, s58, 7
	s_cmp_lg_u32 s3, 0
	s_cselect_b64 s[30:31], -1, 0
	s_and_b64 vcc, exec, s[30:31]
	s_mov_b32 s88, s2
	s_waitcnt lgkmcnt(0)
	s_barrier
	s_cbranch_vccz .LBB0_4
	s_cmp_gt_i32 s56, -1
	s_cbranch_scc1 .LBB0_16
	s_branch .LBB0_5

.LBB0_5:
	v_lshrrev_b32_e32 v1, 20, v0
	v_lshrrev_b32_e32 v0, 10, v0
	v_or_b32_e32 v0, v0, v1
	s_movk_i32 s3, 0x3ff
	v_and_or_b32 v0, v0, s3, v255
	v_cmp_eq_u32_e32 vcc, 0, v0
	s_barrier
	s_and_saveexec_b64 s[4:5], vcc
	s_cbranch_execz .LBB0_15
	buffer_wbl2 sc1
	s_load_dwordx2 s[6:7], s[6:7], 0x58
	s_mov_b64 s[8:9], exec
	v_mbcnt_lo_u32_b32 v0, s8, 0
	v_mbcnt_hi_u32_b32 v0, s9, v0
	v_cmp_eq_u32_e32 vcc, 0, v0
	s_waitcnt lgkmcnt(0)
	s_load_dword s3, s[6:7], 0x28
	s_and_saveexec_b64 s[10:11], vcc
	s_cbranch_execz .LBB0_8
	s_bcnt1_i32_b64 s8, s[8:9]
	v_mov_b32_e32 v1, 0
	v_mov_b32_e32 v2, s8
	global_atomic_add v1, v1, v2, s[6:7] offset:32 sc0

.LBB0_16:
	s_add_u32 s28, s54, 0x80000
	s_getreg_b32 s3, hwreg(HW_REG_XCC_ID, 0, 4)
	s_addc_u32 s29, s55, 0
	s_and_b32 s3, s3, 15
	v_cmp_eq_u32_e64 s[8:9], 0, v255
	s_and_saveexec_b64 s[4:5], s[8:9]
	s_cbranch_execz .LBB0_19
	s_mov_b64 s[6:7], exec
	v_mbcnt_lo_u32_b32 v0, s6, 0
	v_mbcnt_hi_u32_b32 v0, s7, v0
	v_cmp_eq_u32_e32 vcc, 0, v0
	s_and_b64 s[10:11], exec, vcc
	s_mov_b64 exec, s[10:11]
	s_cbranch_execz .LBB0_19
	s_lshl_b32 s10, s3, 8
	s_bcnt1_i32_b64 s6, s[6:7]
	v_mov_b32_e32 v0, s10
	v_mov_b32_e32 v1, s6
	global_atomic_add v0, v1, s[28:29] offset:1024
.LBB0_19:
	s_or_b64 exec, exec, s[4:5]
	s_load_dwordx16 s[36:51], s[0:1], 0x0
	s_load_dwordx16 s[12:27], s[0:1], 0x40
	s_cmp_lt_i32 s56, 1
	s_cselect_b64 s[0:1], -1, 0
	s_cmp_gt_i32 s57, 0
	s_cselect_b64 s[4:5], -1, 0
	s_and_b64 s[4:5], s[0:1], s[4:5]
	s_andn2_b64 vcc, exec, s[4:5]
	s_cbranch_vccnz .LBB0_88
	v_readfirstlane_b32 s0, v255
	s_lshl_b32 s1, s2, 3
	s_lshr_b32 s0, s0, 6
	s_lshl_b32 s6, s58, 3
	s_add_i32 s10, s0, s1
	v_and_b32_e32 v42, 63, v255
	s_cmpk_gt_i32 s10, 0x4a3f
	v_mov_b32_e32 v5, 0
	s_cbranch_scc1 .LBB0_61
	s_add_u32 s34, s54, 0x4500000
	v_lshlrev_b32_e32 v4, 12, v42
	s_addc_u32 s35, s55, 0
	v_lshl_add_u64 v[0:1], s[54:55], 0, v[4:5]
	s_mov_b64 s[68:69], 0x4400000
	v_lshl_add_u64 v[6:7], v[0:1], 0, s[68:69]
	s_add_u32 s68, s54, 0x2400000
	s_addc_u32 s69, s55, 0
	s_add_u32 s70, s54, 0x1c00000
	s_addc_u32 s71, s55, 0
	s_add_u32 s72, s54, 0x1a00000
	s_addc_u32 s73, s55, 0
	s_add_u32 s74, s54, 0x200000
	s_addc_u32 s75, s55, 0
	v_lshlrev_b32_e32 v4, 2, v42
	v_lshl_add_u64 v[0:1], s[60:61], 0, v[4:5]
	s_mov_b64 s[76:77], 0x8000
	s_waitcnt lgkmcnt(0)
	s_cmp_lg_u64 s[26:27], 0
	v_lshl_add_u64 v[8:9], v[0:1], 0, s[76:77]
	s_cselect_b64 s[76:77], -1, 0
	s_cmp_lg_u64 s[38:39], 0
	s_cselect_b64 s[78:79], -1, 0
	s_lshl_b32 s1, s2, 8
	s_lshl_b32 s7, s0, 5
	s_add_i32 s7, s1, s7
	s_lshl_b32 s1, s2, 4
	s_lshl_b32 s0, s0, 1
	v_or_b32_e32 v43, 0xffffbdc0, v42
	v_or_b32_e32 v44, 0xffffde00, v42
	v_or_b32_e32 v45, 0xffffe600, v42
	v_or_b32_e32 v46, 0xffffd000, v42
	s_lshl_b32 s11, s58, 8
	s_add_i32 s89, s1, s0
	s_lshl_b32 s90, s58, 4
	s_movk_i32 s91, 0x800
	s_movk_i32 s92, 0x2000
	v_mov_b32_e32 v47, 0x8040
	s_mov_b32 s93, 0x60000
	s_mov_b32 s94, 0x78000
	s_mov_b32 s95, 0x90000
	s_mov_b32 s96, 0xa8000
	s_movk_i32 s97, 0x1800
	s_mov_b32 s33, s10
	v_cmp_gt_u32_e64 s[0:1], 16, v42
	s_mov_b32 s81, 0
	s_branch .LBB0_23

.LBB0_66:
	v_lshl_add_u32 v4, s2, 9, v255
	s_movk_i32 s0, 0x1000
	v_cmp_gt_i32_e32 vcc, s0, v4
	s_lshl_b32 s33, s58, 9
	s_and_saveexec_b64 s[0:1], vcc
	s_cbranch_execz .LBB0_75
	s_add_u32 s6, s54, 0x100000
	s_waitcnt lgkmcnt(0)
	s_mov_b32 s20, 0x652b82fe
	s_mov_b32 s24, 0xfee00000
	s_mov_b32 s26, 0x35793c76
	v_mov_b32_e32 v6, 0xb7789f5c
	s_mov_b32 s34, 0x67f544e4
	s_mov_b32 s36, 0xa556c734
	s_mov_b32 s38, 0x1a01a01a
	s_waitcnt vmcnt(3)
	v_mov_b32_e32 v11, 0x3f2a01a0
	v_mov_b32_e32 v14, 0x16c16c17
	s_mov_b32 s40, 0x11111111
	s_mov_b32 s60, 0x55555555
	v_mov_b32_e32 v19, 0x3fc55555
	s_mov_b32 s64, 0x6dc9c883
	s_mov_b32 s68, 0x54400000
	s_mov_b32 s70, 0x1a626331
	s_mov_b32 s72, 0x13a86d09
	s_mov_b32 s74, 0xa8c07c9d
	s_addc_u32 s7, s55, 0
	s_mov_b64 s[10:11], 0
	s_mov_b32 s21, 0x3ff71547
	s_mov_b32 s25, 0xbfe62e42
	s_mov_b32 s27, 0xbdea39ef
	v_mov_b32_e32 v7, 0x3e927e4f
	s_mov_b32 s35, 0x3e5ae645
	s_mov_b32 s37, 0x3ec71de3
	s_mov_b32 s39, 0x3efa01a0
	v_mov_b32_e32 v8, 0x1a01a01a
	v_mov_b32_e32 v12, 0x1a01a01a
	v_mov_b32_e32 v13, v11
	v_mov_b32_e32 v15, 0x3f56c16c
	s_mov_b32 s41, 0x3f811111
	s_mov_b32 s61, 0x3fa55555
	v_mov_b32_e32 v16, 0x55555555
	v_mov_b32_e32 v20, 0x55555555
	v_mov_b32_e32 v21, v19
	v_mov_b32_e32 v5, 0x3ff00000
	v_mov_b32_e32 v2, 0
	s_mov_b32 s65, 0x3fe45f30
	s_mov_b32 s69, 0xbff921fb
	s_mov_b32 s71, 0xbdd0b461
	v_mov_b32_e32 v22, 0x67f544e4
	v_mov_b32_e32 v23, 0xbe5ae645
	s_mov_b32 s73, 0x3de61246
	v_mov_b32_e32 v25, 0xbf2a01a0
	v_mov_b32_e32 v24, 0x1a01a01a
	v_mov_b32_e32 v27, 0xbfc55555
	v_mov_b32_e32 v26, 0x55555555
	v_mov_b32_e32 v28, 0xeff8d898
	v_mov_b32_e32 v29, 0x3e21eed8
	s_mov_b32 s75, 0xbda93974
	v_mov_b32_e32 v31, 0xbe927e4f
	v_mov_b32_e32 v30, v6
	v_mov_b32_e32 v33, 0xbf56c16c
	v_mov_b32_e32 v32, v14
	s_movk_i32 s80, 0xfff
	v_mov_b32_e32 v34, 0xa556c734
	v_mov_b32_e32 v35, 0x3ec71de3
	v_mov_b32_e32 v9, 0x3efa01a0
	v_mov_b32_e32 v36, 0x11111111
	v_mov_b32_e32 v37, 0x3f811111
	v_mov_b32_e32 v17, 0x3fa55555
	v_mov_b32_e32 v38, v4
	s_branch .LBB0_70

.LBB0_78:
	s_or_b64 exec, exec, s[0:1]
	s_cmp_lg_u32 s2, 0
	s_cbranch_scc1 .LBB0_88
	s_add_u32 s6, s54, 0x50000
	v_lshlrev_b32_e32 v1, 2, v255
	s_addc_u32 s7, s55, 0
	v_lshrrev_b32_e32 v0, 9, v255
	v_mov_b32_e32 v2, 0
	v_add_u32_e32 v3, 0x800, v1
	v_xor_b32_e32 v0, 7, v0
	global_store_dword v1, v2, s[6:7]
	global_store_dword v3, v2, s[6:7]
	v_or_b32_e32 v3, 0x1000, v1
	v_add_u32_e32 v1, 0x1800, v1
	global_store_dword v3, v2, s[6:7]
	global_store_dword v1, v2, s[6:7]
	v_add_u32_e32 v1, 0xa00, v255
	v_or_b32_e32 v3, 0x800, v255
	v_cmp_lt_u32_e32 vcc, 4, v0
	v_cmp_lt_u32_e64 s[0:1], 3, v0
	s_and_saveexec_b64 s[10:11], s[0:1]
	s_cbranch_execz .LBB0_81
	v_lshlrev_b32_e32 v3, 2, v3
	global_store_dword v3, v2, s[6:7]

.LBB0_83:
	s_or_b64 exec, exec, s[0:1]
	v_add_u32_e32 v1, 0xe00, v255
	v_or_b32_e32 v2, 0xc00, v255
	v_cmp_lt_u32_e32 vcc, 6, v0
	v_cmp_lt_u32_e64 s[0:1], 5, v0
	v_mov_b32_e32 v0, 0
	s_and_saveexec_b64 s[10:11], s[0:1]
	s_cbranch_execz .LBB0_85
	v_lshlrev_b32_e32 v2, 2, v2
	global_store_dword v2, v0, s[6:7]

.LBB0_88:
	s_cmp_gt_i32 s57, 1
	s_cselect_b64 s[0:1], -1, 0
	s_and_b64 s[4:5], s[4:5], s[0:1]
	s_andn2_b64 vcc, exec, s[4:5]
	s_cbranch_vccnz .LBB0_142
	s_waitcnt vmcnt(0)
	s_waitcnt lgkmcnt(0)
	s_barrier
	s_and_saveexec_b64 s[4:5], s[8:9]
	s_cbranch_execz .LBB0_141
	s_add_i32 s6, 0, 0x23000
	v_mov_b32_e32 v0, s6
	s_waitcnt vmcnt(0) expcnt(0) lgkmcnt(0)
	ds_read_b32 v2, v0
	s_add_i32 s6, 0, 0x23004
	v_mov_b32_e32 v0, s6
	ds_read_b32 v0, v0
	s_waitcnt lgkmcnt(1)
	v_cmp_ne_u32_e32 vcc, 0, v2
	s_cbranch_vccnz .LBB0_105
	v_readlane_b32 s6, v254, 0
	s_mul_i32 s33, s59, s6
	s_add_u32 s6, s54, 0x80200
	s_addc_u32 s7, s55, 0
	s_add_u32 s10, s54, 0x80400
	s_addc_u32 s11, s55, 0
	s_add_u32 s20, s54, 0x80500
	s_addc_u32 s21, s55, 0
	s_add_u32 s24, s54, 0x80600
	s_addc_u32 s25, s55, 0
	s_add_u32 s26, s54, 0x80700
	s_addc_u32 s27, s55, 0
	s_add_u32 s34, s54, 0x80800
	s_addc_u32 s35, s55, 0
	s_add_u32 s36, s54, 0x80900
	s_addc_u32 s37, s55, 0
	s_add_u32 s38, s54, 0x80a00
	s_addc_u32 s39, s55, 0
	s_add_u32 s40, s54, 0x80b00
	s_addc_u32 s41, s55, 0
	s_add_u32 s44, s54, 0x80c00
	s_addc_u32 s45, s55, 0
	s_add_u32 s46, s54, 0x80d00
	s_addc_u32 s47, s55, 0
	s_add_u32 s48, s54, 0x80e00
	s_addc_u32 s49, s55, 0
	s_add_u32 s60, s54, 0x80f00
	s_addc_u32 s61, s55, 0
	s_add_u32 s64, s54, 0x81000
	s_addc_u32 s65, s55, 0
	s_add_u32 s68, s54, 0x81100
	s_addc_u32 s69, s55, 0
	s_add_u32 s70, s54, 0x81200
	s_addc_u32 s71, s55, 0
	s_add_u32 s72, s54, 0x81300
	s_mul_i32 s33, s33, s58
	s_addc_u32 s73, s55, 0
	s_mov_b32 s80, 1
	v_mov_b32_e32 v16, 0
	s_branch .LBB0_93

.LBB0_142:
	s_cmp_lt_i32 s56, 2
	s_cselect_b64 s[4:5], -1, 0
	s_and_b64 s[6:7], s[4:5], s[0:1]
	s_andn2_b64 vcc, exec, s[6:7]
	s_cbranch_vccnz .LBB0_159
	s_cmpk_gt_i32 s2, 0x5ff
	v_readfirstlane_b32 s1, v255
	s_cbranch_scc1 .LBB0_159
	v_lshrrev_b32_e32 v2, 1, v255
	s_waitcnt vmcnt(3)
	v_and_b32_e32 v11, 24, v2
	v_lshrrev_b32_e32 v2, 5, v255
	v_and_b32_e32 v2, 4, v2
	v_bfe_u32 v3, v255, 2, 2
	s_add_u32 s33, s54, 0x5600000
	v_lshlrev_b32_e32 v0, 4, v255
	v_and_b32_e32 v1, 32, v255
	v_bfe_u32 v10, v255, 2, 4
	v_or3_b32 v2, v2, v3, v11
	v_lshrrev_b32_e32 v3, 3, v255
	s_movk_i32 s0, 0x70
	s_addc_u32 s60, s55, 0
	v_bitop3_b32 v8, v0, v1, 48 bitop3:0x6c
	v_and_b32_e32 v9, 64, v255
	v_and_or_b32 v4, v3, s0, v10
	s_movk_i32 s0, 0x60
	s_waitcnt lgkmcnt(0)
	v_add_u32_e32 v12, 0x2000, v0
	s_add_u32 s61, s54, 0x200000
	v_or_b32_e32 v1, v8, v9
	v_and_or_b32 v3, v3, s0, v2
	v_lshrrev_b32_e32 v0, 7, v12
	s_movk_i32 s0, 0xf0
	s_addc_u32 s64, s55, 0
	v_lshl_or_b32 v130, v3, 12, v1
	v_and_or_b32 v3, v0, s0, v10
	s_movk_i32 s0, 0xe0
	s_ashr_i32 s68, s2, 31
	v_and_or_b32 v0, v0, s0, v2
	s_lshr_b32 s0, s68, 29
	s_add_i32 s0, s2, s0
	s_lshr_b32 s24, s1, 6
	s_ashr_i32 s4, s0, 3
	s_and_b32 s0, s0, -8
	s_lshr_b32 s26, s1, 8
	s_lshl_b32 s65, s24, 10
	s_sub_i32 s0, s2, s0
	s_cmp_lt_i32 s0, 0
	s_movk_i32 s69, 0xc1
	s_cselect_b32 s5, s69, 0xc0
	s_mul_i32 s0, s0, s5
	s_add_i32 s0, s0, s4
	s_mul_hi_i32 s4, s0, 0x2aaaaaab
	s_lshr_b32 s5, s4, 31
	s_ashr_i32 s4, s4, 5
	s_add_i32 s4, s4, s5
	s_lshl_b32 s5, s4, 3
	s_mulk_i32 s4, 0xc0
	s_sub_i32 s4, s0, s4
	s_sext_i32_i16 s0, s4
	s_bfe_u32 s0, s0, 0x3001c
	s_add_i32 s10, s4, s0
	s_sext_i32_i16 s0, s10
	s_and_b32 s10, s10, 0xfff8
	s_sub_i32 s4, s4, s10
	s_sext_i32_i16 s4, s4
	s_lshr_b32 s0, s0, 3
	s_add_i32 s4, s5, s4
	s_ashr_i32 s5, s4, 31
	s_bfe_i64 s[20:21], s[0:1], 0x100000
	s_lshl_b64 s[10:11], s[4:5], 20
	s_lshl_b64 s[20:21], s[20:21], 20
	s_add_u32 s46, s61, s20
	s_addc_u32 s47, s64, s21
	s_add_i32 s70, s65, 0
	s_add_i32 m0, s70, 0x10000
	v_lshl_or_b32 v134, v0, 12, v1
	global_load_lds_dwordx4 v130, s[46:47]
	s_add_i32 m0, s70, 0x12000
	s_add_u32 s20, s46, 0x80000
	global_load_lds_dwordx4 v134, s[46:47]
	s_addc_u32 s21, s47, 0
	s_add_i32 m0, s70, 0x14000
	v_lshl_or_b32 v128, v4, 12, v1
	global_load_lds_dwordx4 v130, s[20:21]
	s_add_i32 m0, s70, 0x16000
	s_add_u32 s44, s33, s10
	s_addc_u32 s45, s60, s11
	s_add_i32 s71, s70, 0x2000
	global_load_lds_dwordx4 v134, s[20:21]
	s_mov_b32 m0, s70
	s_add_u32 s10, s44, 0x80000
	v_lshl_or_b32 v132, v3, 12, v1
	global_load_lds_dwordx4 v128, s[44:45]
	s_mov_b32 m0, s71
	s_addc_u32 s11, s45, 0
	s_add_i32 s72, s70, 0x4000
	global_load_lds_dwordx4 v132, s[44:45]
	s_mov_b32 m0, s72
	s_add_i32 s73, s70, 0x6000
	global_load_lds_dwordx4 v128, s[10:11]
	s_mov_b32 m0, s73
	v_mov_b32_e32 v131, 0
	global_load_lds_dwordx4 v132, s[10:11]
	v_mov_b32_e32 v135, v131
	v_mov_b32_e32 v129, v131
	v_mov_b32_e32 v133, v131
	s_cmp_eq_u32 s26, 1
	s_mov_b32 s74, 0
	v_lshl_add_u64 v[6:7], s[46:47], 0, v[130:131]
	v_lshl_add_u64 v[4:5], s[46:47], 0, v[134:135]
	v_lshl_add_u64 v[0:1], s[44:45], 0, v[128:129]
	s_cselect_b64 s[10:11], -1, 0
	s_cmp_lg_u32 s26, 1
	v_lshl_add_u64 v[2:3], s[44:45], 0, v[132:133]
	s_cbranch_scc1 .LBB0_146
	s_barrier
.LBB0_146:
	s_add_u32 s20, s54, 0x9600000
	s_addc_u32 s21, s55, 0
	s_lshl_b32 s5, s24, 5
	s_mov_b64 s[24:25], 0x80
	s_and_b32 s36, s5, 0x60
	s_add_i32 m0, s70, 0x18000
	v_lshl_add_u64 v[6:7], v[6:7], 0, s[24:25]
	s_ashr_i32 s75, s58, 31
	s_lshl_b32 s27, s26, 13
	s_lshl_b32 s37, s36, 7
	s_waitcnt vmcnt(2)
	s_barrier
	global_load_lds_dwordx4 v[6:7], off
	v_lshl_add_u64 v[4:5], v[4:5], 0, s[24:25]
	s_add_i32 m0, s70, 0x1a000
	s_add_i32 s76, s70, 0x8000
	s_add_i32 s77, s70, 0xa000
	global_load_lds_dwordx4 v[4:5], off
	v_lshl_add_u64 v[0:1], v[0:1], 0, s[24:25]
	s_mov_b32 m0, s76
	s_add_u32 s34, s46, 0x80080
	global_load_lds_dwordx4 v[0:1], off
	v_lshl_add_u64 v[0:1], v[2:3], 0, s[24:25]
	s_mov_b32 m0, s77
	s_addc_u32 s35, s47, 0
	global_load_lds_dwordx4 v[0:1], off
	s_add_i32 m0, s70, 0x1c000
	v_lshl_add_u64 v[0:1], s[34:35], 0, v[130:131]
	global_load_lds_dwordx4 v[0:1], off
	v_lshl_add_u64 v[0:1], s[34:35], 0, v[134:135]
	s_add_i32 m0, s70, 0x1e000
	s_sext_i32_i16 s5, s0
	global_load_lds_dwordx4 v[0:1], off
	v_and_b32_e32 v0, 15, v255
	v_lshlrev_b32_e32 v1, 1, v11
	v_lshlrev_b32_e32 v2, 6, v255
	s_movk_i32 s0, 0x3c0
	v_lshlrev_b32_e32 v3, 2, v255
	v_and_or_b32 v2, v2, s0, v1
	v_and_b32_e32 v3, 32, v3
	v_lshl_or_b32 v152, s26, 6, v0
	v_lshl_or_b32 v0, v0, 6, v1
	v_lshlrev_b32_e32 v1, 9, v255
	v_bitop3_b32 v153, s37, v2, v3 bitop3:0xf6
	v_and_b32_e32 v1, 0x70000, v1
	v_lshlrev_b32_e32 v2, 12, v10
	v_or3_b32 v1, v8, v1, v2
	v_add_u32_e32 v136, v1, v9
	v_lshlrev_b32_e32 v1, 5, v12
	s_waitcnt vmcnt(6)
	s_cmpk_lt_u32 s1, 0x100
	v_and_b32_e32 v1, 0xf0000, v1
	v_bitop3_b32 v0, v0, s27, v3 bitop3:0xde
	s_cselect_b64 s[26:27], -1, 0
	v_or3_b32 v1, v8, v1, v2
	s_add_i32 s79, 0, 0x10000
	s_add_i32 s80, 0, 0x14000
	s_mov_b32 s78, s58
	v_or_b32_e32 v154, s36, v11
	v_mov_b32_e32 v137, v131
	v_add_u32_e32 v138, v1, v9
	v_mov_b32_e32 v139, v131
	v_mov_b64_e32 v[140:141], 0x600
	v_mov_b64_e32 v[142:143], 0x5ff
	v_add_u32_e32 v155, s79, v153
	v_add_u32_e32 v156, s80, v153
	v_add_u32_e32 v157, 0, v0
	v_mov_b32_e32 v158, 0x358637bd
	s_mov_b32 s81, 0xf800000
	v_mov_b32_e32 v159, 0x260
	s_movk_i32 s82, 0x3000
	v_mov_b32_e32 v160, 0x3e38aa3b
	s_barrier
	s_branch .LBB0_149

.LBB0_159:
	s_cmp_gt_i32 s57, 2
	s_cselect_b64 s[0:1], -1, 0
	s_and_b64 s[4:5], s[6:7], s[0:1]
	s_andn2_b64 vcc, exec, s[4:5]
	s_cbranch_vccnz .LBB0_213
	s_waitcnt vmcnt(0)
	s_waitcnt lgkmcnt(0)
	s_barrier
	s_and_saveexec_b64 s[4:5], s[8:9]
	s_cbranch_execz .LBB0_212
	s_add_i32 s6, 0, 0x23000
	v_mov_b32_e32 v0, s6
	s_waitcnt vmcnt(0) expcnt(0) lgkmcnt(0)
	ds_read_b32 v2, v0
	s_add_i32 s6, 0, 0x23004
	v_mov_b32_e32 v0, s6
	ds_read_b32 v0, v0
	s_waitcnt lgkmcnt(1)
	v_cmp_ne_u32_e32 vcc, 0, v2
	s_cbranch_vccnz .LBB0_176
	v_readlane_b32 s6, v254, 0
	s_mul_i32 s33, s59, s6
	s_add_u32 s6, s54, 0x80200
	s_addc_u32 s7, s55, 0
	s_add_u32 s10, s54, 0x80400
	s_addc_u32 s11, s55, 0
	s_add_u32 s20, s54, 0x80500
	s_addc_u32 s21, s55, 0
	s_add_u32 s24, s54, 0x80600
	s_addc_u32 s25, s55, 0
	s_add_u32 s26, s54, 0x80700
	s_addc_u32 s27, s55, 0
	s_add_u32 s34, s54, 0x80800
	s_addc_u32 s35, s55, 0
	s_add_u32 s36, s54, 0x80900
	s_addc_u32 s37, s55, 0
	s_add_u32 s38, s54, 0x80a00
	s_addc_u32 s39, s55, 0
	s_add_u32 s40, s54, 0x80b00
	s_addc_u32 s41, s55, 0
	s_add_u32 s44, s54, 0x80c00
	s_addc_u32 s45, s55, 0
	s_add_u32 s46, s54, 0x80d00
	s_addc_u32 s47, s55, 0
	s_add_u32 s48, s54, 0x80e00
	s_addc_u32 s49, s55, 0
	s_add_u32 s60, s54, 0x80f00
	s_addc_u32 s61, s55, 0
	s_add_u32 s64, s54, 0x81000
	s_addc_u32 s65, s55, 0
	s_add_u32 s68, s54, 0x81100
	s_addc_u32 s69, s55, 0
	s_add_u32 s70, s54, 0x81200
	s_addc_u32 s71, s55, 0
	s_add_u32 s72, s54, 0x81300
	s_mul_i32 s33, s33, s58
	s_addc_u32 s73, s55, 0
	s_mov_b32 s80, 1
	v_mov_b32_e32 v16, 0
	s_branch .LBB0_164

.LBB0_217:
	s_mov_b32 s6, s45
	s_and_b32 s36, s68, 15
	s_ashr_i32 s24, s68, 8
	s_bfe_u32 s45, s68, 0x40004
	v_mov_b32_e32 v108, v255
	s_cmp_lg_u32 s6, s45
	s_cselect_b64 s[34:35], -1, 0
	v_readfirstlane_b32 s70, v108
	s_ashr_i32 s69, s70, 6
	s_ashr_i32 s25, s24, 31
	s_lshl_b64 s[26:27], s[24:25], 12
	s_lshl_b32 s6, s36, 8
	s_lshl_b32 s72, s69, 5
	s_lshl_b32 s71, s36, 2
	s_or_b32 s6, s26, s6
	s_ashr_i32 s25, s72, 31
	v_and_b32_e32 v34, 31, v108
	s_mul_hi_i32 s36, s24, 0x3000000
	s_mul_i32 s37, s24, 0x3000000
	s_add_u32 s24, s6, s72
	v_or_b32_e32 v0, s24, v34
	s_addc_u32 s25, s27, s25
	v_mad_u64_u32 v[0:1], s[26:27], v0, s44, v[104:105]
	v_bfe_u32 v35, v108, 5, 1
	v_mad_i32_i24 v1, s25, v111, v1
	s_lshl_b32 s6, s45, 7
	v_lshl_add_u64 v[0:1], v[0:1], 0, s[6:7]
	v_lshlrev_b32_e32 v106, 4, v35
	v_lshl_add_u64 v[0:1], v[0:1], 0, v[106:107]
	global_load_dwordx4 v[64:67], v[0:1], off
	global_load_dwordx4 v[68:71], v[0:1], off offset:32
	global_load_dwordx4 v[72:75], v[0:1], off offset:64
	global_load_dwordx4 v[76:79], v[0:1], off offset:96
	v_ashrrev_i32_e32 v0, 31, v108
	s_add_u32 s26, s4, s37
	v_lshrrev_b32_e32 v0, 29, v0
	s_addc_u32 s27, s5, s36
	v_add_u32_e32 v0, v108, v0
	s_add_u32 s26, s26, s6
	v_ashrrev_i32_e32 v116, 3, v0
	v_and_b32_e32 v0, -8, v0
	v_sub_u32_e64 v8, s71, 8 clamp
	s_addc_u32 s27, s27, 0
	s_waitcnt vmcnt(8)
	v_sub_u32_e32 v10, v108, v0
	v_lshl_add_u32 v2, v8, 6, v116
	v_mov_b64_e32 v[0:1], s[26:27]
	v_lshlrev_b32_e32 v32, 3, v10
	v_mad_i64_i32 v[0:1], s[36:37], v2, s44, v[0:1]
	v_ashrrev_i32_e32 v33, 31, v32
	v_lshl_add_u64 v[0:1], v[32:33], 1, v[0:1]
	v_add_co_u32_e32 v4, vcc, 0x1000, v0
	v_readfirstlane_b32 s6, v8
	s_nop 0
	v_addc_co_u32_e32 v5, vcc, 0, v1, vcc
	global_load_dwordx4 v[0:3], v[0:1], off offset:2048
	s_nop 0
	global_load_dwordx4 v[4:7], v[4:5], off
	v_cmp_gt_i32_e32 vcc, s46, v108
	s_and_b64 s[36:37], s[34:35], vcc
	s_and_saveexec_b64 s[34:35], s[36:37]
	s_cbranch_execz .LBB0_230
	v_max_i32_e32 v8, 0xffffff01, v108
	v_sub_u32_e32 v8, v8, v108
	v_add_u32_e32 v9, 0x1ff, v8
	v_cmp_lt_u32_e32 vcc, s47, v9
	s_mov_b64 s[38:39], -1
	v_mov_b32_e32 v8, v108
	s_and_saveexec_b64 s[36:37], vcc
	s_cbranch_execz .LBB0_227
	s_waitcnt vmcnt(9)
	v_lshrrev_b32_e32 v11, 9, v9
	v_add_u32_e32 v8, -1, v11
	v_add_u32_e32 v109, 0x200, v108
	v_lshrrev_b32_e32 v9, 1, v8
	s_mul_i32 s73, s45, 0x101
	v_add_u32_e32 v12, 1, v9
	v_cmp_lt_u32_e32 vcc, 5, v8
	v_mov_b32_e32 v15, 0
	v_mov_b64_e32 v[8:9], v[108:109]
	s_and_saveexec_b64 s[38:39], vcc
	s_cbranch_execz .LBB0_223
	s_add_i32 s74, s73, 0x400
	s_add_i32 s76, s73, 0x800
	s_add_i32 s78, s73, 0xc00
	v_and_b32_e32 v13, -4, v12
	s_mov_b32 s75, s74
	s_mov_b32 s77, s76
	s_mov_b32 s79, s78
	v_lshl_add_u32 v14, v108, 2, s48
	s_mov_b32 s80, 0
	s_mov_b64 s[40:41], 0
	v_mov_b64_e32 v[8:9], v[108:109]

.LBB0_241:
	s_cmpk_gt_i32 s2, 0x3ff
	v_readfirstlane_b32 s10, v255
	s_cbranch_scc1 .LBB0_244
	s_add_u32 s4, s54, 0x4d00000
	v_bfe_u32 v229, v255, 5, 1
	s_addc_u32 s5, s55, 0
	v_lshrrev_b32_e32 v0, 1, v255
	v_and_b32_e32 v1, 3, v255
	v_and_or_b32 v228, v0, 12, v1
	v_lshlrev_b32_e32 v0, 3, v229
	v_mov_b32_e32 v231, 0
	s_add_u32 s6, s54, 0x100000
	v_lshlrev_b32_e32 v230, 5, v229
	v_and_b32_e32 v226, 31, v255
	v_bfe_u32 v240, v255, 2, 1
	s_addc_u32 s7, s55, 0
	s_waitcnt lgkmcnt(0)
	v_lshl_add_u64 v[232:233], s[50:51], 0, v[230:231]
	v_lshl_add_u64 v[234:235], s[12:13], 0, v[230:231]
	s_lshr_b32 s24, s10, 6
	s_lshl_b32 s25, s2, 3
	s_lshl_b32 s26, s58, 3
	s_mov_b32 s11, 0
	s_movk_i32 s27, 0x3000
	v_mov_b64_e32 v[236:237], s[54:55]
	v_lshlrev_b32_e32 v238, 1, v0
	v_mov_b32_e32 v239, v231
	s_mov_b32 s33, 0x9601000
	s_mov_b32 s34, 0x9631000
	s_mov_b32 s35, 0x9661000
	s_mov_b32 s36, 0x9691000
	s_mov_b32 s37, s2

.LBB0_244:
	s_cmp_gt_i32 s57, 3
	s_cselect_b64 s[4:5], -1, 0
	s_and_b64 s[0:1], s[0:1], s[4:5]
	s_andn2_b64 vcc, exec, s[0:1]
	s_cbranch_vccnz .LBB0_298
	s_waitcnt vmcnt(0)
	s_waitcnt lgkmcnt(0)
	s_barrier
	s_and_saveexec_b64 s[0:1], s[8:9]
	s_cbranch_execz .LBB0_297
	s_add_i32 s6, 0, 0x23000
	v_mov_b32_e32 v0, s6
	s_waitcnt vmcnt(0) expcnt(0) lgkmcnt(0)
	ds_read_b32 v2, v0
	s_add_i32 s6, 0, 0x23004
	v_mov_b32_e32 v0, s6
	ds_read_b32 v0, v0
	s_waitcnt lgkmcnt(1)
	v_cmp_ne_u32_e32 vcc, 0, v2
	s_cbranch_vccnz .LBB0_261
	v_readlane_b32 s6, v254, 0
	s_mul_i32 s33, s59, s6
	s_add_u32 s6, s54, 0x80200
	s_addc_u32 s7, s55, 0
	s_add_u32 s10, s54, 0x80400
	s_addc_u32 s11, s55, 0
	s_add_u32 s20, s54, 0x80500
	s_addc_u32 s21, s55, 0
	s_add_u32 s24, s54, 0x80600
	s_addc_u32 s25, s55, 0
	s_add_u32 s26, s54, 0x80700
	s_addc_u32 s27, s55, 0
	s_add_u32 s34, s54, 0x80800
	s_addc_u32 s35, s55, 0
	s_add_u32 s36, s54, 0x80900
	s_addc_u32 s37, s55, 0
	s_add_u32 s38, s54, 0x80a00
	s_addc_u32 s39, s55, 0
	s_add_u32 s40, s54, 0x80b00
	s_addc_u32 s41, s55, 0
	s_add_u32 s42, s54, 0x80c00
	s_addc_u32 s43, s55, 0
	s_add_u32 s44, s54, 0x80d00
	s_addc_u32 s45, s55, 0
	s_add_u32 s46, s54, 0x80e00
	s_addc_u32 s47, s55, 0
	s_add_u32 s48, s54, 0x80f00
	s_addc_u32 s49, s55, 0
	s_add_u32 s60, s54, 0x81000
	s_addc_u32 s61, s55, 0
	s_add_u32 s64, s54, 0x81100
	s_addc_u32 s65, s55, 0
	s_add_u32 s68, s54, 0x81200
	s_addc_u32 s69, s55, 0
	s_add_u32 s70, s54, 0x81300
	s_mul_i32 s33, s33, s58
	s_addc_u32 s71, s55, 0
	s_mov_b32 s78, 1
	v_mov_b32_e32 v16, 0
	s_branch .LBB0_249

.LBB0_298:
	s_cmp_lt_i32 s56, 4
	s_cselect_b64 s[0:1], -1, 0
	s_and_b64 s[4:5], s[0:1], s[4:5]
	s_andn2_b64 vcc, exec, s[4:5]
	s_cbranch_vccnz .LBB0_310
	s_cmpk_gt_i32 s2, 0x3ff
	v_readfirstlane_b32 s0, v255
	s_cbranch_scc1 .LBB0_310
	v_lshrrev_b32_e32 v2, 2, v255
	v_and_b32_e32 v128, 12, v2
	s_add_u32 s6, s54, 0x9600000
	v_lshrrev_b32_e32 v0, 1, v255
	v_and_b32_e32 v3, 3, v255
	v_mov_b32_e32 v127, 0
	v_lshlrev_b32_e32 v126, 1, v128
	s_addc_u32 s7, s55, 0
	v_and_or_b32 v124, v0, 12, v3
	v_lshl_add_u64 v[2:3], s[54:55], 0, v[126:127]
	s_mov_b64 s[10:11], 0x15600000
	v_lshl_add_u64 v[130:131], v[2:3], 0, s[10:11]
	s_add_u32 s10, s54, 0x100000
	s_addc_u32 s11, s55, 0
	s_waitcnt lgkmcnt(0)
	s_lshr_b32 s36, s0, 6
	v_and_b32_e32 v122, 31, v255
	v_bfe_u32 v1, v255, 5, 1
	s_mul_i32 s1, s36, 0x2400
	v_lshlrev_b32_e32 v2, 2, v122
	v_mul_u32_u24_e32 v3, 0x1100, v1
	s_add_i32 s1, s1, 0
	v_add3_u32 v129, s1, v3, v2
	v_mov_b32_e32 v2, s1
	s_lshl_b64 s[0:1], s[0:1], 3
	v_lshlrev_b32_e32 v126, 5, v1
	s_and_b32 s1, s1, 7
	s_and_b32 s0, s0, 0xfffffe00
	v_lshl_add_u64 v[132:133], s[50:51], 0, v[126:127]
	v_lshl_add_u64 v[134:135], s[12:13], 0, v[126:127]
	v_lshlrev_b32_e32 v126, 2, v128
	s_add_u32 s0, s54, s0
	v_and_b32_e32 v125, 15, v255
	v_lshl_add_u64 v[136:137], s[18:19], 0, v[126:127]
	s_movk_i32 s12, 0x110
	v_lshlrev_b32_e32 v126, 3, v122
	s_addc_u32 s1, s55, s1
	v_mad_u32_u24 v5, v125, s12, v2
	v_lshl_add_u64 v[2:3], s[0:1], 0, v[126:127]
	s_mov_b64 s[0:1], 0x4d18100
	v_lshlrev_b32_e32 v0, 3, v1
	v_and_b32_e32 v4, 48, v255
	v_lshl_add_u64 v[138:139], v[2:3], 0, s[0:1]
	s_mov_b64 s[0:1], 0x4d00100
	v_bfe_u32 v123, v255, 2, 1
	s_mov_b32 s13, 0
	v_lshlrev_b32_e32 v162, 6, v1
	s_lshl_b32 s37, s2, 3
	s_lshl_b32 s38, s58, 3
	v_lshl_add_u64 v[140:141], v[2:3], 0, s[0:1]
	s_mov_b32 s39, 0xffff0000
	s_movk_i32 s40, 0x8000
	s_mov_b64 s[18:19], 0x20000
	s_mov_b64 s[20:21], 0x8000
	s_movk_i32 s41, 0x3000
	v_lshlrev_b32_e32 v142, 1, v0
	s_movk_i32 s42, 0x1000
	s_mov_b32 s43, 0x31000
	s_mov_b32 s44, 0x61000
	s_mov_b32 s45, 0x91000
	v_add_u32_e32 v163, v5, v4
	v_mov_b32_e32 v164, 0x3000
	s_mov_b32 s46, s2
	s_branch .LBB0_302

.LBB0_310:
	s_cmp_gt_i32 s57, 4
	s_cselect_b64 s[0:1], -1, 0
	s_and_b64 s[4:5], s[4:5], s[0:1]
	s_andn2_b64 vcc, exec, s[4:5]
	s_cbranch_vccnz .LBB0_364
	s_waitcnt vmcnt(0)
	s_waitcnt lgkmcnt(0)
	s_barrier
	s_and_saveexec_b64 s[4:5], s[8:9]
	s_cbranch_execz .LBB0_363
	s_add_i32 s6, 0, 0x23000
	v_mov_b32_e32 v0, s6
	s_waitcnt vmcnt(0) expcnt(0) lgkmcnt(0)
	ds_read_b32 v2, v0
	s_add_i32 s6, 0, 0x23004
	v_mov_b32_e32 v0, s6
	ds_read_b32 v0, v0
	s_waitcnt lgkmcnt(1)
	v_cmp_ne_u32_e32 vcc, 0, v2
	s_cbranch_vccnz .LBB0_327
	v_readlane_b32 s6, v254, 0
	s_mul_i32 s33, s59, s6
	s_add_u32 s6, s54, 0x80200
	s_addc_u32 s7, s55, 0
	s_add_u32 s10, s54, 0x80400
	s_addc_u32 s11, s55, 0
	s_add_u32 s12, s54, 0x80500
	s_addc_u32 s13, s55, 0
	s_add_u32 s14, s54, 0x80600
	s_addc_u32 s15, s55, 0
	s_add_u32 s16, s54, 0x80700
	s_addc_u32 s17, s55, 0
	s_add_u32 s18, s54, 0x80800
	s_addc_u32 s19, s55, 0
	s_add_u32 s20, s54, 0x80900
	s_addc_u32 s21, s55, 0
	s_add_u32 s24, s54, 0x80a00
	s_addc_u32 s25, s55, 0
	s_add_u32 s26, s54, 0x80b00
	s_addc_u32 s27, s55, 0
	s_add_u32 s34, s54, 0x80c00
	s_addc_u32 s35, s55, 0
	s_add_u32 s36, s54, 0x80d00
	s_addc_u32 s37, s55, 0
	s_add_u32 s38, s54, 0x80e00
	s_addc_u32 s39, s55, 0
	s_add_u32 s40, s54, 0x80f00
	s_addc_u32 s41, s55, 0
	s_add_u32 s42, s54, 0x81000
	s_addc_u32 s43, s55, 0
	s_add_u32 s44, s54, 0x81100
	s_addc_u32 s45, s55, 0
	s_add_u32 s46, s54, 0x81200
	s_addc_u32 s47, s55, 0
	s_add_u32 s48, s54, 0x81300
	s_mul_i32 s33, s33, s58
	s_addc_u32 s49, s55, 0
	s_mov_b32 s68, 1
	v_mov_b32_e32 v16, 0
	s_branch .LBB0_315

.LBB0_364:
	s_cmp_lt_i32 s56, 5
	s_cselect_b64 s[4:5], -1, 0
	s_and_b64 s[4:5], s[4:5], s[0:1]
	s_andn2_b64 vcc, exec, s[4:5]
	s_cbranch_vccnz .LBB0_385
	s_cmpk_gt_i32 s2, 0xff
	v_readfirstlane_b32 s1, v255
	s_cbranch_scc1 .LBB0_385
	v_lshrrev_b32_e32 v2, 1, v255
	s_waitcnt vmcnt(3)
	v_and_b32_e32 v11, 24, v2
	v_lshrrev_b32_e32 v2, 5, v255
	v_and_b32_e32 v2, 4, v2
	v_bfe_u32 v3, v255, 2, 2
	s_add_u32 s6, s54, 0x15600000
	v_lshlrev_b32_e32 v0, 4, v255
	v_and_b32_e32 v1, 32, v255
	v_bfe_u32 v10, v255, 2, 4
	v_or3_b32 v2, v2, v3, v11
	v_lshrrev_b32_e32 v3, 3, v255
	s_movk_i32 s0, 0x70
	s_addc_u32 s7, s55, 0
	v_bitop3_b32 v8, v0, v1, 48 bitop3:0x6c
	v_and_b32_e32 v9, 64, v255
	v_and_or_b32 v4, v3, s0, v10
	s_movk_i32 s0, 0x60
	s_waitcnt lgkmcnt(0)
	v_add_u32_e32 v12, 0x2000, v0
	s_add_u32 s44, s54, 0x1a00000
	v_or_b32_e32 v1, v8, v9
	v_and_or_b32 v3, v3, s0, v2
	v_lshrrev_b32_e32 v0, 7, v12
	s_movk_i32 s0, 0xf0
	s_addc_u32 s45, s55, 0
	v_lshl_or_b32 v138, v3, 11, v1
	v_and_or_b32 v3, v0, s0, v10
	s_movk_i32 s0, 0xe0
	s_ashr_i32 s47, s2, 31
	v_and_or_b32 v0, v0, s0, v2
	s_lshr_b32 s0, s47, 29
	s_add_i32 s0, s2, s0
	s_and_b32 s10, s0, -8
	s_lshr_b32 s16, s1, 6
	s_sub_i32 s10, s2, s10
	s_lshr_b32 s18, s1, 8
	s_lshl_b32 s46, s16, 10
	s_lshl_b32 s12, s10, 5
	s_ashr_i32 s0, s0, 3
	s_mul_i32 s11, s10, 33
	s_cmp_lt_i32 s10, 0
	s_cselect_b32 s10, s11, s12
	s_add_i32 s0, s10, s0
	s_ashr_i32 s10, s0, 31
	s_lshr_b32 s10, s10, 27
	s_add_i32 s10, s0, s10
	s_ashr_i32 s11, s10, 5
	s_andn2_b32 s10, s10, 31
	s_sub_i32 s10, s0, s10
	s_bfe_i32 s0, s10, 0x80000
	s_bfe_u32 s0, s0, 0x3000c
	s_add_i32 s12, s10, s0
	s_bfe_i32 s0, s12, 0x80000
	s_and_b32 s12, s12, 0xf8
	s_sub_i32 s10, s10, s12
	s_lshl_b32 s11, s11, 3
	s_sext_i32_i16 s0, s0
	s_sext_i32_i8 s10, s10
	s_lshr_b32 s0, s0, 3
	s_add_i32 s36, s11, s10
	s_ashr_i32 s37, s36, 31
	s_bfe_i64 s[12:13], s[0:1], 0x100000
	s_lshl_b64 s[10:11], s[36:37], 19
	s_lshl_b64 s[12:13], s[12:13], 19
	s_add_u32 s40, s44, s12
	s_addc_u32 s41, s45, s13
	s_add_i32 s37, s46, 0
	s_add_i32 m0, s37, 0x10000
	v_lshl_or_b32 v142, v0, 11, v1
	global_load_lds_dwordx4 v138, s[40:41]
	s_add_i32 m0, s37, 0x12000
	s_add_u32 s12, s40, 0x40000
	global_load_lds_dwordx4 v142, s[40:41]
	s_addc_u32 s13, s41, 0
	s_add_i32 m0, s37, 0x14000
	v_lshl_or_b32 v136, v4, 11, v1
	global_load_lds_dwordx4 v138, s[12:13]
	s_add_i32 m0, s37, 0x16000
	s_add_u32 s38, s6, s10
	s_addc_u32 s39, s7, s11
	s_add_i32 s48, s37, 0x2000
	global_load_lds_dwordx4 v142, s[12:13]
	s_mov_b32 m0, s37
	s_add_u32 s10, s38, 0x40000
	v_lshl_or_b32 v140, v3, 11, v1
	global_load_lds_dwordx4 v136, s[38:39]
	s_mov_b32 m0, s48
	s_addc_u32 s11, s39, 0
	s_add_i32 s49, s37, 0x4000
	global_load_lds_dwordx4 v140, s[38:39]
	s_mov_b32 m0, s49
	s_add_i32 s50, s37, 0x6000
	global_load_lds_dwordx4 v136, s[10:11]
	s_mov_b32 m0, s50
	v_mov_b32_e32 v139, 0
	global_load_lds_dwordx4 v140, s[10:11]
	v_mov_b32_e32 v143, v139
	v_mov_b32_e32 v137, v139
	v_mov_b32_e32 v141, v139
	s_cmp_eq_u32 s18, 1
	s_mov_b32 s51, 0
	v_lshl_add_u64 v[6:7], s[40:41], 0, v[138:139]
	v_lshl_add_u64 v[4:5], s[40:41], 0, v[142:143]
	v_lshl_add_u64 v[0:1], s[38:39], 0, v[136:137]
	s_cselect_b64 s[10:11], -1, 0
	s_cmp_lg_u32 s18, 1
	v_lshl_add_u64 v[2:3], s[38:39], 0, v[140:141]
	s_cbranch_scc1 .LBB0_368
	s_barrier
.LBB0_368:
	s_add_u32 s12, s54, 0x9602800
	s_addc_u32 s13, s55, 0
	s_add_u32 s14, s54, 0x17600800
	s_addc_u32 s15, s55, 0
	s_lshl_b32 s16, s16, 5
	s_and_b32 s24, s16, 0x60
	s_mov_b64 s[16:17], 0x80
	s_add_i32 m0, s37, 0x18000
	v_lshl_add_u64 v[6:7], v[6:7], 0, s[16:17]
	s_ashr_i32 s60, s58, 31
	s_lshl_b32 s19, s18, 13
	s_lshl_b32 s25, s24, 7
	s_waitcnt vmcnt(2)
	s_barrier
	global_load_lds_dwordx4 v[6:7], off
	v_lshl_add_u64 v[4:5], v[4:5], 0, s[16:17]
	s_add_i32 m0, s37, 0x1a000
	s_add_i32 s61, s37, 0x8000
	s_add_i32 s64, s37, 0xa000
	global_load_lds_dwordx4 v[4:5], off
	v_lshl_add_u64 v[0:1], v[0:1], 0, s[16:17]
	s_mov_b32 m0, s61
	s_add_u32 s20, s40, 0x40080
	global_load_lds_dwordx4 v[0:1], off
	v_lshl_add_u64 v[0:1], v[2:3], 0, s[16:17]
	s_mov_b32 m0, s64
	s_addc_u32 s21, s41, 0
	global_load_lds_dwordx4 v[0:1], off
	s_add_i32 m0, s37, 0x1c000
	v_lshl_add_u64 v[0:1], s[20:21], 0, v[138:139]
	global_load_lds_dwordx4 v[0:1], off
	v_lshl_add_u64 v[0:1], s[20:21], 0, v[142:143]
	s_add_i32 m0, s37, 0x1e000
	s_sext_i32_i8 s33, s0
	global_load_lds_dwordx4 v[0:1], off
	v_and_b32_e32 v0, 15, v255
	v_lshlrev_b32_e32 v1, 1, v11
	v_lshlrev_b32_e32 v2, 6, v255
	s_movk_i32 s0, 0x3c0
	v_lshlrev_b32_e32 v3, 2, v255
	v_and_or_b32 v2, v2, s0, v1
	v_and_b32_e32 v3, 32, v3
	v_lshl_or_b32 v160, s18, 6, v0
	v_lshl_or_b32 v0, v0, 6, v1
	v_lshlrev_b32_e32 v1, 8, v255
	v_bitop3_b32 v161, s25, v2, v3 bitop3:0xf6
	v_and_b32_e32 v1, 0x38000, v1
	v_lshlrev_b32_e32 v2, 11, v10
	v_or3_b32 v1, v8, v1, v2
	v_add_u32_e32 v144, v1, v9
	v_lshlrev_b32_e32 v1, 4, v12
	s_waitcnt vmcnt(6)
	s_cmpk_lt_u32 s1, 0x100
	v_and_b32_e32 v1, 0x78000, v1
	v_bitop3_b32 v0, v0, s19, v3 bitop3:0xde
	s_cselect_b64 s[18:19], -1, 0
	v_or3_b32 v1, v8, v1, v2
	s_add_i32 s68, 0, 0x10000
	s_add_i32 s69, 0, 0x14000
	s_mov_b32 s65, s58
	v_or_b32_e32 v162, s24, v11
	v_mov_b32_e32 v145, v139
	v_add_u32_e32 v146, v1, v9
	v_mov_b32_e32 v147, v139
	v_mov_b64_e32 v[148:149], 0x100
	v_mov_b64_e32 v[150:151], 0xff
	v_add_u32_e32 v163, s68, v161
	v_add_u32_e32 v164, s69, v161
	v_add_u32_e32 v165, 0, v0
	s_movk_i32 s70, 0x3000
	s_barrier
	s_branch .LBB0_371

.LBB0_385:
	s_cmp_gt_i32 s57, 5
	s_cselect_b64 s[0:1], -1, 0
	s_and_b64 s[4:5], s[4:5], s[0:1]
	s_andn2_b64 vcc, exec, s[4:5]
	s_cbranch_vccnz .LBB0_439
	s_waitcnt vmcnt(0)
	s_waitcnt lgkmcnt(0)
	s_barrier
	s_and_saveexec_b64 s[4:5], s[8:9]
	s_cbranch_execz .LBB0_438
	s_add_i32 s6, 0, 0x23000
	v_mov_b32_e32 v0, s6
	s_waitcnt vmcnt(0) expcnt(0) lgkmcnt(0)
	ds_read_b32 v2, v0
	s_add_i32 s6, 0, 0x23004
	v_mov_b32_e32 v0, s6
	ds_read_b32 v0, v0
	s_waitcnt lgkmcnt(1)
	v_cmp_ne_u32_e32 vcc, 0, v2
	s_cbranch_vccnz .LBB0_402
	v_readlane_b32 s6, v254, 0
	s_mul_i32 s33, s59, s6
	s_add_u32 s6, s54, 0x80200
	s_addc_u32 s7, s55, 0
	s_add_u32 s10, s54, 0x80400
	s_addc_u32 s11, s55, 0
	s_add_u32 s12, s54, 0x80500
	s_addc_u32 s13, s55, 0
	s_add_u32 s14, s54, 0x80600
	s_addc_u32 s15, s55, 0
	s_add_u32 s16, s54, 0x80700
	s_addc_u32 s17, s55, 0
	s_add_u32 s18, s54, 0x80800
	s_addc_u32 s19, s55, 0
	s_add_u32 s20, s54, 0x80900
	s_addc_u32 s21, s55, 0
	s_add_u32 s22, s54, 0x80a00
	s_addc_u32 s23, s55, 0
	s_add_u32 s24, s54, 0x80b00
	s_addc_u32 s25, s55, 0
	s_add_u32 s26, s54, 0x80c00
	s_addc_u32 s27, s55, 0
	s_add_u32 s34, s54, 0x80d00
	s_addc_u32 s35, s55, 0
	s_add_u32 s36, s54, 0x80e00
	s_addc_u32 s37, s55, 0
	s_add_u32 s38, s54, 0x80f00
	s_addc_u32 s39, s55, 0
	s_add_u32 s40, s54, 0x81000
	s_addc_u32 s41, s55, 0
	s_add_u32 s42, s54, 0x81100
	s_addc_u32 s43, s55, 0
	s_add_u32 s44, s54, 0x81200
	s_addc_u32 s45, s55, 0
	s_add_u32 s46, s54, 0x81300
	s_mul_i32 s33, s33, s58
	s_addc_u32 s47, s55, 0
	s_mov_b32 s64, 1
	v_mov_b32_e32 v16, 0
	s_branch .LBB0_390

.LBB0_439:
	s_cmp_lt_i32 s56, 6
	s_cselect_b64 s[4:5], -1, 0
	s_and_b64 s[6:7], s[4:5], s[0:1]
	s_andn2_b64 vcc, exec, s[6:7]
	s_cbranch_vccnz .LBB0_482
	s_cmpk_lt_i32 s2, 0x200
	s_cselect_b64 s[0:1], -1, 0
	s_cmpk_gt_i32 s2, 0x1ff
	s_waitcnt lgkmcnt(0)
	v_readfirstlane_b32 s18, v255
	s_cbranch_scc1 .LBB0_446
	s_ashr_i32 s4, s2, 31
	s_lshr_b32 s4, s4, 29
	s_add_i32 s10, s2, s4
	s_and_b32 s4, s10, -8
	s_sub_i32 s11, s2, s4
	s_cmp_gt_i32 s11, -1
	s_cbranch_scc0 .LBB0_443
	s_lshl_b32 s12, s11, 6
	s_cbranch_execz .LBB0_444
	s_branch .LBB0_445

.LBB0_446:
	s_andn2_b64 vcc, exec, s[0:1]
	s_cbranch_vccnz .LBB0_482
	v_lshrrev_b32_e32 v2, 1, v255
	v_lshrrev_b32_e32 v3, 5, v255
	v_and_b32_e32 v2, 24, v2
	v_and_b32_e32 v3, 4, v3
	v_bfe_u32 v4, v255, 2, 2
	v_lshlrev_b32_e32 v0, 4, v255
	v_and_b32_e32 v1, 32, v255
	s_waitcnt vmcnt(4)
	v_bfe_u32 v10, v255, 2, 4
	v_or3_b32 v2, v3, v4, v2
	v_lshrrev_b32_e32 v3, 3, v255
	s_movk_i32 s1, 0x70
	s_add_u32 s33, s54, 0x17600000
	v_bitop3_b32 v8, v0, v1, 48 bitop3:0x6c
	v_and_b32_e32 v9, 64, v255
	v_and_or_b32 v4, v3, s1, v10
	s_movk_i32 s1, 0x60
	s_waitcnt vmcnt(3)
	v_add_u32_e32 v11, 0x2000, v0
	s_addc_u32 s44, s55, 0
	v_or_b32_e32 v1, v8, v9
	v_and_or_b32 v3, v3, s1, v2
	v_lshrrev_b32_e32 v0, 7, v11
	s_movk_i32 s1, 0xf0
	s_add_u32 s45, s54, 0x1c00000
	v_lshl_or_b32 v154, v3, 12, v1
	v_and_or_b32 v3, v0, s1, v10
	s_movk_i32 s1, 0xe0
	s_addc_u32 s46, s55, 0
	v_and_or_b32 v0, v0, s1, v2
	s_lshr_b32 s1, s18, 6
	s_ashr_i32 s35, s34, 31
	s_ashr_i32 s37, s36, 31
	s_lshr_b32 s0, s18, 8
	s_lshl_b32 s47, s1, 10
	s_lshl_b64 s[4:5], s[34:35], 20
	s_lshl_b64 s[10:11], s[36:37], 20
	s_add_u32 s40, s45, s10
	s_addc_u32 s41, s46, s11
	s_add_i32 s37, s47, 0
	s_add_i32 m0, s37, 0x10000
	v_lshl_or_b32 v158, v0, 12, v1
	global_load_lds_dwordx4 v154, s[40:41]
	s_add_i32 m0, s37, 0x12000
	s_add_u32 s10, s40, 0x80000
	global_load_lds_dwordx4 v158, s[40:41]
	s_addc_u32 s11, s41, 0
	s_add_i32 m0, s37, 0x14000
	v_lshl_or_b32 v152, v4, 12, v1
	global_load_lds_dwordx4 v154, s[10:11]
	s_add_i32 m0, s37, 0x16000
	s_add_u32 s38, s33, s4
	s_addc_u32 s39, s44, s5
	s_add_i32 s48, s37, 0x2000
	global_load_lds_dwordx4 v158, s[10:11]
	s_mov_b32 m0, s37
	s_add_u32 s4, s38, 0x80000
	v_lshl_or_b32 v156, v3, 12, v1
	global_load_lds_dwordx4 v152, s[38:39]
	s_mov_b32 m0, s48
	s_addc_u32 s5, s39, 0
	s_add_i32 s49, s37, 0x4000
	global_load_lds_dwordx4 v156, s[38:39]
	s_mov_b32 m0, s49
	s_add_i32 s50, s37, 0x6000
	global_load_lds_dwordx4 v152, s[4:5]
	s_mov_b32 m0, s50
	v_mov_b32_e32 v155, 0
	global_load_lds_dwordx4 v156, s[4:5]
	v_mov_b32_e32 v159, v155
	v_mov_b32_e32 v153, v155
	v_mov_b32_e32 v157, v155
	s_cmp_eq_u32 s0, 1
	s_mov_b32 s51, 0
	v_lshl_add_u64 v[6:7], s[40:41], 0, v[154:155]
	v_lshl_add_u64 v[4:5], s[40:41], 0, v[158:159]
	v_lshl_add_u64 v[0:1], s[38:39], 0, v[152:153]
	s_cselect_b64 s[10:11], -1, 0
	s_cmp_lg_u32 s0, 1
	v_lshl_add_u64 v[2:3], s[38:39], 0, v[156:157]
	s_cbranch_scc1 .LBB0_449
	s_barrier
.LBB0_449:
	s_add_u32 s12, s54, 0x5600000
	s_addc_u32 s13, s55, 0
	s_add_u32 s14, s54, 0x10000
	s_addc_u32 s15, s55, 0
	s_lshl_b32 s1, s1, 5
	s_mov_b64 s[16:17], 0x80
	s_and_b32 s20, s1, 0x60
	s_add_i32 m0, s37, 0x18000
	v_lshl_add_u64 v[6:7], v[6:7], 0, s[16:17]
	s_lshl_b32 s19, s0, 13
	s_lshl_b32 s1, s20, 7
	s_waitcnt vmcnt(2)
	s_barrier
	global_load_lds_dwordx4 v[6:7], off
	v_lshl_add_u64 v[4:5], v[4:5], 0, s[16:17]
	s_add_i32 m0, s37, 0x1a000
	s_add_i32 s60, s37, 0x8000
	s_add_i32 s61, s37, 0xa000
	global_load_lds_dwordx4 v[4:5], off
	v_lshl_add_u64 v[0:1], v[0:1], 0, s[16:17]
	s_mov_b32 m0, s60
	s_add_u32 s4, s40, 0x80080
	global_load_lds_dwordx4 v[0:1], off
	v_lshl_add_u64 v[0:1], v[2:3], 0, s[16:17]
	s_mov_b32 m0, s61
	s_addc_u32 s5, s41, 0
	global_load_lds_dwordx4 v[0:1], off
	s_add_i32 m0, s37, 0x1c000
	v_lshl_add_u64 v[0:1], s[4:5], 0, v[154:155]
	global_load_lds_dwordx4 v[0:1], off
	v_lshl_add_u64 v[0:1], s[4:5], 0, v[158:159]
	s_add_i32 m0, s37, 0x1e000
	v_lshlrev_b32_e32 v3, 2, v255
	global_load_lds_dwordx4 v[0:1], off
	v_and_b32_e32 v0, 15, v255
	v_bfe_u32 v1, v255, 4, 2
	v_lshl_or_b32 v184, s0, 6, v0
	v_lshlrev_b32_e32 v2, 4, v1
	v_lshlrev_b32_e32 v4, 6, v255
	s_movk_i32 s0, 0x3c0
	v_lshl_or_b32 v0, v0, 6, v2
	v_and_b32_e32 v3, 32, v3
	v_and_or_b32 v2, v4, s0, v2
	v_bitop3_b32 v185, s1, v2, v3 bitop3:0xf6
	v_cmp_eq_u32_e64 s[0:1], 0, v1
	v_lshl_or_b32 v186, v1, 3, s20
	v_lshlrev_b32_e32 v1, 9, v255
	v_and_b32_e32 v1, 0x70000, v1
	v_lshlrev_b32_e32 v2, 12, v10
	v_or3_b32 v1, v8, v1, v2
	v_add_u32_e32 v160, v1, v9
	v_lshlrev_b32_e32 v1, 5, v11
	v_bitop3_b32 v0, v0, s19, v3 bitop3:0xde
	s_waitcnt vmcnt(6)
	s_cmpk_lt_u32 s18, 0x100
	v_and_b32_e32 v1, 0xf0000, v1
	s_cselect_b64 s[18:19], -1, 0
	v_or3_b32 v1, v8, v1, v2
	s_add_i32 s69, 0, 0x10000
	s_add_i32 s70, 0, 0x14000
	v_add_u32_e32 v189, 0, v0
	v_mbcnt_lo_u32_b32 v0, -1, 0
	s_ashr_i32 s64, s58, 31
	s_mov_b32 s65, s58
	s_ashr_i32 s68, s2, 31
	v_mov_b32_e32 v161, v155
	v_add_u32_e32 v162, v1, v9
	v_mov_b32_e32 v163, v155
	v_mov_b64_e32 v[164:165], 0x200
	v_mov_b64_e32 v[166:167], 0x1ff
	v_add_u32_e32 v187, s69, v185
	v_add_u32_e32 v188, s70, v185
	v_mbcnt_hi_u32_b32 v190, -1, v0
	s_barrier
	s_branch .LBB0_452

.LBB0_482:
	s_cmp_gt_i32 s57, 6
	s_cselect_b64 s[0:1], -1, 0
	s_and_b64 s[4:5], s[6:7], s[0:1]
	s_andn2_b64 vcc, exec, s[4:5]
	s_cbranch_vccnz .LBB0_536
	s_waitcnt vmcnt(0)
	s_waitcnt lgkmcnt(0)
	s_barrier
	s_and_saveexec_b64 s[4:5], s[8:9]
	s_cbranch_execz .LBB0_535
	s_add_i32 s6, 0, 0x23000
	v_mov_b32_e32 v0, s6
	s_waitcnt vmcnt(0) expcnt(0) lgkmcnt(0)
	ds_read_b32 v2, v0
	s_add_i32 s6, 0, 0x23004
	v_mov_b32_e32 v0, s6
	ds_read_b32 v0, v0
	s_waitcnt lgkmcnt(1)
	v_cmp_ne_u32_e32 vcc, 0, v2
	s_cbranch_vccnz .LBB0_499
	v_readlane_b32 s6, v254, 0
	s_mul_i32 s33, s59, s6
	s_add_u32 s6, s54, 0x80200
	s_addc_u32 s7, s55, 0
	s_add_u32 s10, s54, 0x80400
	s_addc_u32 s11, s55, 0
	s_add_u32 s12, s54, 0x80500
	s_addc_u32 s13, s55, 0
	s_add_u32 s14, s54, 0x80600
	s_addc_u32 s15, s55, 0
	s_add_u32 s16, s54, 0x80700
	s_addc_u32 s17, s55, 0
	s_add_u32 s18, s54, 0x80800
	s_addc_u32 s19, s55, 0
	s_add_u32 s20, s54, 0x80900
	s_addc_u32 s21, s55, 0
	s_add_u32 s22, s54, 0x80a00
	s_addc_u32 s23, s55, 0
	s_add_u32 s24, s54, 0x80b00
	s_addc_u32 s25, s55, 0
	s_add_u32 s26, s54, 0x80c00
	s_addc_u32 s27, s55, 0
	s_add_u32 s34, s54, 0x80d00
	s_addc_u32 s35, s55, 0
	s_add_u32 s36, s54, 0x80e00
	s_addc_u32 s37, s55, 0
	s_add_u32 s38, s54, 0x80f00
	s_addc_u32 s39, s55, 0
	s_add_u32 s40, s54, 0x81000
	s_addc_u32 s41, s55, 0
	s_add_u32 s42, s54, 0x81100
	s_addc_u32 s43, s55, 0
	s_add_u32 s44, s54, 0x81200
	s_addc_u32 s45, s55, 0
	s_add_u32 s46, s54, 0x81300
	s_mul_i32 s33, s33, s58
	s_addc_u32 s47, s55, 0
	s_mov_b32 s64, 1
	v_mov_b32_e32 v16, 0
	s_branch .LBB0_487

.LBB0_536:
	s_cmp_lt_i32 s56, 7
	s_cselect_b64 s[4:5], -1, 0
	s_waitcnt lgkmcnt(0)
	s_and_b64 s[14:15], s[4:5], s[0:1]
	s_andn2_b64 vcc, exec, s[14:15]
	s_cbranch_vccnz .LBB0_568
	s_add_u32 s16, s54, 0x10000
	s_addc_u32 s17, s55, 0
	v_and_b32_e32 v19, 15, v255
	s_cmpk_gt_i32 s2, 0xff
	v_mov_b32_e32 v9, 0
	v_readfirstlane_b32 s0, v255
	v_lshlrev_b32_e32 v8, 2, v19
	s_cbranch_scc1 .LBB0_548
	s_add_u32 s18, s54, 0x5500000
	s_addc_u32 s19, s55, 0
	s_add_u32 s20, s54, 0x30000
	s_addc_u32 s21, s55, 0
	s_lshr_b32 s1, s0, 8
	s_bfe_u32 s7, s0, 0x20006
	v_bfe_u32 v0, v255, 4, 2
	s_lshr_b32 s6, s0, 6
	s_lshl_b32 s24, s7, 4
	s_lshl_b32 s22, s1, 10
	v_lshlrev_b32_e32 v1, 2, v0
	s_cmp_eq_u32 s1, 1
	v_or_b32_e32 v2, 1, v1
	v_or_b32_e32 v3, 2, v1
	v_or_b32_e32 v4, 3, v1
	s_cselect_b64 s[4:5], -1, 0
	s_lshl_b32 s26, s7, 10
	v_or_b32_e32 v1, s24, v1
	s_mov_b32 s23, 0
	v_add_u32_e32 v31, 0, v8
	s_cmpk_lt_u32 s0, 0x100
	v_lshlrev_b32_e32 v25, 6, v1
	v_or_b32_e32 v1, s24, v2
	s_cselect_b64 s[0:1], -1, 0
	v_lshl_add_u32 v30, s6, 10, v31
	v_lshlrev_b32_e32 v27, 6, v1
	v_or_b32_e32 v1, s24, v3
	s_lshl_b64 s[6:7], s[22:23], 1
	v_lshlrev_b32_e32 v23, 8, v0
	v_lshlrev_b32_e32 v29, 6, v1
	v_or_b32_e32 v1, s24, v4
	v_lshlrev_b32_e32 v0, 4, v0
	s_add_u32 s6, s54, s6
	v_lshlrev_b32_e32 v5, 6, v4
	v_lshlrev_b32_e32 v6, 6, v3
	v_lshlrev_b32_e32 v7, 6, v2
	v_lshlrev_b32_e32 v4, 6, v1
	v_mov_b32_e32 v1, v9
	v_lshl_or_b32 v2, v19, 12, v0
	v_mov_b32_e32 v3, v9
	s_addc_u32 s7, s55, s7
	v_lshl_add_u64 v[12:13], s[16:17], 0, v[0:1]
	v_lshl_add_u64 v[2:3], s[6:7], 0, v[2:3]
	v_lshl_add_u64 v[0:1], s[6:7], 0, v[0:1]
	s_mov_b64 s[6:7], 0x5600100
	v_lshl_add_u64 v[16:17], v[0:1], 0, s[6:7]
	v_cndmask_b32_e64 v0, 0, 1, s[4:5]
	v_add_u32_e32 v21, v31, v23
	s_mov_b64 s[12:13], 0x4400100
	v_cmp_ne_u32_e64 s[4:5], 1, v0
	v_cndmask_b32_e64 v0, 0, 1, s[0:1]
	v_cmp_gt_u32_e64 s[10:11], 16, v255
	v_lshl_add_u32 v20, v255, 2, 0
	s_waitcnt vmcnt(3)
	v_lshl_add_u64 v[10:11], s[62:63], 0, v[8:9]
	s_mov_b32 s25, s23
	v_lshl_add_u64 v[14:15], v[2:3], 0, s[12:13]
	v_or_b32_e32 v18, s24, v19
	v_add_u32_e32 v9, s26, v21
	v_cmp_ne_u32_e64 s[6:7], 1, v0
	v_mov_b32_e32 v21, 0x358637bd
	s_mov_b32 s33, 0xf800000
	v_mov_b32_e32 v22, 0x260
	v_add_u32_e32 v23, v30, v23
	s_mov_b32 s34, 0xbfb8aa3b
	s_mov_b32 s35, 0x3f2aaaab
	v_mov_b32_e32 v24, 0x3ecc95a3
	s_mov_b32 s36, 0x3f317218
	s_mov_b32 s37, 0x7f800000
	s_mov_b32 s38, 0x33800000
	v_add_u32_e32 v25, v31, v25
	v_add_u32_e32 v26, v30, v7
	v_add_u32_e32 v27, v31, v27
	v_add_u32_e32 v28, v30, v6
	v_add_u32_e32 v29, v31, v29
	v_add_u32_e32 v30, v30, v5
	v_add_u32_e32 v31, v31, v4
	v_mov_b32_e32 v32, 0x7f800000
	v_mov_b32_e32 v33, 0x7fc00000
	v_mov_b32_e32 v34, 0xff800000
	s_mov_b32 s26, s2
	s_branch .LBB0_540

.LBB0_546:
	s_waitcnt lgkmcnt(0)
	s_barrier
	s_and_saveexec_b64 s[0:1], s[10:11]
	s_cbranch_execz .LBB0_539
	v_add_u32_e32 v35, 0x1000, v20
	s_ashr_i32 s12, s26, 2
	ds_read2_b32 v[2:3], v35 offset1:16
	v_and_or_b32 v0, s12, -16, v255
	v_ashrrev_i32_e32 v1, 31, v0
	ds_read2_b32 v[4:5], v35 offset0:32 offset1:48
	v_lshlrev_b64 v[0:1], 14, v[0:1]
	s_lshl_b32 s12, s26, 8
	v_lshl_add_u64 v[0:1], s[18:19], 0, v[0:1]
	s_and_b32 s22, s12, 0x3f00
	ds_read2_b32 v[36:37], v35 offset0:64 offset1:80
	v_lshl_add_u64 v[6:7], v[0:1], 0, s[22:23]
	s_waitcnt lgkmcnt(2)
	v_add_f32_e32 v0, 0, v2
	v_add_f32_e32 v1, v0, v3
	s_waitcnt lgkmcnt(1)
	v_add_f32_e32 v2, v1, v4
	v_add_f32_e32 v3, v2, v5
	ds_read2_b32 v[4:5], v35 offset0:96 offset1:112
	global_store_dwordx4 v[6:7], v[0:3], off
	s_waitcnt lgkmcnt(1)
	s_nop 0
	v_add_f32_e32 v0, v3, v36
	v_add_f32_e32 v1, v0, v37
	ds_read2_b32 v[36:37], v35 offset0:128 offset1:144
	s_waitcnt lgkmcnt(1)
	v_add_f32_e32 v2, v1, v4
	v_add_f32_e32 v3, v2, v5
	ds_read2_b32 v[4:5], v35 offset0:160 offset1:176
	global_store_dwordx4 v[6:7], v[0:3], off offset:16
	s_waitcnt lgkmcnt(1)
	s_nop 0
	v_add_f32_e32 v0, v3, v36
	v_add_f32_e32 v1, v0, v37
	ds_read2_b32 v[36:37], v35 offset0:192 offset1:208
	s_waitcnt lgkmcnt(1)
	v_add_f32_e32 v2, v1, v4
	v_add_f32_e32 v3, v2, v5
	ds_read2_b32 v[4:5], v35 offset0:224 offset1:240
	global_store_dwordx4 v[6:7], v[0:3], off offset:32
	v_add_u32_e32 v35, 0x1400, v20
	s_waitcnt lgkmcnt(1)
	v_add_f32_e32 v0, v3, v36
	v_add_f32_e32 v1, v0, v37
	ds_read2_b32 v[36:37], v35 offset1:16
	s_waitcnt lgkmcnt(1)
	v_add_f32_e32 v2, v1, v4
	v_add_f32_e32 v3, v2, v5
	ds_read2_b32 v[4:5], v35 offset0:32 offset1:48
	global_store_dwordx4 v[6:7], v[0:3], off offset:48
	s_waitcnt lgkmcnt(1)
	s_nop 0
	v_add_f32_e32 v0, v3, v36
	v_add_f32_e32 v1, v0, v37
	ds_read2_b32 v[36:37], v35 offset0:64 offset1:80
	s_waitcnt lgkmcnt(1)
	v_add_f32_e32 v2, v1, v4
	v_add_f32_e32 v3, v2, v5
	ds_read2_b32 v[4:5], v35 offset0:96 offset1:112
	global_store_dwordx4 v[6:7], v[0:3], off offset:64
	s_waitcnt lgkmcnt(1)
	s_nop 0
	v_add_f32_e32 v0, v3, v36
	v_add_f32_e32 v1, v0, v37
	ds_read2_b32 v[36:37], v35 offset0:128 offset1:144
	s_waitcnt lgkmcnt(1)
	v_add_f32_e32 v2, v1, v4
	v_add_f32_e32 v3, v2, v5
	ds_read2_b32 v[4:5], v35 offset0:160 offset1:176
	global_store_dwordx4 v[6:7], v[0:3], off offset:80
	s_waitcnt lgkmcnt(1)
	s_nop 0
	v_add_f32_e32 v0, v3, v36
	v_add_f32_e32 v1, v0, v37
	ds_read2_b32 v[36:37], v35 offset0:192 offset1:208
	s_waitcnt lgkmcnt(1)
	v_add_f32_e32 v2, v1, v4
	v_add_f32_e32 v3, v2, v5
	ds_read2_b32 v[4:5], v35 offset0:224 offset1:240
	global_store_dwordx4 v[6:7], v[0:3], off offset:96
	v_add_u32_e32 v35, 0x1800, v20
	s_waitcnt lgkmcnt(1)
	v_add_f32_e32 v0, v3, v36
	v_add_f32_e32 v1, v0, v37
	ds_read2_b32 v[36:37], v35 offset1:16
	s_waitcnt lgkmcnt(1)
	v_add_f32_e32 v2, v1, v4
	v_add_f32_e32 v3, v2, v5
	ds_read2_b32 v[4:5], v35 offset0:32 offset1:48
	global_store_dwordx4 v[6:7], v[0:3], off offset:112
	s_waitcnt lgkmcnt(1)
	s_nop 0
	v_add_f32_e32 v0, v3, v36
	v_add_f32_e32 v1, v0, v37
	ds_read2_b32 v[36:37], v35 offset0:64 offset1:80
	s_waitcnt lgkmcnt(1)
	v_add_f32_e32 v2, v1, v4
	v_add_f32_e32 v3, v2, v5
	ds_read2_b32 v[4:5], v35 offset0:96 offset1:112
	global_store_dwordx4 v[6:7], v[0:3], off offset:128
	s_waitcnt lgkmcnt(1)
	s_nop 0
	v_add_f32_e32 v0, v3, v36
	v_add_f32_e32 v1, v0, v37
	ds_read2_b32 v[36:37], v35 offset0:128 offset1:144
	s_waitcnt lgkmcnt(1)
	v_add_f32_e32 v2, v1, v4
	v_add_f32_e32 v3, v2, v5
	ds_read2_b32 v[4:5], v35 offset0:160 offset1:176
	global_store_dwordx4 v[6:7], v[0:3], off offset:144
	s_waitcnt lgkmcnt(1)
	s_nop 0
	v_add_f32_e32 v0, v3, v36
	v_add_f32_e32 v1, v0, v37
	ds_read2_b32 v[36:37], v35 offset0:192 offset1:208
	s_waitcnt lgkmcnt(1)
	v_add_f32_e32 v2, v1, v4
	v_add_f32_e32 v3, v2, v5
	ds_read2_b32 v[4:5], v35 offset0:224 offset1:240
	global_store_dwordx4 v[6:7], v[0:3], off offset:160
	v_add_u32_e32 v35, 0x1c00, v20
	ds_read2_b32 v[38:39], v35 offset0:224 offset1:240
	s_waitcnt lgkmcnt(2)
	v_add_f32_e32 v0, v3, v36
	v_add_f32_e32 v1, v0, v37
	ds_read2_b32 v[36:37], v35 offset1:16
	s_waitcnt lgkmcnt(2)
	v_add_f32_e32 v2, v1, v4
	v_add_f32_e32 v3, v2, v5
	ds_read2_b32 v[4:5], v35 offset0:32 offset1:48
	global_store_dwordx4 v[6:7], v[0:3], off offset:176
	s_waitcnt lgkmcnt(1)
	s_nop 0
	v_add_f32_e32 v0, v3, v36
	v_add_f32_e32 v1, v0, v37
	ds_read2_b32 v[36:37], v35 offset0:64 offset1:80
	s_waitcnt lgkmcnt(1)
	v_add_f32_e32 v2, v1, v4
	v_add_f32_e32 v3, v2, v5
	ds_read2_b32 v[4:5], v35 offset0:96 offset1:112
	global_store_dwordx4 v[6:7], v[0:3], off offset:192
	s_waitcnt lgkmcnt(1)
	s_nop 0
	v_add_f32_e32 v0, v3, v36
	v_add_f32_e32 v1, v0, v37
	ds_read2_b32 v[36:37], v35 offset0:128 offset1:144
	s_waitcnt lgkmcnt(1)
	v_add_f32_e32 v2, v1, v4
	v_add_f32_e32 v3, v2, v5
	ds_read2_b32 v[4:5], v35 offset0:160 offset1:176
	global_store_dwordx4 v[6:7], v[0:3], off offset:208
	s_waitcnt lgkmcnt(1)
	s_nop 0
	v_add_f32_e32 v0, v3, v36
	v_add_f32_e32 v1, v0, v37
	ds_read2_b32 v[36:37], v35 offset0:192 offset1:208
	s_waitcnt lgkmcnt(1)
	v_add_f32_e32 v2, v1, v4
	v_add_f32_e32 v3, v2, v5
	global_store_dwordx4 v[6:7], v[0:3], off offset:224
	s_waitcnt lgkmcnt(0)
	s_nop 0
	v_add_f32_e32 v0, v3, v36
	v_add_f32_e32 v1, v0, v37
	v_add_f32_e32 v2, v1, v38
	v_add_f32_e32 v3, v2, v39
	global_store_dwordx4 v[6:7], v[0:3], off offset:240
	s_nop 1
	v_lshl_or_b32 v0, s26, 4, v255
	v_ashrrev_i32_e32 v1, 31, v0
	v_lshl_add_u64 v[0:1], v[0:1], 2, s[20:21]
	global_store_dword v[0:1], v3, off
	s_branch .LBB0_539
.LBB0_548:
	s_cmpk_gt_i32 s2, 0x7ff
	v_readfirstlane_b32 s1, v255
	s_cbranch_scc1 .LBB0_568
	v_lshrrev_b32_e32 v2, 1, v255
	v_and_b32_e32 v12, 24, v2
	v_lshrrev_b32_e32 v2, 5, v255
	v_and_b32_e32 v2, 4, v2
	v_bfe_u32 v3, v255, 2, 2
	s_add_u32 s33, s54, 0x5600000
	v_lshlrev_b32_e32 v0, 4, v255
	v_and_b32_e32 v1, 32, v255
	s_waitcnt vmcnt(3)
	v_bfe_u32 v11, v255, 2, 4
	v_or3_b32 v2, v2, v3, v12
	v_lshrrev_b32_e32 v3, 3, v255
	s_movk_i32 s0, 0x70
	s_addc_u32 s48, s55, 0
	v_bitop3_b32 v9, v0, v1, 48 bitop3:0x6c
	v_and_b32_e32 v10, 64, v255
	v_and_or_b32 v4, v3, s0, v11
	s_movk_i32 s0, 0x60
	v_add_u32_e32 v13, 0x2000, v0
	s_add_u32 s49, s54, 0x2400000
	v_or_b32_e32 v1, v9, v10
	v_and_or_b32 v3, v3, s0, v2
	v_lshrrev_b32_e32 v0, 7, v13
	s_movk_i32 s0, 0xf0
	s_addc_u32 s50, s55, 0
	v_lshl_or_b32 v130, v3, 12, v1
	v_and_or_b32 v3, v0, s0, v11
	s_movk_i32 s0, 0xe0
	s_ashr_i32 s60, s2, 31
	v_and_or_b32 v0, v0, s0, v2
	s_lshr_b32 s0, s60, 29
	s_add_i32 s0, s2, s0
	s_and_b32 s4, s0, -8
	s_lshr_b32 s12, s1, 6
	s_sub_i32 s4, s2, s4
	s_lshr_b32 s18, s1, 8
	s_lshl_b32 s51, s12, 10
	s_lshl_b32 s6, s4, 8
	s_ashr_i32 s0, s0, 3
	s_mul_i32 s5, s4, 0x101
	s_cmp_lt_i32 s4, 0
	s_cselect_b32 s4, s5, s6
	s_add_i32 s0, s4, s0
	s_ashr_i32 s4, s0, 31
	s_lshr_b32 s4, s4, 24
	s_add_i32 s4, s0, s4
	s_ashr_i32 s5, s4, 8
	s_and_b32 s4, s4, 0xffffff00
	s_sub_i32 s4, s0, s4
	s_sext_i32_i16 s0, s4
	s_bfe_u32 s0, s0, 0x3001c
	s_add_i32 s6, s4, s0
	s_sext_i32_i16 s0, s6
	s_and_b32 s6, s6, 0xfff8
	s_sub_i32 s4, s4, s6
	s_lshl_b32 s5, s5, 3
	s_sext_i32_i16 s4, s4
	s_lshr_b32 s0, s0, 3
	s_add_i32 s4, s5, s4
	s_ashr_i32 s5, s4, 31
	s_bfe_i64 s[10:11], s[0:1], 0x100000
	s_lshl_b64 s[6:7], s[4:5], 20
	s_lshl_b64 s[10:11], s[10:11], 20
	s_add_u32 s44, s49, s10
	s_addc_u32 s45, s50, s11
	s_add_i32 s61, s51, 0
	s_add_i32 m0, s61, 0x10000
	v_lshl_or_b32 v134, v0, 12, v1
	global_load_lds_dwordx4 v130, s[44:45]
	s_add_i32 m0, s61, 0x12000
	s_add_u32 s10, s44, 0x80000
	global_load_lds_dwordx4 v134, s[44:45]
	s_addc_u32 s11, s45, 0
	s_add_i32 m0, s61, 0x14000
	v_lshl_or_b32 v128, v4, 12, v1
	global_load_lds_dwordx4 v130, s[10:11]
	s_add_i32 m0, s61, 0x16000
	s_add_u32 s42, s33, s6
	s_addc_u32 s43, s48, s7
	s_add_i32 s62, s61, 0x2000
	global_load_lds_dwordx4 v134, s[10:11]
	s_mov_b32 m0, s61
	s_add_u32 s6, s42, 0x80000
	v_lshl_or_b32 v132, v3, 12, v1
	global_load_lds_dwordx4 v128, s[42:43]
	s_mov_b32 m0, s62
	s_addc_u32 s7, s43, 0
	s_add_i32 s63, s61, 0x4000
	global_load_lds_dwordx4 v132, s[42:43]
	s_mov_b32 m0, s63
	s_add_i32 s64, s61, 0x6000
	global_load_lds_dwordx4 v128, s[6:7]
	s_mov_b32 m0, s64
	v_mov_b32_e32 v131, 0
	global_load_lds_dwordx4 v132, s[6:7]
	v_mov_b32_e32 v135, v131
	v_mov_b32_e32 v129, v131
	v_mov_b32_e32 v133, v131
	s_cmp_eq_u32 s18, 1
	s_mov_b32 s65, 0
	v_lshl_add_u64 v[6:7], s[44:45], 0, v[130:131]
	v_lshl_add_u64 v[4:5], s[44:45], 0, v[134:135]
	v_lshl_add_u64 v[0:1], s[42:43], 0, v[128:129]
	s_cselect_b64 s[6:7], -1, 0
	s_cmp_lg_u32 s18, 1
	v_lshl_add_u64 v[2:3], s[42:43], 0, v[132:133]
	s_cbranch_scc1 .LBB0_551
	s_barrier
.LBB0_551:
	s_add_u32 s10, s54, 0x9600000
	s_addc_u32 s11, s55, 0
	s_lshl_b32 s5, s12, 5
	s_mov_b64 s[12:13], 0x80
	s_and_b32 s22, s5, 0x60
	s_add_i32 m0, s61, 0x18000
	v_lshl_add_u64 v[6:7], v[6:7], 0, s[12:13]
	s_ashr_i32 s68, s58, 31
	s_lshl_b32 s19, s18, 13
	s_lshl_b32 s23, s22, 7
	s_waitcnt vmcnt(2)
	s_barrier
	global_load_lds_dwordx4 v[6:7], off
	v_lshl_add_u64 v[4:5], v[4:5], 0, s[12:13]
	s_add_i32 m0, s61, 0x1a000
	s_add_i32 s69, s61, 0x8000
	s_add_i32 s70, s61, 0xa000
	global_load_lds_dwordx4 v[4:5], off
	v_lshl_add_u64 v[0:1], v[0:1], 0, s[12:13]
	s_mov_b32 m0, s69
	s_add_u32 s20, s44, 0x80080
	global_load_lds_dwordx4 v[0:1], off
	v_lshl_add_u64 v[0:1], v[2:3], 0, s[12:13]
	s_mov_b32 m0, s70
	s_addc_u32 s21, s45, 0
	global_load_lds_dwordx4 v[0:1], off
	s_add_i32 m0, s61, 0x1c000
	v_lshl_add_u64 v[0:1], s[20:21], 0, v[130:131]
	global_load_lds_dwordx4 v[0:1], off
	v_lshl_add_u64 v[0:1], s[20:21], 0, v[134:135]
	s_add_i32 m0, s61, 0x1e000
	s_sext_i32_i16 s5, s0
	global_load_lds_dwordx4 v[0:1], off
	v_lshlrev_b32_e32 v0, 1, v12
	v_lshlrev_b32_e32 v1, 6, v255
	s_movk_i32 s0, 0x3c0
	v_lshlrev_b32_e32 v2, 2, v255
	v_and_or_b32 v1, v1, s0, v0
	v_and_b32_e32 v2, 32, v2
	v_bitop3_b32 v153, s23, v1, v2 bitop3:0xf6
	v_lshlrev_b32_e32 v1, 9, v255
	v_and_b32_e32 v1, 0x70000, v1
	v_lshlrev_b32_e32 v2, 12, v11
	v_or3_b32 v1, v9, v1, v2
	v_add_u32_e32 v136, v1, v10
	v_lshlrev_b32_e32 v1, 5, v13
	v_lshl_or_b32 v0, v19, 6, v0
	v_and_b32_e32 v3, 32, v8
	s_waitcnt vmcnt(6)
	s_cmpk_lt_u32 s1, 0x100
	v_and_b32_e32 v1, 0xf0000, v1
	v_lshl_or_b32 v152, s18, 6, v19
	v_bitop3_b32 v0, v0, s19, v3 bitop3:0xde
	s_cselect_b64 s[18:19], -1, 0
	v_or3_b32 v1, v9, v1, v2
	s_add_i32 s72, 0, 0x10000
	s_add_i32 s73, 0, 0x14000
	s_mov_b32 s71, s58
	v_or_b32_e32 v154, s22, v12
	v_mov_b32_e32 v137, v131
	v_add_u32_e32 v138, v1, v10
	v_mov_b32_e32 v139, v131
	v_mov_b64_e32 v[140:141], 0x800
	v_mov_b64_e32 v[142:143], 0x7ff
	v_add_u32_e32 v155, s72, v153
	v_add_u32_e32 v156, s73, v153
	v_add_u32_e32 v157, 0, v0
	v_mov_b32_e32 v158, 0x358637bd
	s_mov_b32 s74, 0xf800000
	v_mov_b32_e32 v159, 0x260
	s_mov_b64 s[20:21], 0x200000
	s_mov_b32 s75, 0x200000
	s_mov_b64 s[22:23], 0x240000
	s_mov_b32 s76, 0x240000
	s_mov_b64 s[24:25], 0x280000
	s_mov_b32 s77, 0x280000
	s_mov_b64 s[26:27], 0x2c0000
	s_mov_b32 s78, 0x2c0000
	v_mov_b32_e32 v160, 0x3e0293ee
	s_barrier
	s_branch .LBB0_554

.LBB0_568:
	s_cmp_gt_i32 s57, 7
	s_cselect_b64 s[0:1], -1, 0
	s_and_b64 s[4:5], s[14:15], s[0:1]
	s_andn2_b64 vcc, exec, s[4:5]
	s_cbranch_vccnz .LBB0_622
	s_waitcnt vmcnt(0)
	s_barrier
	s_and_saveexec_b64 s[4:5], s[8:9]
	s_cbranch_execz .LBB0_621
	s_add_i32 s6, 0, 0x23000
	v_mov_b32_e32 v0, s6
	s_waitcnt vmcnt(0) expcnt(0) lgkmcnt(0)
	ds_read_b32 v2, v0
	s_add_i32 s6, 0, 0x23004
	v_mov_b32_e32 v0, s6
	ds_read_b32 v0, v0
	s_waitcnt lgkmcnt(1)
	v_cmp_ne_u32_e32 vcc, 0, v2
	s_cbranch_vccnz .LBB0_585
	v_readlane_b32 s6, v254, 0
	s_mul_i32 s33, s59, s6
	s_add_u32 s6, s54, 0x80200
	s_addc_u32 s7, s55, 0
	s_add_u32 s10, s54, 0x80400
	s_addc_u32 s11, s55, 0
	s_add_u32 s12, s54, 0x80500
	s_addc_u32 s13, s55, 0
	s_add_u32 s14, s54, 0x80600
	s_addc_u32 s15, s55, 0
	s_add_u32 s16, s54, 0x80700
	s_addc_u32 s17, s55, 0
	s_add_u32 s18, s54, 0x80800
	s_addc_u32 s19, s55, 0
	s_add_u32 s20, s54, 0x80900
	s_addc_u32 s21, s55, 0
	s_add_u32 s22, s54, 0x80a00
	s_addc_u32 s23, s55, 0
	s_add_u32 s24, s54, 0x80b00
	s_addc_u32 s25, s55, 0
	s_add_u32 s26, s54, 0x80c00
	s_addc_u32 s27, s55, 0
	s_add_u32 s34, s54, 0x80d00
	s_addc_u32 s35, s55, 0
	s_add_u32 s36, s54, 0x80e00
	s_addc_u32 s37, s55, 0
	s_add_u32 s38, s54, 0x80f00
	s_addc_u32 s39, s55, 0
	s_add_u32 s40, s54, 0x81000
	s_addc_u32 s41, s55, 0
	s_add_u32 s42, s54, 0x81100
	s_addc_u32 s43, s55, 0
	s_add_u32 s44, s54, 0x81200
	s_addc_u32 s45, s55, 0
	s_add_u32 s46, s54, 0x81300
	s_mul_i32 s33, s33, s58
	s_addc_u32 s47, s55, 0
	s_mov_b32 s62, 1
	v_mov_b32_e32 v16, 0
	s_branch .LBB0_573

.LBB0_626:
	v_mov_b32_e32 v18, v255
	s_and_b32 s50, s88, 7
	s_ashr_i32 s0, s88, 7
	s_xor_b32 s51, s50, 15
	v_readfirstlane_b32 s5, v18
	s_ashr_i32 s1, s0, 31
	s_ashr_i32 s33, s5, 1
	s_lshl_b64 s[22:23], s[0:1], 12
	s_lshl_b32 s60, s51, 8
	s_andn2_b32 s33, s33, 31
	s_bfe_u32 s4, s88, 0x40003
	s_lshl_b64 s[6:7], s[0:1], 26
	s_or_b32 s1, s22, s60
	s_ashr_i32 s16, s33, 31
	s_add_u32 s24, s1, s33
	v_and_b32_e32 v30, 31, v18
	s_addc_u32 s25, s23, s16
	v_or_b32_e32 v2, s24, v30
	v_mov_b32_e32 v3, s25
	v_lshlrev_b64 v[2:3], 14, v[2:3]
	v_bfe_u32 v31, v18, 5, 1
	v_lshl_add_u64 v[2:3], s[12:13], 0, v[2:3]
	s_lshl_b32 s16, s4, 8
	v_lshl_add_u64 v[2:3], v[2:3], 0, s[16:17]
	v_lshlrev_b32_e32 v0, 4, v31
	v_ashrrev_i32_e32 v19, 31, v18
	v_lshl_add_u64 v[2:3], v[2:3], 0, v[0:1]
	v_lshrrev_b32_e32 v0, 28, v19
	s_add_u32 s1, s12, s6
	v_add_u32_e32 v0, v18, v0
	s_addc_u32 s6, s13, s7
	v_ashrrev_i32_e32 v146, 4, v0
	v_and_b32_e32 v0, -16, v0
	s_add_u32 s20, s1, s16
	v_sub_u32_e32 v0, v18, v0
	v_ashrrev_i32_e32 v147, 31, v146
	global_load_dwordx4 v[98:101], v[2:3], off
	global_load_dwordx4 v[102:105], v[2:3], off offset:32
	global_load_dwordx4 v[106:109], v[2:3], off offset:64
	global_load_dwordx4 v[110:113], v[2:3], off offset:96
	global_load_dwordx4 v[114:117], v[2:3], off offset:128
	global_load_dwordx4 v[118:121], v[2:3], off offset:160
	global_load_dwordx4 v[122:125], v[2:3], off offset:192
	global_load_dwordx4 v[126:129], v[2:3], off offset:224
	s_addc_u32 s21, s6, 0
	v_lshlrev_b64 v[2:3], 14, v[146:147]
	v_lshlrev_b32_e32 v20, 3, v0
	v_lshl_add_u64 v[2:3], s[20:21], 0, v[2:3]
	v_ashrrev_i32_e32 v21, 31, v20
	v_lshl_add_u64 v[2:3], v[20:21], 1, v[2:3]
	v_add_co_u32_e32 v2, vcc, s43, v2
	s_cmp_gt_u32 s5, 63
	s_nop 0
	v_addc_co_u32_e32 v3, vcc, 0, v3, vcc
	global_load_dwordx4 v[14:17], v[2:3], off offset:-4096
	global_load_dwordx4 v[10:13], v[2:3], off
	v_add_u32_e32 v2, 0x200, v18
	v_ashrrev_i32_e32 v3, 31, v2
	v_lshrrev_b32_e32 v3, 28, v3
	v_add_u32_e32 v3, v2, v3
	v_ashrrev_i32_e32 v148, 4, v3
	v_and_b32_e32 v3, -16, v3
	v_sub_u32_e32 v32, v2, v3
	v_ashrrev_i32_e32 v149, 31, v148
	v_lshlrev_b64 v[2:3], 14, v[148:149]
	v_lshlrev_b32_e32 v22, 3, v32
	v_lshl_add_u64 v[2:3], s[20:21], 0, v[2:3]
	v_ashrrev_i32_e32 v23, 31, v22
	v_lshl_add_u64 v[2:3], v[22:23], 1, v[2:3]
	v_add_co_u32_e32 v4, vcc, 0x1000, v2
	v_and_b32_e32 v156, 63, v18
	s_nop 0
	v_addc_co_u32_e32 v5, vcc, 0, v3, vcc
	v_add_co_u32_e32 v6, vcc, 0x2000, v2
	s_nop 1
	v_addc_co_u32_e32 v7, vcc, 0, v3, vcc
	global_load_dwordx4 v[2:5], v[4:5], off
	s_nop 0
	global_load_dwordx4 v[6:9], v[6:7], off
	s_cbranch_scc1 .LBB0_628
	s_lshl_b32 s1, s0, 10
	v_lshl_or_b32 v24, v156, 4, s1
	v_or_b32_e32 v24, s4, v24
	v_ashrrev_i32_e32 v25, 31, v24
	v_lshl_add_u64 v[24:25], v[24:25], 2, s[14:15]
	global_load_dword v24, v[24:25], off
	v_and_b32_e32 v25, 64, v154
	v_add_u32_e32 v26, -1, v154
	v_cmp_lt_i32_e32 vcc, v26, v25
	v_add_u32_e32 v27, -2, v154
	v_add_u32_e32 v28, -4, v154
	v_cndmask_b32_e32 v26, v26, v154, vcc
	v_lshlrev_b32_e32 v26, 2, v26
	v_cmp_lt_i32_e32 vcc, v27, v25
	s_waitcnt vmcnt(0)
	ds_bpermute_b32 v26, v26, v24
	v_cndmask_b32_e32 v27, v27, v154, vcc
	v_cmp_eq_u32_e32 vcc, 0, v156
	v_lshlrev_b32_e32 v27, 2, v27
	s_waitcnt lgkmcnt(0)
	v_add_f32_e32 v26, v24, v26
	v_cndmask_b32_e32 v26, v26, v24, vcc
	ds_bpermute_b32 v27, v27, v26
	v_cmp_lt_i32_e32 vcc, v28, v25
	s_waitcnt lgkmcnt(0)
	v_add_f32_e32 v27, v26, v27
	v_cndmask_b32_e32 v28, v28, v154, vcc
	v_cmp_gt_u32_e32 vcc, 2, v156
	v_lshlrev_b32_e32 v28, 2, v28
	s_nop 0
	v_cndmask_b32_e32 v26, v27, v26, vcc
	ds_bpermute_b32 v27, v28, v26
	v_add_u32_e32 v28, -8, v154
	v_cmp_lt_i32_e32 vcc, v28, v25
	s_waitcnt lgkmcnt(0)
	v_add_f32_e32 v27, v26, v27
	v_cndmask_b32_e32 v28, v28, v154, vcc
	v_cmp_gt_u32_e32 vcc, 4, v156
	v_lshlrev_b32_e32 v28, 2, v28
	s_nop 0
	v_cndmask_b32_e32 v26, v27, v26, vcc
	ds_bpermute_b32 v27, v28, v26
	v_add_u32_e32 v28, -16, v154
	v_cmp_lt_i32_e32 vcc, v28, v25
	s_waitcnt lgkmcnt(0)
	v_add_f32_e32 v27, v26, v27
	v_cndmask_b32_e32 v28, v28, v154, vcc
	v_cmp_gt_u32_e32 vcc, 8, v156
	v_lshlrev_b32_e32 v28, 2, v28
	s_nop 0
	v_cndmask_b32_e32 v26, v27, v26, vcc
	ds_bpermute_b32 v27, v28, v26
	v_subrev_u32_e32 v28, 32, v154
	v_cmp_lt_i32_e32 vcc, v28, v25
	s_waitcnt lgkmcnt(0)
	v_add_f32_e32 v27, v26, v27
	v_cndmask_b32_e32 v25, v28, v154, vcc
	v_cmp_gt_u32_e32 vcc, 16, v156
	v_lshlrev_b32_e32 v25, 2, v25
	s_nop 0
	v_cndmask_b32_e32 v26, v27, v26, vcc
	ds_bpermute_b32 v25, v25, v26
	v_cmp_gt_u32_e32 vcc, 32, v156
	v_lshl_add_u32 v27, v156, 2, 0
	s_waitcnt lgkmcnt(0)
	v_add_f32_e32 v25, v26, v25
	v_cndmask_b32_e32 v25, v25, v26, vcc
	v_sub_f32_e32 v24, v25, v24
	v_add_u32_e32 v25, 0x16800, v27
	ds_write_b32 v25, v24

.LBB0_646:
	v_mul_lo_u32 v157, v146, s45
	v_lshlrev_b32_e32 v158, 4, v0
	v_add3_u32 v0, 0, v157, v158
	s_waitcnt vmcnt(0)
	ds_write_b128 v0, v[14:17]
	v_mad_u64_u32 v[14:15], s[4:5], v146, 48, v[0:1]
	ds_write_b128 v14, v[10:13] offset:34816
	v_lshlrev_b64 v[10:11], 14, v[146:147]
	v_lshl_add_u64 v[10:11], s[20:21], 0, v[10:11]
	v_lshlrev_b64 v[12:13], 1, v[20:21]
	v_lshl_add_u64 v[10:11], v[10:11], 0, v[12:13]
	v_add_co_u32_e32 v10, vcc, s47, v10
	v_lshlrev_b64 v[14:15], 1, v[22:23]
	s_nop 0
	v_addc_co_u32_e32 v11, vcc, 0, v11, vcc
	global_load_dwordx4 v[130:133], v[10:11], off offset:-4096
	global_load_dwordx4 v[134:137], v[10:11], off
	v_lshlrev_b64 v[10:11], 14, v[148:149]
	v_lshl_add_u64 v[10:11], s[20:21], 0, v[10:11]
	v_lshl_add_u64 v[10:11], v[10:11], 0, v[14:15]
	v_add_co_u32_e32 v10, vcc, s47, v10
	v_mul_lo_u32 v160, v148, s45
	s_nop 0
	v_addc_co_u32_e32 v11, vcc, 0, v11, vcc
	global_load_dwordx4 v[138:141], v[10:11], off offset:-4096
	global_load_dwordx4 v[142:145], v[10:11], off
	v_lshlrev_b32_e32 v161, 4, v32
	v_add3_u32 v0, 0, v160, v161
	ds_write_b128 v0, v[2:5]
	v_mad_u64_u32 v[2:3], s[4:5], v148, 48, v[0:1]
	v_lshrrev_b32_e32 v0, 2, v18
	v_lshlrev_b32_e32 v163, 2, v31
	ds_write_b128 v2, v[6:9] offset:34816
	v_and_or_b32 v0, v0, 3, v163
	v_lshlrev_b32_e32 v2, 1, v18
	v_lshlrev_b32_e32 v3, 3, v18
	s_add_i32 s5, s33, s60
	v_lshl_add_u32 v149, v31, 4, 0
	v_mad_u32_u24 v0, v0, s46, 0
	v_and_b32_e32 v2, 32, v2
	v_and_b32_e32 v3, 24, v3
	v_lshl_add_u64 v[152:153], s[20:21], 0, v[14:15]
	v_mov_b32_e32 v14, v1
	v_mov_b32_e32 v15, v1
	v_mad_u32_u24 v162, v30, s45, v149
	v_add3_u32 v164, v0, v2, v3
	v_lshl_add_u64 v[150:151], s[20:21], 0, v[12:13]
	v_add_u32_e32 v195, s5, v30
	v_mov_b32_e32 v0, v1
	v_mov_b32_e32 v2, v1
	v_mov_b32_e32 v3, v1
	v_mov_b32_e32 v4, v1
	v_mov_b32_e32 v5, v1
	v_mov_b32_e32 v6, v1
	v_mov_b32_e32 v7, v1
	v_mov_b32_e32 v8, v1
	v_mov_b32_e32 v9, v1
	v_mov_b32_e32 v10, v1
	v_mov_b32_e32 v11, v1
	v_mov_b32_e32 v12, v1
	v_mov_b32_e32 v13, v1
	v_mov_b64_e32 v[64:65], v[14:15]
	v_mov_b64_e32 v[48:49], v[14:15]
	v_mov_b64_e32 v[32:33], v[14:15]
	s_lshl_b32 s6, s51, 2
	s_lshl_b32 s7, s51, 10
	v_mov_b64_e32 v[62:63], v[12:13]
	v_mov_b64_e32 v[60:61], v[10:11]
	v_mov_b64_e32 v[58:59], v[8:9]
	v_mov_b64_e32 v[56:57], v[6:7]
	v_mov_b64_e32 v[54:55], v[4:5]
	v_mov_b64_e32 v[52:53], v[2:3]
	v_mov_b64_e32 v[50:51], v[0:1]
	v_mov_b64_e32 v[46:47], v[12:13]
	v_mov_b64_e32 v[44:45], v[10:11]
	v_mov_b64_e32 v[42:43], v[8:9]
	v_mov_b64_e32 v[40:41], v[6:7]
	v_mov_b64_e32 v[38:39], v[4:5]
	v_mov_b64_e32 v[36:37], v[2:3]
	v_mov_b64_e32 v[34:35], v[0:1]
	v_mov_b64_e32 v[30:31], v[12:13]
	v_mov_b64_e32 v[28:29], v[10:11]
	v_mov_b64_e32 v[26:27], v[8:9]
	v_mov_b64_e32 v[24:25], v[6:7]
	v_mov_b64_e32 v[22:23], v[4:5]
	v_mov_b64_e32 v[20:21], v[2:3]
	v_mov_b64_e32 v[18:19], v[0:1]
	v_mov_b64_e32 v[16:17], v[14:15]
	s_mov_b32 s0, 2
	s_add_i32 s1, s6, 4
	v_mul_lo_u32 v159, v146, s46
	v_mul_lo_u32 v147, v148, s46
	s_mov_b32 s4, 0
	s_or_b32 s6, s6, 3
	v_or_b32_e32 v165, 32, v163
	v_or_b32_e32 v166, 33, v163
	v_or_b32_e32 v167, 2, v163
	v_or_b32_e32 v168, 34, v163
	v_or_b32_e32 v169, 3, v163
	v_or_b32_e32 v170, 35, v163
	v_or_b32_e32 v171, 8, v163
	v_or_b32_e32 v172, 40, v163
	v_or_b32_e32 v173, 9, v163
	v_or_b32_e32 v174, 41, v163
	v_or_b32_e32 v175, 10, v163
	v_or_b32_e32 v176, 42, v163
	v_or_b32_e32 v177, 11, v163
	v_or_b32_e32 v178, 43, v163
	v_or_b32_e32 v179, 16, v163
	v_or_b32_e32 v180, 48, v163
	v_or_b32_e32 v181, 17, v163
	v_or_b32_e32 v182, 49, v163
	v_or_b32_e32 v183, 18, v163
	v_or_b32_e32 v184, 50, v163
	v_or_b32_e32 v185, 19, v163
	v_or_b32_e32 v186, 51, v163
	v_or_b32_e32 v187, 24, v163
	v_or_b32_e32 v188, 56, v163
	v_or_b32_e32 v189, 25, v163
	v_or_b32_e32 v190, 57, v163
	v_or_b32_e32 v191, 26, v163
	v_or_b32_e32 v192, 58, v163
	v_or_b32_e32 v193, 27, v163
	v_or_b32_e32 v194, 59, v163
	s_addk_i32 s7, 0x400
	v_mov_b32_e32 v196, 0
	v_mov_b32_e32 v197, 0xf149f2ca
	s_mov_b32 s26, 63
	v_mov_b64_e32 v[14:15], v[12:13]
	v_mov_b64_e32 v[12:13], v[10:11]
	v_mov_b64_e32 v[10:11], v[8:9]
	v_mov_b64_e32 v[8:9], v[6:7]
	v_mov_b64_e32 v[6:7], v[4:5]
	v_mov_b64_e32 v[4:5], v[2:3]
	v_mov_b64_e32 v[2:3], v[0:1]
	s_waitcnt lgkmcnt(0)
	s_movk_i32 s68, 0x5000
	s_mov_b32 s69, 0
	s_mov_b32 s70, 0xe800
	s_mov_b32 s72, 0
	s_barrier
	s_branch .LBB0_649
.LBB0_649:
	s_add_i32 s27, s0, -2
	s_and_b32 s27, s27, 1
	s_xor_b32 s34, s27, 1
	s_mul_i32 s35, s34, 0x4400
	s_add_i32 s35, s35, 0
	s_mulk_i32 s34, 0xc00
	s_add_i32 s34, s35, s34
	v_add3_u32 v0, s35, v157, v158
	s_waitcnt vmcnt(3)
	ds_write_b128 v0, v[130:133]
	v_add3_u32 v0, s68, v159, v158
	s_waitcnt vmcnt(2)
	ds_write_b128 v0, v[134:137] offset:34816
	v_add3_u32 v0, s35, v160, v161
	s_cmp_lt_u32 s0, s1
	s_waitcnt vmcnt(1)
	ds_write_b128 v0, v[138:141]
	v_add3_u32 v0, s68, v147, v161
	s_cselect_b32 s34, s0, s6
	s_lshl_b32 s34, s34, 6
	v_add_u32_e32 v250, s34, v146
	v_ashrrev_i32_e32 v251, 31, v250
	v_lshlrev_b64 v[250:251], 14, v[250:251]
	v_lshl_add_u64 v[250:251], v[150:151], 0, v[250:251]
	v_add_co_u32_e32 v252, vcc, s42, v250
	s_waitcnt vmcnt(0)
	ds_write_b128 v0, v[142:145] offset:34816
	v_addc_co_u32_e32 v253, vcc, 0, v251, vcc
	v_add_co_u32_e32 v250, vcc, 0x2000, v250
	s_nop 1
	v_addc_co_u32_e32 v251, vcc, 0, v251, vcc
	global_load_dwordx4 v[130:133], v[252:253], off
	global_load_dwordx4 v[134:137], v[250:251], off
	v_add_u32_e32 v250, s34, v148
	v_ashrrev_i32_e32 v251, 31, v250
	v_lshlrev_b64 v[250:251], 14, v[250:251]
	v_lshl_add_u64 v[250:251], v[152:153], 0, v[250:251]
	v_add_co_u32_e32 v252, vcc, 0x1000, v250
	s_sub_i32 s34, s26, 63
	s_nop 0
	v_addc_co_u32_e32 v253, vcc, 0, v251, vcc
	v_add_co_u32_e32 v250, vcc, 0x2000, v250
	s_cmp_gt_i32 s34, s5
	s_nop 0
	v_addc_co_u32_e32 v251, vcc, 0, v251, vcc
	global_load_dwordx4 v[138:141], v[252:253], off
	global_load_dwordx4 v[142:145], v[250:251], off
	s_sub_i32 s34, s26, 63
	s_cmp_gt_i32 s34, s5
	s_cbranch_scc1 .Lff1_inact
	s_cmp_eq_u32 s72, 0
	s_cbranch_scc1 .Lff1_first
	s_mul_i32 s34, s27, 0x4400
	v_add_u32_e32 v0, s34, v162
	ds_read_b128 v[198:201], v0
	ds_read_b128 v[202:205], v0 offset:32
	ds_read_b128 v[206:209], v0 offset:8704
	ds_read_b128 v[210:213], v0 offset:8736
	v_add_u32_e32 v246, s4, v149
	v_add_u32_e32 v234, 0x12800, v246
	v_add_u32_e32 v235, 0x12880, v246
	v_add_u32_e32 v238, 0x12820, v246
	v_add_u32_e32 v239, 0x128a0, v246
	v_add_u32_e32 v242, 0x12840, v246
	v_add_u32_e32 v243, 0x128c0, v246
	v_add_u32_e32 v247, 0x12860, v246
	v_add_u32_e32 v246, 0x128e0, v246
	ds_read_b128 v[218:221], v234
	ds_read_b128 v[234:237], v235
	ds_read_b128 v[222:225], v238
	ds_read_b128 v[238:241], v239
	ds_read_b128 v[226:229], v242
	ds_read_b128 v[242:245], v243
	ds_read_b128 v[230:233], v247
	ds_read_b128 v[246:249], v246
	s_waitcnt lgkmcnt(1)
	v_mfma_f32_32x32x16_bf16 v[218:233], v[198:201], v[98:101], v[218:233]
	v_sub_f32_e32 v82, v82, v197
	v_sub_f32_e32 v83, v83, v197
	v_sub_f32_e32 v84, v84, v197
	v_sub_f32_e32 v85, v85, v197
	v_exp_f32_e32 v82, v82
	v_exp_f32_e32 v83, v83
	v_exp_f32_e32 v84, v84
	v_exp_f32_e32 v85, v85
	s_waitcnt lgkmcnt(0)
	v_mfma_f32_32x32x16_bf16 v[234:249], v[206:209], v[98:101], v[234:249]
	v_sub_f32_e32 v86, v86, v197
	v_sub_f32_e32 v87, v87, v197
	v_sub_f32_e32 v88, v88, v197
	v_sub_f32_e32 v89, v89, v197
	v_exp_f32_e32 v86, v86
	v_exp_f32_e32 v87, v87
	v_exp_f32_e32 v88, v88
	v_exp_f32_e32 v89, v89
	v_mfma_f32_32x32x16_bf16 v[218:233], v[202:205], v[102:105], v[218:233]
	v_sub_f32_e32 v66, v66, v197
	v_sub_f32_e32 v67, v67, v197
	v_sub_f32_e32 v68, v68, v197
	v_sub_f32_e32 v69, v69, v197
	v_exp_f32_e32 v66, v66
	v_exp_f32_e32 v67, v67
	v_exp_f32_e32 v68, v68
	v_exp_f32_e32 v69, v69
	ds_read_b128 v[198:201], v0 offset:64
	ds_read_b128 v[202:205], v0 offset:96
	ds_read_b128 v[206:209], v0 offset:8768
	ds_read_b128 v[214:217], v0 offset:8800
	v_mfma_f32_32x32x16_bf16 v[234:249], v[210:213], v[102:105], v[234:249]
	v_add_f32_e32 v250, v82, v86
	v_add_f32_e32 v251, v83, v87
	v_add_f32_e32 v252, v84, v88
	v_add_f32_e32 v253, v85, v89
	v_sub_f32_e32 v70, v70, v197
	v_sub_f32_e32 v71, v71, v197
	v_sub_f32_e32 v72, v72, v197
	v_sub_f32_e32 v73, v73, v197
	s_waitcnt lgkmcnt(3)
	v_mfma_f32_32x32x16_bf16 v[218:233], v[198:201], v[106:109], v[218:233]
	v_exp_f32_e32 v70, v70
	v_exp_f32_e32 v71, v71
	v_exp_f32_e32 v72, v72
	v_exp_f32_e32 v73, v73
	v_add_f32_e32 v250, v250, v66
	v_add_f32_e32 v251, v251, v67
	v_add_f32_e32 v252, v252, v68
	v_add_f32_e32 v253, v253, v69
	s_waitcnt lgkmcnt(1)
	v_mfma_f32_32x32x16_bf16 v[234:249], v[206:209], v[106:109], v[234:249]
	v_sub_f32_e32 v90, v90, v197
	v_sub_f32_e32 v91, v91, v197
	v_sub_f32_e32 v92, v92, v197
	v_sub_f32_e32 v93, v93, v197
	v_exp_f32_e32 v90, v90
	v_exp_f32_e32 v91, v91
	v_exp_f32_e32 v92, v92
	v_exp_f32_e32 v93, v93
	v_mfma_f32_32x32x16_bf16 v[218:233], v[202:205], v[110:113], v[218:233]
	v_add_f32_e32 v250, v250, v70
	v_add_f32_e32 v251, v251, v71
	v_add_f32_e32 v252, v252, v72
	v_add_f32_e32 v253, v253, v73
	v_sub_f32_e32 v94, v94, v197
	v_sub_f32_e32 v95, v95, v197
	v_sub_f32_e32 v96, v96, v197
	v_sub_f32_e32 v97, v97, v197
	ds_read_b128 v[198:201], v0 offset:128
	ds_read_b128 v[202:205], v0 offset:160
	ds_read_b128 v[206:209], v0 offset:8832
	ds_read_b128 v[210:213], v0 offset:8864
	s_waitcnt lgkmcnt(4)
	v_mfma_f32_32x32x16_bf16 v[234:249], v[214:217], v[110:113], v[234:249]
	v_exp_f32_e32 v94, v94
	v_exp_f32_e32 v95, v95
	v_exp_f32_e32 v96, v96
	v_exp_f32_e32 v97, v97
	v_add_f32_e32 v250, v250, v90
	v_add_f32_e32 v251, v251, v91
	v_add_f32_e32 v252, v252, v92
	v_add_f32_e32 v253, v253, v93
	s_waitcnt lgkmcnt(3)
	v_mfma_f32_32x32x16_bf16 v[218:233], v[198:201], v[114:117], v[218:233]
	v_sub_f32_e32 v74, v74, v197
	v_sub_f32_e32 v75, v75, v197
	v_sub_f32_e32 v76, v76, v197
	v_sub_f32_e32 v77, v77, v197
	v_exp_f32_e32 v74, v74
	v_exp_f32_e32 v75, v75
	v_exp_f32_e32 v76, v76
	v_exp_f32_e32 v77, v77
	s_waitcnt lgkmcnt(1)
	v_mfma_f32_32x32x16_bf16 v[234:249], v[206:209], v[114:117], v[234:249]
	v_add_f32_e32 v250, v250, v94
	v_add_f32_e32 v251, v251, v95
	v_add_f32_e32 v252, v252, v96
	v_add_f32_e32 v253, v253, v97
	v_sub_f32_e32 v78, v78, v197
	v_sub_f32_e32 v79, v79, v197
	v_sub_f32_e32 v80, v80, v197
	v_sub_f32_e32 v81, v81, v197
	v_mfma_f32_32x32x16_bf16 v[218:233], v[202:205], v[118:121], v[218:233]
	v_exp_f32_e32 v78, v78
	v_exp_f32_e32 v79, v79
	v_exp_f32_e32 v80, v80
	v_exp_f32_e32 v81, v81
	v_add_f32_e32 v250, v250, v74
	v_add_f32_e32 v251, v251, v75
	v_add_f32_e32 v252, v252, v76
	v_add_f32_e32 v253, v253, v77
	ds_read_b128 v[198:201], v0 offset:192
	ds_read_b128 v[202:205], v0 offset:224
	ds_read_b128 v[206:209], v0 offset:8896
	ds_read_b128 v[214:217], v0 offset:8928
	s_waitcnt lgkmcnt(4)
	v_mfma_f32_32x32x16_bf16 v[234:249], v[210:213], v[118:121], v[234:249]
	v_add_f32_e32 v250, v250, v78
	v_add_f32_e32 v251, v251, v79
	v_add_f32_e32 v252, v252, v80
	v_add_f32_e32 v253, v253, v81
	v_add_f32_e32 v250, v250, v251
	v_add_f32_e32 v252, v252, v253
	v_add_f32_e32 v250, v250, v252
	v_add_f32_e32 v196, v196, v250
	s_waitcnt lgkmcnt(3)
	v_mfma_f32_32x32x16_bf16 v[218:233], v[198:201], v[122:125], v[218:233]
	v_cvt_pk_bf16_f32 v73, v72, v73
	v_cvt_pk_bf16_f32 v72, v70, v71
	v_cvt_pk_bf16_f32 v71, v68, v69
	v_cvt_pk_bf16_f32 v70, v66, v67
	v_cvt_pk_bf16_f32 v66, v82, v83
	v_cvt_pk_bf16_f32 v67, v84, v85
	v_cvt_pk_bf16_f32 v68, v86, v87
	v_cvt_pk_bf16_f32 v69, v88, v89
	s_waitcnt lgkmcnt(1)
	v_mfma_f32_32x32x16_bf16 v[234:249], v[206:209], v[122:125], v[234:249]
	v_cvt_pk_bf16_f32 v81, v80, v81
	v_cvt_pk_bf16_f32 v80, v78, v79
	v_cvt_pk_bf16_f32 v79, v76, v77
	v_cvt_pk_bf16_f32 v78, v74, v75
	v_cvt_pk_bf16_f32 v74, v90, v91
	v_cvt_pk_bf16_f32 v75, v92, v93
	v_cvt_pk_bf16_f32 v76, v94, v95
	v_cvt_pk_bf16_f32 v77, v96, v97
	v_mfma_f32_32x32x16_bf16 v[218:233], v[202:205], v[126:129], v[218:233]
	s_waitcnt lgkmcnt(0)
	v_mfma_f32_32x32x16_bf16 v[234:249], v[214:217], v[126:129], v[234:249]
	s_cmp_le_i32 s26, s5
	s_cbranch_scc1 .Lff1_z2
	v_cmp_le_i32_e32 vcc, v165, v195
	s_nop 8
	v_cndmask_b32_e32 v234, v155, v234, vcc
	v_cmp_lt_i32_e32 vcc, v163, v195
	s_nop 1
	v_cndmask_b32_e32 v219, v155, v219, vcc
	v_cmp_le_i32_e32 vcc, v163, v195
	s_nop 1
	v_cndmask_b32_e32 v218, v155, v218, vcc
	v_cmp_le_i32_e32 vcc, v166, v195
	s_nop 1
	v_cndmask_b32_e32 v235, v155, v235, vcc
	v_cmp_le_i32_e32 vcc, v167, v195
	s_nop 1
	v_cndmask_b32_e32 v220, v155, v220, vcc
	v_cmp_le_i32_e32 vcc, v168, v195
	s_nop 1
	v_cndmask_b32_e32 v236, v155, v236, vcc
	v_cmp_le_i32_e32 vcc, v169, v195
	s_nop 1
	v_cndmask_b32_e32 v221, v155, v221, vcc
	v_cmp_le_i32_e32 vcc, v170, v195
	s_nop 1
	v_cndmask_b32_e32 v237, v155, v237, vcc
	v_cmp_le_i32_e32 vcc, v171, v195
	s_nop 1
	v_cndmask_b32_e32 v222, v155, v222, vcc
	v_cmp_le_i32_e32 vcc, v172, v195
	s_nop 1
	v_cndmask_b32_e32 v238, v155, v238, vcc
	v_cmp_le_i32_e32 vcc, v173, v195
	s_nop 1
	v_cndmask_b32_e32 v223, v155, v223, vcc
	v_cmp_le_i32_e32 vcc, v174, v195
	s_nop 1
	v_cndmask_b32_e32 v239, v155, v239, vcc
	v_cmp_le_i32_e32 vcc, v175, v195
	s_nop 1
	v_cndmask_b32_e32 v224, v155, v224, vcc
	v_cmp_le_i32_e32 vcc, v176, v195
	s_nop 1
	v_cndmask_b32_e32 v240, v155, v240, vcc
	v_cmp_le_i32_e32 vcc, v177, v195
	s_nop 1
	v_cndmask_b32_e32 v225, v155, v225, vcc
	v_cmp_le_i32_e32 vcc, v178, v195
	s_nop 1
	v_cndmask_b32_e32 v241, v155, v241, vcc
	v_cmp_le_i32_e32 vcc, v179, v195
	s_nop 1
	v_cndmask_b32_e32 v226, v155, v226, vcc
	v_cmp_le_i32_e32 vcc, v180, v195
	s_nop 1
	v_cndmask_b32_e32 v242, v155, v242, vcc
	v_cmp_le_i32_e32 vcc, v181, v195
	s_nop 1
	v_cndmask_b32_e32 v227, v155, v227, vcc
	v_cmp_le_i32_e32 vcc, v182, v195
	s_nop 1
	v_cndmask_b32_e32 v243, v155, v243, vcc
	v_cmp_le_i32_e32 vcc, v183, v195
	s_nop 1
	v_cndmask_b32_e32 v228, v155, v228, vcc
	v_cmp_le_i32_e32 vcc, v184, v195
	s_nop 1
	v_cndmask_b32_e32 v244, v155, v244, vcc
	v_cmp_le_i32_e32 vcc, v185, v195
	s_nop 1
	v_cndmask_b32_e32 v229, v155, v229, vcc
	v_cmp_le_i32_e32 vcc, v186, v195
	s_nop 1
	v_cndmask_b32_e32 v245, v155, v245, vcc
	v_cmp_le_i32_e32 vcc, v187, v195
	s_nop 1
	v_cndmask_b32_e32 v230, v155, v230, vcc
	v_cmp_le_i32_e32 vcc, v188, v195
	s_nop 1
	v_cndmask_b32_e32 v246, v155, v246, vcc
	v_cmp_le_i32_e32 vcc, v189, v195
	s_nop 1
	v_cndmask_b32_e32 v231, v155, v231, vcc
	v_cmp_le_i32_e32 vcc, v190, v195
	s_nop 1
	v_cndmask_b32_e32 v247, v155, v247, vcc
	v_cmp_le_i32_e32 vcc, v191, v195
	s_nop 1
	v_cndmask_b32_e32 v232, v155, v232, vcc
	v_cmp_le_i32_e32 vcc, v192, v195
	s_nop 1
	v_cndmask_b32_e32 v248, v155, v248, vcc
	v_cmp_le_i32_e32 vcc, v193, v195
	s_nop 1
	v_cndmask_b32_e32 v233, v155, v233, vcc
	v_cmp_le_i32_e32 vcc, v194, v195
	s_nop 1
	v_cndmask_b32_e32 v249, v155, v249, vcc
.Lff1_z2:
	v_add_u32_e32 v250, s70, v164
	ds_read_b64_tr_b16 v[82:83], v250 offset:34816
	ds_read_b64_tr_b16 v[84:85], v250 offset:37376
	ds_read_b64_tr_b16 v[86:87], v250 offset:39936
	ds_read_b64_tr_b16 v[88:89], v250 offset:42496
	ds_read_b64_tr_b16 v[90:91], v250 offset:45056
	ds_read_b64_tr_b16 v[92:93], v250 offset:47616
	ds_read_b64_tr_b16 v[94:95], v250 offset:50176
	ds_read_b64_tr_b16 v[96:97], v250 offset:52736
	s_waitcnt lgkmcnt(6)
	v_mfma_f32_32x32x16_bf16 v[50:65], v[82:85], v[66:69], v[50:65]
	s_waitcnt lgkmcnt(4)
	v_mfma_f32_32x32x16_bf16 v[50:65], v[86:89], v[74:77], v[50:65]
	v_max3_f32 v0, v218, v234, v219
	v_max3_f32 v251, v222, v238, v223
	v_max3_f32 v252, v226, v242, v227
	s_waitcnt lgkmcnt(2)
	v_mfma_f32_32x32x16_bf16 v[50:65], v[90:93], v[70:73], v[50:65]
	v_max3_f32 v253, v230, v246, v231
	v_max3_f32 v0, v0, v235, v220
	v_max3_f32 v251, v251, v239, v224
	ds_read_b64_tr_b16 v[82:83], v250 offset:34880
	ds_read_b64_tr_b16 v[84:85], v250 offset:37440
	ds_read_b64_tr_b16 v[86:87], v250 offset:40000
	ds_read_b64_tr_b16 v[88:89], v250 offset:42560
	ds_read_b64_tr_b16 v[90:91], v250 offset:45120
	ds_read_b64_tr_b16 v[92:93], v250 offset:47680
	ds_read_b64_tr_b16 v[198:199], v250 offset:50240
	ds_read_b64_tr_b16 v[200:201], v250 offset:52800
	s_waitcnt lgkmcnt(8)
	v_mfma_f32_32x32x16_bf16 v[50:65], v[94:97], v[78:81], v[50:65]
	v_max3_f32 v252, v252, v243, v228
	v_max3_f32 v253, v253, v247, v232
	v_max3_f32 v0, v0, v236, v221
	s_waitcnt lgkmcnt(6)
	v_mfma_f32_32x32x16_bf16 v[34:49], v[82:85], v[66:69], v[34:49]
	v_max3_f32 v251, v251, v240, v225
	v_max3_f32 v252, v252, v244, v229
	v_max3_f32 v253, v253, v248, v233
	s_waitcnt lgkmcnt(4)
	v_mfma_f32_32x32x16_bf16 v[34:49], v[86:89], v[74:77], v[34:49]
	v_max_f32_e32 v0, v0, v237
	v_max_f32_e32 v251, v251, v241
	v_max_f32_e32 v252, v252, v245
	s_waitcnt lgkmcnt(2)
	v_mfma_f32_32x32x16_bf16 v[34:49], v[90:93], v[70:73], v[34:49]
	v_max_f32_e32 v253, v253, v249
	v_max3_f32 v0, v0, v251, v252
	v_max_f32_e32 v0, v0, v253
	ds_read_b64_tr_b16 v[82:83], v250 offset:34944
	ds_read_b64_tr_b16 v[84:85], v250 offset:37504
	ds_read_b64_tr_b16 v[86:87], v250 offset:40064
	ds_read_b64_tr_b16 v[88:89], v250 offset:42624
	ds_read_b64_tr_b16 v[90:91], v250 offset:45184
	ds_read_b64_tr_b16 v[92:93], v250 offset:47744
	ds_read_b64_tr_b16 v[94:95], v250 offset:50304
	ds_read_b64_tr_b16 v[96:97], v250 offset:52864
	s_waitcnt lgkmcnt(8)
	v_mfma_f32_32x32x16_bf16 v[34:49], v[198:201], v[78:81], v[34:49]
	s_nop 0
	v_mov_b32_e32 v251, v0
	v_nop
	s_waitcnt lgkmcnt(6)
	v_mfma_f32_32x32x16_bf16 v[18:33], v[82:85], v[66:69], v[18:33]
	v_nop
	v_permlane32_swap_b32 v0, v251
	s_nop 0
	s_waitcnt lgkmcnt(4)
	v_mfma_f32_32x32x16_bf16 v[18:33], v[86:89], v[74:77], v[18:33]
	v_max_f32_e32 v251, v251, v251
	v_max_f32_e32 v0, v0, v0
	v_max_f32_e32 v0, v0, v251
	s_waitcnt lgkmcnt(2)
	v_mfma_f32_32x32x16_bf16 v[18:33], v[90:93], v[70:73], v[18:33]
	v_add_f32_e32 v251, 0x42800000, v197
	v_cmp_gt_f32_e32 vcc, v0, v251
	ds_read_b64_tr_b16 v[82:83], v250 offset:35008
	ds_read_b64_tr_b16 v[84:85], v250 offset:37568
	ds_read_b64_tr_b16 v[86:87], v250 offset:40128
	ds_read_b64_tr_b16 v[88:89], v250 offset:42688
	ds_read_b64_tr_b16 v[90:91], v250 offset:45248
	ds_read_b64_tr_b16 v[92:93], v250 offset:47808
	ds_read_b64_tr_b16 v[198:199], v250 offset:50368
	ds_read_b64_tr_b16 v[200:201], v250 offset:52928
	s_waitcnt lgkmcnt(8)
	v_mfma_f32_32x32x16_bf16 v[18:33], v[94:97], v[78:81], v[18:33]
	s_waitcnt lgkmcnt(6)
	v_mfma_f32_32x32x16_bf16 v[2:17], v[82:85], v[66:69], v[2:17]
	s_waitcnt lgkmcnt(4)
	v_mfma_f32_32x32x16_bf16 v[2:17], v[86:89], v[74:77], v[2:17]
	s_waitcnt lgkmcnt(2)
	v_mfma_f32_32x32x16_bf16 v[2:17], v[90:93], v[70:73], v[2:17]
	s_waitcnt lgkmcnt(0)
	v_mfma_f32_32x32x16_bf16 v[2:17], v[198:201], v[78:81], v[2:17]
	s_branch .Lff1_copy
.Lff1_first:
	s_mul_i32 s34, s27, 0x4400
	v_add_u32_e32 v0, s34, v162
	ds_read_b128 v[198:201], v0
	ds_read_b128 v[202:205], v0 offset:32
	ds_read_b128 v[206:209], v0 offset:8704
	ds_read_b128 v[210:213], v0 offset:8736
	v_add_u32_e32 v246, s4, v149
	v_add_u32_e32 v234, 0x12800, v246
	v_add_u32_e32 v235, 0x12880, v246
	v_add_u32_e32 v238, 0x12820, v246
	v_add_u32_e32 v239, 0x128a0, v246
	v_add_u32_e32 v242, 0x12840, v246
	v_add_u32_e32 v243, 0x128c0, v246
	v_add_u32_e32 v247, 0x12860, v246
	v_add_u32_e32 v246, 0x128e0, v246
	ds_read_b128 v[218:221], v234
	ds_read_b128 v[234:237], v235
	ds_read_b128 v[222:225], v238
	ds_read_b128 v[238:241], v239
	ds_read_b128 v[226:229], v242
	ds_read_b128 v[242:245], v243
	ds_read_b128 v[230:233], v247
	ds_read_b128 v[246:249], v246
	s_waitcnt lgkmcnt(1)
	v_mfma_f32_32x32x16_bf16 v[218:233], v[198:201], v[98:101], v[218:233]
	s_waitcnt lgkmcnt(0)
	v_mfma_f32_32x32x16_bf16 v[234:249], v[206:209], v[98:101], v[234:249]
	v_mfma_f32_32x32x16_bf16 v[218:233], v[202:205], v[102:105], v[218:233]
	ds_read_b128 v[198:201], v0 offset:64
	ds_read_b128 v[202:205], v0 offset:96
	ds_read_b128 v[206:209], v0 offset:8768
	ds_read_b128 v[214:217], v0 offset:8800
	v_mfma_f32_32x32x16_bf16 v[234:249], v[210:213], v[102:105], v[234:249]
	s_waitcnt lgkmcnt(3)
	v_mfma_f32_32x32x16_bf16 v[218:233], v[198:201], v[106:109], v[218:233]
	s_waitcnt lgkmcnt(1)
	v_mfma_f32_32x32x16_bf16 v[234:249], v[206:209], v[106:109], v[234:249]
	v_mfma_f32_32x32x16_bf16 v[218:233], v[202:205], v[110:113], v[218:233]
	ds_read_b128 v[198:201], v0 offset:128
	ds_read_b128 v[202:205], v0 offset:160
	ds_read_b128 v[206:209], v0 offset:8832
	ds_read_b128 v[210:213], v0 offset:8864
	s_waitcnt lgkmcnt(4)
	v_mfma_f32_32x32x16_bf16 v[234:249], v[214:217], v[110:113], v[234:249]
	s_waitcnt lgkmcnt(3)
	v_mfma_f32_32x32x16_bf16 v[218:233], v[198:201], v[114:117], v[218:233]
	s_waitcnt lgkmcnt(1)
	v_mfma_f32_32x32x16_bf16 v[234:249], v[206:209], v[114:117], v[234:249]
	v_mfma_f32_32x32x16_bf16 v[218:233], v[202:205], v[118:121], v[218:233]
	ds_read_b128 v[198:201], v0 offset:192
	ds_read_b128 v[202:205], v0 offset:224
	ds_read_b128 v[206:209], v0 offset:8896
	ds_read_b128 v[214:217], v0 offset:8928
	s_waitcnt lgkmcnt(4)
	v_mfma_f32_32x32x16_bf16 v[234:249], v[210:213], v[118:121], v[234:249]
	s_waitcnt lgkmcnt(3)
	v_mfma_f32_32x32x16_bf16 v[218:233], v[198:201], v[122:125], v[218:233]
	s_waitcnt lgkmcnt(1)
	v_mfma_f32_32x32x16_bf16 v[234:249], v[206:209], v[122:125], v[234:249]
	v_mfma_f32_32x32x16_bf16 v[218:233], v[202:205], v[126:129], v[218:233]
	s_waitcnt lgkmcnt(0)
	v_mfma_f32_32x32x16_bf16 v[234:249], v[214:217], v[126:129], v[234:249]
	s_cmp_le_i32 s26, s5
	s_cbranch_scc1 .Lff1_m1
	v_cmp_le_i32_e32 vcc, v165, v195
	s_nop 8
	v_cndmask_b32_e32 v234, v155, v234, vcc
	v_cmp_lt_i32_e32 vcc, v163, v195
	s_nop 1
	v_cndmask_b32_e32 v219, v155, v219, vcc
	v_cmp_le_i32_e32 vcc, v163, v195
	s_nop 1
	v_cndmask_b32_e32 v218, v155, v218, vcc
	v_cmp_le_i32_e32 vcc, v166, v195
	s_nop 1
	v_cndmask_b32_e32 v235, v155, v235, vcc
	v_cmp_le_i32_e32 vcc, v167, v195
	s_nop 1
	v_cndmask_b32_e32 v220, v155, v220, vcc
	v_cmp_le_i32_e32 vcc, v168, v195
	s_nop 1
	v_cndmask_b32_e32 v236, v155, v236, vcc
	v_cmp_le_i32_e32 vcc, v169, v195
	s_nop 1
	v_cndmask_b32_e32 v221, v155, v221, vcc
	v_cmp_le_i32_e32 vcc, v170, v195
	s_nop 1
	v_cndmask_b32_e32 v237, v155, v237, vcc
	v_cmp_le_i32_e32 vcc, v171, v195
	s_nop 1
	v_cndmask_b32_e32 v222, v155, v222, vcc
	v_cmp_le_i32_e32 vcc, v172, v195
	s_nop 1
	v_cndmask_b32_e32 v238, v155, v238, vcc
	v_cmp_le_i32_e32 vcc, v173, v195
	s_nop 1
	v_cndmask_b32_e32 v223, v155, v223, vcc
	v_cmp_le_i32_e32 vcc, v174, v195
	s_nop 1
	v_cndmask_b32_e32 v239, v155, v239, vcc
	v_cmp_le_i32_e32 vcc, v175, v195
	s_nop 1
	v_cndmask_b32_e32 v224, v155, v224, vcc
	v_cmp_le_i32_e32 vcc, v176, v195
	s_nop 1
	v_cndmask_b32_e32 v240, v155, v240, vcc
	v_cmp_le_i32_e32 vcc, v177, v195
	s_nop 1
	v_cndmask_b32_e32 v225, v155, v225, vcc
	v_cmp_le_i32_e32 vcc, v178, v195
	s_nop 1
	v_cndmask_b32_e32 v241, v155, v241, vcc
	v_cmp_le_i32_e32 vcc, v179, v195
	s_nop 1
	v_cndmask_b32_e32 v226, v155, v226, vcc
	v_cmp_le_i32_e32 vcc, v180, v195
	s_nop 1
	v_cndmask_b32_e32 v242, v155, v242, vcc
	v_cmp_le_i32_e32 vcc, v181, v195
	s_nop 1
	v_cndmask_b32_e32 v227, v155, v227, vcc
	v_cmp_le_i32_e32 vcc, v182, v195
	s_nop 1
	v_cndmask_b32_e32 v243, v155, v243, vcc
	v_cmp_le_i32_e32 vcc, v183, v195
	s_nop 1
	v_cndmask_b32_e32 v228, v155, v228, vcc
	v_cmp_le_i32_e32 vcc, v184, v195
	s_nop 1
	v_cndmask_b32_e32 v244, v155, v244, vcc
	v_cmp_le_i32_e32 vcc, v185, v195
	s_nop 1
	v_cndmask_b32_e32 v229, v155, v229, vcc
	v_cmp_le_i32_e32 vcc, v186, v195
	s_nop 1
	v_cndmask_b32_e32 v245, v155, v245, vcc
	v_cmp_le_i32_e32 vcc, v187, v195
	s_nop 1
	v_cndmask_b32_e32 v230, v155, v230, vcc
	v_cmp_le_i32_e32 vcc, v188, v195
	s_nop 1
	v_cndmask_b32_e32 v246, v155, v246, vcc
	v_cmp_le_i32_e32 vcc, v189, v195
	s_nop 1
	v_cndmask_b32_e32 v231, v155, v231, vcc
	v_cmp_le_i32_e32 vcc, v190, v195
	s_nop 1
	v_cndmask_b32_e32 v247, v155, v247, vcc
	v_cmp_le_i32_e32 vcc, v191, v195
	s_nop 1
	v_cndmask_b32_e32 v232, v155, v232, vcc
	v_cmp_le_i32_e32 vcc, v192, v195
	s_nop 1
	v_cndmask_b32_e32 v248, v155, v248, vcc
	v_cmp_le_i32_e32 vcc, v193, v195
	s_nop 1
	v_cndmask_b32_e32 v233, v155, v233, vcc
	v_cmp_le_i32_e32 vcc, v194, v195
	s_nop 1
	v_cndmask_b32_e32 v249, v155, v249, vcc
.Lff1_m1:
	s_nop 11
	v_max3_f32 v0, v218, v234, v219
	v_max3_f32 v251, v222, v238, v223
	v_max3_f32 v252, v226, v242, v227
	v_max3_f32 v253, v230, v246, v231
	v_max3_f32 v0, v0, v235, v220
	v_max3_f32 v251, v251, v239, v224
	v_max3_f32 v252, v252, v243, v228
	v_max3_f32 v253, v253, v247, v232
	v_max3_f32 v0, v0, v236, v221
	v_max3_f32 v251, v251, v240, v225
	v_max3_f32 v252, v252, v244, v229
	v_max3_f32 v253, v253, v248, v233
	v_max_f32_e32 v0, v0, v237
	v_max_f32_e32 v251, v251, v241
	v_max_f32_e32 v252, v252, v245
	v_max_f32_e32 v253, v253, v249
	v_max3_f32 v0, v0, v251, v252
	v_max_f32_e32 v0, v0, v253
	s_nop 0
	v_mov_b32_e32 v251, v0
	v_nop
	v_nop
	v_permlane32_swap_b32 v0, v251
	s_nop 0
	v_max_f32_e32 v251, v251, v251
	v_max_f32_e32 v0, v0, v0
	v_max_f32_e32 v0, v0, v251
	v_add_f32_e32 v251, 0x42800000, v197
	v_cmp_gt_f32_e32 vcc, v0, v251
.Lff1_copy:
	v_mov_b32_e32 v82, v218
	v_mov_b32_e32 v83, v219
	v_mov_b32_e32 v84, v220
	v_mov_b32_e32 v85, v221
	v_mov_b32_e32 v86, v222
	v_mov_b32_e32 v87, v223
	v_mov_b32_e32 v88, v224
	v_mov_b32_e32 v89, v225
	v_mov_b32_e32 v90, v226
	v_mov_b32_e32 v91, v227
	v_mov_b32_e32 v92, v228
	v_mov_b32_e32 v93, v229
	v_mov_b32_e32 v94, v230
	v_mov_b32_e32 v95, v231
	v_mov_b32_e32 v96, v232
	v_mov_b32_e32 v97, v233
	v_mov_b32_e32 v66, v234
	v_mov_b32_e32 v67, v235
	v_mov_b32_e32 v68, v236
	v_mov_b32_e32 v69, v237
	v_mov_b32_e32 v70, v238
	v_mov_b32_e32 v71, v239
	v_mov_b32_e32 v72, v240
	v_mov_b32_e32 v73, v241
	v_mov_b32_e32 v74, v242
	v_mov_b32_e32 v75, v243
	v_mov_b32_e32 v76, v244
	v_mov_b32_e32 v77, v245
	v_mov_b32_e32 v78, v246
	v_mov_b32_e32 v79, v247
	v_mov_b32_e32 v80, v248
	v_mov_b32_e32 v81, v249
	s_cbranch_vccz .Lff1_norsc
	v_max_f32_e32 v0, v0, v0
	v_max_f32_e32 v251, v197, v197
	v_max_f32_e32 v251, v251, v0
	v_sub_f32_e32 v252, v197, v251
	v_exp_f32_e32 v252, v252
	v_mov_b32_e32 v197, v251
	s_nop 0
	v_mul_f32_e32 v196, v196, v252
	s_nop 1
	v_pk_mul_f32 v[64:65], v[64:65], v[252:253] op_sel_hi:[1,0]
	v_pk_mul_f32 v[62:63], v[62:63], v[252:253] op_sel_hi:[1,0]
	v_pk_mul_f32 v[60:61], v[60:61], v[252:253] op_sel_hi:[1,0]
	v_pk_mul_f32 v[58:59], v[58:59], v[252:253] op_sel_hi:[1,0]
	v_pk_mul_f32 v[56:57], v[56:57], v[252:253] op_sel_hi:[1,0]
	v_pk_mul_f32 v[54:55], v[54:55], v[252:253] op_sel_hi:[1,0]
	v_pk_mul_f32 v[52:53], v[52:53], v[252:253] op_sel_hi:[1,0]
	v_pk_mul_f32 v[50:51], v[50:51], v[252:253] op_sel_hi:[1,0]
	v_pk_mul_f32 v[48:49], v[48:49], v[252:253] op_sel_hi:[1,0]
	v_pk_mul_f32 v[46:47], v[46:47], v[252:253] op_sel_hi:[1,0]
	v_pk_mul_f32 v[44:45], v[44:45], v[252:253] op_sel_hi:[1,0]
	v_pk_mul_f32 v[42:43], v[42:43], v[252:253] op_sel_hi:[1,0]
	v_pk_mul_f32 v[40:41], v[40:41], v[252:253] op_sel_hi:[1,0]
	v_pk_mul_f32 v[38:39], v[38:39], v[252:253] op_sel_hi:[1,0]
	v_pk_mul_f32 v[36:37], v[36:37], v[252:253] op_sel_hi:[1,0]
	v_pk_mul_f32 v[34:35], v[34:35], v[252:253] op_sel_hi:[1,0]
	v_pk_mul_f32 v[32:33], v[32:33], v[252:253] op_sel_hi:[1,0]
	v_pk_mul_f32 v[30:31], v[30:31], v[252:253] op_sel_hi:[1,0]
	v_pk_mul_f32 v[28:29], v[28:29], v[252:253] op_sel_hi:[1,0]
	v_pk_mul_f32 v[26:27], v[26:27], v[252:253] op_sel_hi:[1,0]
	v_pk_mul_f32 v[24:25], v[24:25], v[252:253] op_sel_hi:[1,0]
	v_pk_mul_f32 v[22:23], v[22:23], v[252:253] op_sel_hi:[1,0]
	v_pk_mul_f32 v[20:21], v[20:21], v[252:253] op_sel_hi:[1,0]
	v_pk_mul_f32 v[18:19], v[18:19], v[252:253] op_sel_hi:[1,0]
	v_pk_mul_f32 v[16:17], v[16:17], v[252:253] op_sel_hi:[1,0]
	v_pk_mul_f32 v[14:15], v[14:15], v[252:253] op_sel_hi:[1,0]
	v_pk_mul_f32 v[12:13], v[12:13], v[252:253] op_sel_hi:[1,0]
	v_pk_mul_f32 v[10:11], v[10:11], v[252:253] op_sel_hi:[1,0]
	v_pk_mul_f32 v[8:9], v[8:9], v[252:253] op_sel_hi:[1,0]
	v_pk_mul_f32 v[6:7], v[6:7], v[252:253] op_sel_hi:[1,0]
	v_pk_mul_f32 v[4:5], v[4:5], v[252:253] op_sel_hi:[1,0]
	v_pk_mul_f32 v[2:3], v[2:3], v[252:253] op_sel_hi:[1,0]
.Lff1_norsc:
	s_mov_b32 s72, 1
	s_branch .Lff1_bar
.Lff1_inact:
	s_cmp_eq_u32 s72, 0
	s_cbranch_scc1 .Lff1_bar
	v_sub_f32_e32 v82, v82, v197
	v_sub_f32_e32 v83, v83, v197
	v_sub_f32_e32 v84, v84, v197
	v_sub_f32_e32 v85, v85, v197
	v_exp_f32_e32 v82, v82
	v_exp_f32_e32 v83, v83
	v_exp_f32_e32 v84, v84
	v_exp_f32_e32 v85, v85
	v_sub_f32_e32 v86, v86, v197
	v_sub_f32_e32 v87, v87, v197
	v_sub_f32_e32 v88, v88, v197
	v_sub_f32_e32 v89, v89, v197
	v_exp_f32_e32 v86, v86
	v_exp_f32_e32 v87, v87
	v_exp_f32_e32 v88, v88
	v_exp_f32_e32 v89, v89
	v_sub_f32_e32 v66, v66, v197
	v_sub_f32_e32 v67, v67, v197
	v_sub_f32_e32 v68, v68, v197
	v_sub_f32_e32 v69, v69, v197
	v_exp_f32_e32 v66, v66
	v_exp_f32_e32 v67, v67
	v_exp_f32_e32 v68, v68
	v_exp_f32_e32 v69, v69
	v_add_f32_e32 v250, v82, v86
	v_add_f32_e32 v251, v83, v87
	v_add_f32_e32 v252, v84, v88
	v_add_f32_e32 v253, v85, v89
	v_sub_f32_e32 v70, v70, v197
	v_sub_f32_e32 v71, v71, v197
	v_sub_f32_e32 v72, v72, v197
	v_sub_f32_e32 v73, v73, v197
	v_exp_f32_e32 v70, v70
	v_exp_f32_e32 v71, v71
	v_exp_f32_e32 v72, v72
	v_exp_f32_e32 v73, v73
	v_add_f32_e32 v250, v250, v66
	v_add_f32_e32 v251, v251, v67
	v_add_f32_e32 v252, v252, v68
	v_add_f32_e32 v253, v253, v69
	v_sub_f32_e32 v90, v90, v197
	v_sub_f32_e32 v91, v91, v197
	v_sub_f32_e32 v92, v92, v197
	v_sub_f32_e32 v93, v93, v197
	v_exp_f32_e32 v90, v90
	v_exp_f32_e32 v91, v91
	v_exp_f32_e32 v92, v92
	v_exp_f32_e32 v93, v93
	v_add_f32_e32 v250, v250, v70
	v_add_f32_e32 v251, v251, v71
	v_add_f32_e32 v252, v252, v72
	v_add_f32_e32 v253, v253, v73
	v_sub_f32_e32 v94, v94, v197
	v_sub_f32_e32 v95, v95, v197
	v_sub_f32_e32 v96, v96, v197
	v_sub_f32_e32 v97, v97, v197
	v_exp_f32_e32 v94, v94
	v_exp_f32_e32 v95, v95
	v_exp_f32_e32 v96, v96
	v_exp_f32_e32 v97, v97
	v_add_f32_e32 v250, v250, v90
	v_add_f32_e32 v251, v251, v91
	v_add_f32_e32 v252, v252, v92
	v_add_f32_e32 v253, v253, v93
	v_sub_f32_e32 v74, v74, v197
	v_sub_f32_e32 v75, v75, v197
	v_sub_f32_e32 v76, v76, v197
	v_sub_f32_e32 v77, v77, v197
	v_exp_f32_e32 v74, v74
	v_exp_f32_e32 v75, v75
	v_exp_f32_e32 v76, v76
	v_exp_f32_e32 v77, v77
	v_add_f32_e32 v250, v250, v94
	v_add_f32_e32 v251, v251, v95
	v_add_f32_e32 v252, v252, v96
	v_add_f32_e32 v253, v253, v97
	v_sub_f32_e32 v78, v78, v197
	v_sub_f32_e32 v79, v79, v197
	v_sub_f32_e32 v80, v80, v197
	v_sub_f32_e32 v81, v81, v197
	v_exp_f32_e32 v78, v78
	v_exp_f32_e32 v79, v79
	v_exp_f32_e32 v80, v80
	v_exp_f32_e32 v81, v81
	v_add_f32_e32 v250, v250, v74
	v_add_f32_e32 v251, v251, v75
	v_add_f32_e32 v252, v252, v76
	v_add_f32_e32 v253, v253, v77
	v_add_f32_e32 v250, v250, v78
	v_add_f32_e32 v251, v251, v79
	v_add_f32_e32 v252, v252, v80
	v_add_f32_e32 v253, v253, v81
	v_add_f32_e32 v250, v250, v251
	v_add_f32_e32 v252, v252, v253
	v_add_f32_e32 v250, v250, v252
	v_add_f32_e32 v196, v196, v250
	v_cvt_pk_bf16_f32 v73, v72, v73
	v_cvt_pk_bf16_f32 v72, v70, v71
	v_cvt_pk_bf16_f32 v71, v68, v69
	v_cvt_pk_bf16_f32 v70, v66, v67
	v_cvt_pk_bf16_f32 v66, v82, v83
	v_cvt_pk_bf16_f32 v67, v84, v85
	v_cvt_pk_bf16_f32 v68, v86, v87
	v_cvt_pk_bf16_f32 v69, v88, v89
	v_cvt_pk_bf16_f32 v81, v80, v81
	v_cvt_pk_bf16_f32 v80, v78, v79
	v_cvt_pk_bf16_f32 v79, v76, v77
	v_cvt_pk_bf16_f32 v78, v74, v75
	v_cvt_pk_bf16_f32 v74, v90, v91
	v_cvt_pk_bf16_f32 v75, v92, v93
	v_cvt_pk_bf16_f32 v76, v94, v95
	v_cvt_pk_bf16_f32 v77, v96, v97
	v_add_u32_e32 v250, s70, v164
	ds_read_b64_tr_b16 v[82:83], v250 offset:34816
	ds_read_b64_tr_b16 v[84:85], v250 offset:37376
	ds_read_b64_tr_b16 v[86:87], v250 offset:39936
	ds_read_b64_tr_b16 v[88:89], v250 offset:42496
	ds_read_b64_tr_b16 v[90:91], v250 offset:45056
	ds_read_b64_tr_b16 v[92:93], v250 offset:47616
	ds_read_b64_tr_b16 v[94:95], v250 offset:50176
	ds_read_b64_tr_b16 v[96:97], v250 offset:52736
	s_waitcnt lgkmcnt(6)
	v_mfma_f32_32x32x16_bf16 v[50:65], v[82:85], v[66:69], v[50:65]
	s_waitcnt lgkmcnt(4)
	v_mfma_f32_32x32x16_bf16 v[50:65], v[86:89], v[74:77], v[50:65]
	s_waitcnt lgkmcnt(2)
	v_mfma_f32_32x32x16_bf16 v[50:65], v[90:93], v[70:73], v[50:65]
	ds_read_b64_tr_b16 v[82:83], v250 offset:34880
	ds_read_b64_tr_b16 v[84:85], v250 offset:37440
	ds_read_b64_tr_b16 v[86:87], v250 offset:40000
	ds_read_b64_tr_b16 v[88:89], v250 offset:42560
	ds_read_b64_tr_b16 v[90:91], v250 offset:45120
	ds_read_b64_tr_b16 v[92:93], v250 offset:47680
	ds_read_b64_tr_b16 v[198:199], v250 offset:50240
	ds_read_b64_tr_b16 v[200:201], v250 offset:52800
	s_waitcnt lgkmcnt(8)
	v_mfma_f32_32x32x16_bf16 v[50:65], v[94:97], v[78:81], v[50:65]
	s_waitcnt lgkmcnt(6)
	v_mfma_f32_32x32x16_bf16 v[34:49], v[82:85], v[66:69], v[34:49]
	s_waitcnt lgkmcnt(4)
	v_mfma_f32_32x32x16_bf16 v[34:49], v[86:89], v[74:77], v[34:49]
	s_waitcnt lgkmcnt(2)
	v_mfma_f32_32x32x16_bf16 v[34:49], v[90:93], v[70:73], v[34:49]
	ds_read_b64_tr_b16 v[82:83], v250 offset:34944
	ds_read_b64_tr_b16 v[84:85], v250 offset:37504
	ds_read_b64_tr_b16 v[86:87], v250 offset:40064
	ds_read_b64_tr_b16 v[88:89], v250 offset:42624
	ds_read_b64_tr_b16 v[90:91], v250 offset:45184
	ds_read_b64_tr_b16 v[92:93], v250 offset:47744
	ds_read_b64_tr_b16 v[94:95], v250 offset:50304
	ds_read_b64_tr_b16 v[96:97], v250 offset:52864
	s_waitcnt lgkmcnt(8)
	v_mfma_f32_32x32x16_bf16 v[34:49], v[198:201], v[78:81], v[34:49]
	s_waitcnt lgkmcnt(6)
	v_mfma_f32_32x32x16_bf16 v[18:33], v[82:85], v[66:69], v[18:33]
	s_waitcnt lgkmcnt(4)
	v_mfma_f32_32x32x16_bf16 v[18:33], v[86:89], v[74:77], v[18:33]
	s_waitcnt lgkmcnt(2)
	v_mfma_f32_32x32x16_bf16 v[18:33], v[90:93], v[70:73], v[18:33]
	ds_read_b64_tr_b16 v[82:83], v250 offset:35008
	ds_read_b64_tr_b16 v[84:85], v250 offset:37568
	ds_read_b64_tr_b16 v[86:87], v250 offset:40128
	ds_read_b64_tr_b16 v[88:89], v250 offset:42688
	ds_read_b64_tr_b16 v[90:91], v250 offset:45248
	ds_read_b64_tr_b16 v[92:93], v250 offset:47808
	ds_read_b64_tr_b16 v[198:199], v250 offset:50368
	ds_read_b64_tr_b16 v[200:201], v250 offset:52928
	s_waitcnt lgkmcnt(8)
	v_mfma_f32_32x32x16_bf16 v[18:33], v[94:97], v[78:81], v[18:33]
	s_waitcnt lgkmcnt(6)
	v_mfma_f32_32x32x16_bf16 v[2:17], v[82:85], v[66:69], v[2:17]
	s_waitcnt lgkmcnt(4)
	v_mfma_f32_32x32x16_bf16 v[2:17], v[86:89], v[74:77], v[2:17]
	s_waitcnt lgkmcnt(2)
	v_mfma_f32_32x32x16_bf16 v[2:17], v[90:93], v[70:73], v[2:17]
	s_waitcnt lgkmcnt(0)
	v_mfma_f32_32x32x16_bf16 v[2:17], v[198:201], v[78:81], v[2:17]
	s_mov_b32 s72, 0
.Lff1_bar:
	s_waitcnt lgkmcnt(0)
	s_barrier
	s_mov_b32 s71, s70
	s_mov_b32 s70, s69
	s_mov_b32 s69, s68
	s_mov_b32 s68, s71
	s_addk_i32 s4, 0x100
	s_add_i32 s26, s26, 64
	s_add_i32 s0, s0, 1
	s_cmp_lg_u32 s7, s4
	v_subrev_u32_e32 v195, 64, v195
	s_cbranch_scc0 .Lff1_exit
	s_branch .LBB0_649
.Lff1_exit:
	s_cmp_eq_u32 s72, 0
	s_cbranch_scc1 .Lff1_done
	v_sub_f32_e32 v82, v82, v197
	v_sub_f32_e32 v83, v83, v197
	v_sub_f32_e32 v84, v84, v197
	v_sub_f32_e32 v85, v85, v197
	v_exp_f32_e32 v82, v82
	v_exp_f32_e32 v83, v83
	v_exp_f32_e32 v84, v84
	v_exp_f32_e32 v85, v85
	v_sub_f32_e32 v86, v86, v197
	v_sub_f32_e32 v87, v87, v197
	v_sub_f32_e32 v88, v88, v197
	v_sub_f32_e32 v89, v89, v197
	v_exp_f32_e32 v86, v86
	v_exp_f32_e32 v87, v87
	v_exp_f32_e32 v88, v88
	v_exp_f32_e32 v89, v89
	v_sub_f32_e32 v66, v66, v197
	v_sub_f32_e32 v67, v67, v197
	v_sub_f32_e32 v68, v68, v197
	v_sub_f32_e32 v69, v69, v197
	v_exp_f32_e32 v66, v66
	v_exp_f32_e32 v67, v67
	v_exp_f32_e32 v68, v68
	v_exp_f32_e32 v69, v69
	v_add_f32_e32 v250, v82, v86
	v_add_f32_e32 v251, v83, v87
	v_add_f32_e32 v252, v84, v88
	v_add_f32_e32 v253, v85, v89
	v_sub_f32_e32 v70, v70, v197
	v_sub_f32_e32 v71, v71, v197
	v_sub_f32_e32 v72, v72, v197
	v_sub_f32_e32 v73, v73, v197
	v_exp_f32_e32 v70, v70
	v_exp_f32_e32 v71, v71
	v_exp_f32_e32 v72, v72
	v_exp_f32_e32 v73, v73
	v_add_f32_e32 v250, v250, v66
	v_add_f32_e32 v251, v251, v67
	v_add_f32_e32 v252, v252, v68
	v_add_f32_e32 v253, v253, v69
	v_sub_f32_e32 v90, v90, v197
	v_sub_f32_e32 v91, v91, v197
	v_sub_f32_e32 v92, v92, v197
	v_sub_f32_e32 v93, v93, v197
	v_exp_f32_e32 v90, v90
	v_exp_f32_e32 v91, v91
	v_exp_f32_e32 v92, v92
	v_exp_f32_e32 v93, v93
	v_add_f32_e32 v250, v250, v70
	v_add_f32_e32 v251, v251, v71
	v_add_f32_e32 v252, v252, v72
	v_add_f32_e32 v253, v253, v73
	v_sub_f32_e32 v94, v94, v197
	v_sub_f32_e32 v95, v95, v197
	v_sub_f32_e32 v96, v96, v197
	v_sub_f32_e32 v97, v97, v197
	v_exp_f32_e32 v94, v94
	v_exp_f32_e32 v95, v95
	v_exp_f32_e32 v96, v96
	v_exp_f32_e32 v97, v97
	v_add_f32_e32 v250, v250, v90
	v_add_f32_e32 v251, v251, v91
	v_add_f32_e32 v252, v252, v92
	v_add_f32_e32 v253, v253, v93
	v_sub_f32_e32 v74, v74, v197
	v_sub_f32_e32 v75, v75, v197
	v_sub_f32_e32 v76, v76, v197
	v_sub_f32_e32 v77, v77, v197
	v_exp_f32_e32 v74, v74
	v_exp_f32_e32 v75, v75
	v_exp_f32_e32 v76, v76
	v_exp_f32_e32 v77, v77
	v_add_f32_e32 v250, v250, v94
	v_add_f32_e32 v251, v251, v95
	v_add_f32_e32 v252, v252, v96
	v_add_f32_e32 v253, v253, v97
	v_sub_f32_e32 v78, v78, v197
	v_sub_f32_e32 v79, v79, v197
	v_sub_f32_e32 v80, v80, v197
	v_sub_f32_e32 v81, v81, v197
	v_exp_f32_e32 v78, v78
	v_exp_f32_e32 v79, v79
	v_exp_f32_e32 v80, v80
	v_exp_f32_e32 v81, v81
	v_add_f32_e32 v250, v250, v74
	v_add_f32_e32 v251, v251, v75
	v_add_f32_e32 v252, v252, v76
	v_add_f32_e32 v253, v253, v77
	v_add_f32_e32 v250, v250, v78
	v_add_f32_e32 v251, v251, v79
	v_add_f32_e32 v252, v252, v80
	v_add_f32_e32 v253, v253, v81
	v_add_f32_e32 v250, v250, v251
	v_add_f32_e32 v252, v252, v253
	v_add_f32_e32 v250, v250, v252
	v_add_f32_e32 v196, v196, v250
	v_cvt_pk_bf16_f32 v73, v72, v73
	v_cvt_pk_bf16_f32 v72, v70, v71
	v_cvt_pk_bf16_f32 v71, v68, v69
	v_cvt_pk_bf16_f32 v70, v66, v67
	v_cvt_pk_bf16_f32 v66, v82, v83
	v_cvt_pk_bf16_f32 v67, v84, v85
	v_cvt_pk_bf16_f32 v68, v86, v87
	v_cvt_pk_bf16_f32 v69, v88, v89
	v_cvt_pk_bf16_f32 v81, v80, v81
	v_cvt_pk_bf16_f32 v80, v78, v79
	v_cvt_pk_bf16_f32 v79, v76, v77
	v_cvt_pk_bf16_f32 v78, v74, v75
	v_cvt_pk_bf16_f32 v74, v90, v91
	v_cvt_pk_bf16_f32 v75, v92, v93
	v_cvt_pk_bf16_f32 v76, v94, v95
	v_cvt_pk_bf16_f32 v77, v96, v97
	v_add_u32_e32 v250, s70, v164
	ds_read_b64_tr_b16 v[82:83], v250 offset:34816
	ds_read_b64_tr_b16 v[84:85], v250 offset:37376
	ds_read_b64_tr_b16 v[86:87], v250 offset:39936
	ds_read_b64_tr_b16 v[88:89], v250 offset:42496
	ds_read_b64_tr_b16 v[90:91], v250 offset:45056
	ds_read_b64_tr_b16 v[92:93], v250 offset:47616
	ds_read_b64_tr_b16 v[94:95], v250 offset:50176
	ds_read_b64_tr_b16 v[96:97], v250 offset:52736
	s_waitcnt lgkmcnt(6)
	v_mfma_f32_32x32x16_bf16 v[50:65], v[82:85], v[66:69], v[50:65]
	s_waitcnt lgkmcnt(4)
	v_mfma_f32_32x32x16_bf16 v[50:65], v[86:89], v[74:77], v[50:65]
	s_waitcnt lgkmcnt(2)
	v_mfma_f32_32x32x16_bf16 v[50:65], v[90:93], v[70:73], v[50:65]
	ds_read_b64_tr_b16 v[82:83], v250 offset:34880
	ds_read_b64_tr_b16 v[84:85], v250 offset:37440
	ds_read_b64_tr_b16 v[86:87], v250 offset:40000
	ds_read_b64_tr_b16 v[88:89], v250 offset:42560
	ds_read_b64_tr_b16 v[90:91], v250 offset:45120
	ds_read_b64_tr_b16 v[92:93], v250 offset:47680
	ds_read_b64_tr_b16 v[198:199], v250 offset:50240
	ds_read_b64_tr_b16 v[200:201], v250 offset:52800
	s_waitcnt lgkmcnt(8)
	v_mfma_f32_32x32x16_bf16 v[50:65], v[94:97], v[78:81], v[50:65]
	s_waitcnt lgkmcnt(6)
	v_mfma_f32_32x32x16_bf16 v[34:49], v[82:85], v[66:69], v[34:49]
	s_waitcnt lgkmcnt(4)
	v_mfma_f32_32x32x16_bf16 v[34:49], v[86:89], v[74:77], v[34:49]
	s_waitcnt lgkmcnt(2)
	v_mfma_f32_32x32x16_bf16 v[34:49], v[90:93], v[70:73], v[34:49]
	ds_read_b64_tr_b16 v[82:83], v250 offset:34944
	ds_read_b64_tr_b16 v[84:85], v250 offset:37504
	ds_read_b64_tr_b16 v[86:87], v250 offset:40064
	ds_read_b64_tr_b16 v[88:89], v250 offset:42624
	ds_read_b64_tr_b16 v[90:91], v250 offset:45184
	ds_read_b64_tr_b16 v[92:93], v250 offset:47744
	ds_read_b64_tr_b16 v[94:95], v250 offset:50304
	ds_read_b64_tr_b16 v[96:97], v250 offset:52864
	s_waitcnt lgkmcnt(8)
	v_mfma_f32_32x32x16_bf16 v[34:49], v[198:201], v[78:81], v[34:49]
	s_waitcnt lgkmcnt(6)
	v_mfma_f32_32x32x16_bf16 v[18:33], v[82:85], v[66:69], v[18:33]
	s_waitcnt lgkmcnt(4)
	v_mfma_f32_32x32x16_bf16 v[18:33], v[86:89], v[74:77], v[18:33]
	s_waitcnt lgkmcnt(2)
	v_mfma_f32_32x32x16_bf16 v[18:33], v[90:93], v[70:73], v[18:33]
	ds_read_b64_tr_b16 v[82:83], v250 offset:35008
	ds_read_b64_tr_b16 v[84:85], v250 offset:37568
	ds_read_b64_tr_b16 v[86:87], v250 offset:40128
	ds_read_b64_tr_b16 v[88:89], v250 offset:42688
	ds_read_b64_tr_b16 v[90:91], v250 offset:45248
	ds_read_b64_tr_b16 v[92:93], v250 offset:47808
	ds_read_b64_tr_b16 v[198:199], v250 offset:50368
	ds_read_b64_tr_b16 v[200:201], v250 offset:52928
	s_waitcnt lgkmcnt(8)
	v_mfma_f32_32x32x16_bf16 v[18:33], v[94:97], v[78:81], v[18:33]
	s_waitcnt lgkmcnt(6)
	v_mfma_f32_32x32x16_bf16 v[2:17], v[82:85], v[66:69], v[2:17]
	s_waitcnt lgkmcnt(4)
	v_mfma_f32_32x32x16_bf16 v[2:17], v[86:89], v[74:77], v[2:17]
	s_waitcnt lgkmcnt(2)
	v_mfma_f32_32x32x16_bf16 v[2:17], v[90:93], v[70:73], v[2:17]
	s_waitcnt lgkmcnt(0)
	v_mfma_f32_32x32x16_bf16 v[2:17], v[198:201], v[78:81], v[2:17]
.Lff1_done:
	s_waitcnt lgkmcnt(0)
	s_barrier
	s_branch .LBB0_654
.LBB0_654:
	v_mov_b32_e32 v0, v196
	v_nop
	v_nop
	v_permlane32_swap_b32 v196, v0
	s_lshl_b32 s16, s16, 1
	v_add_f32_e32 v146, v196, v0
	v_ashrrev_i32_e32 v0, 31, v156
	v_lshrrev_b32_e32 v0, 28, v0
	v_add_u32_e32 v0, v156, v0
	s_waitcnt vmcnt(0)
	v_ashrrev_i32_e32 v144, 4, v0
	v_and_b32_e32 v0, -16, v0
	v_sub_u32_e32 v147, v156, v0
	v_lshlrev_b32_e32 v68, 3, v147
	v_ashrrev_i32_e32 v69, 31, v68
	v_add_u32_e32 v0, 64, v156
	v_lshlrev_b64 v[140:141], 1, v[68:69]
	v_ashrrev_i32_e32 v68, 31, v0
	v_lshrrev_b32_e32 v68, 28, v68
	v_ashrrev_i32_e32 v145, 31, v144
	v_add_u32_e32 v68, v0, v68
	v_lshl_add_u64 v[138:139], s[24:25], 0, v[144:145]
	v_ashrrev_i32_e32 v142, 4, v68
	v_lshlrev_b64 v[66:67], 14, v[138:139]
	v_and_b32_e32 v68, -16, v68
	v_ashrrev_i32_e32 v143, 31, v142
	v_lshl_add_u64 v[66:67], s[12:13], 0, v[66:67]
	v_sub_u32_e32 v145, v0, v68
	v_lshl_add_u64 v[132:133], s[24:25], 0, v[142:143]
	v_lshl_add_u64 v[66:67], v[66:67], 0, s[16:17]
	v_lshlrev_b64 v[68:69], 14, v[132:133]
	v_lshlrev_b32_e32 v70, 3, v145
	v_lshl_add_u64 v[66:67], v[66:67], 0, v[140:141]
	v_lshl_add_u64 v[68:69], s[12:13], 0, v[68:69]
	v_ashrrev_i32_e32 v71, 31, v70
	v_add_co_u32_e32 v66, vcc, s48, v66
	v_lshl_add_u64 v[68:69], v[68:69], 0, s[16:17]
	v_lshlrev_b64 v[134:135], 1, v[70:71]
	v_addc_co_u32_e32 v67, vcc, 0, v67, vcc
	v_lshl_add_u64 v[68:69], v[68:69], 0, v[134:135]
	v_add_co_u32_e32 v68, vcc, s48, v68
	v_add_u32_e32 v0, 0x80, v156
	s_nop 0
	v_addc_co_u32_e32 v69, vcc, 0, v69, vcc
	global_load_dwordx4 v[94:97], v[66:67], off
	global_load_dwordx4 v[90:93], v[68:69], off
	v_ashrrev_i32_e32 v66, 31, v0
	v_lshrrev_b32_e32 v66, 28, v66
	v_add_u32_e32 v66, v0, v66
	v_ashrrev_i32_e32 v136, 4, v66
	v_and_b32_e32 v66, -16, v66
	v_sub_u32_e32 v143, v0, v66
	v_lshlrev_b32_e32 v68, 3, v143
	v_ashrrev_i32_e32 v69, 31, v68
	v_add_u32_e32 v0, 0xc0, v156
	v_lshlrev_b64 v[128:129], 1, v[68:69]
	v_ashrrev_i32_e32 v68, 31, v0
	v_lshrrev_b32_e32 v68, 28, v68
	v_ashrrev_i32_e32 v137, 31, v136
	v_add_u32_e32 v68, v0, v68
	v_lshl_add_u64 v[126:127], s[24:25], 0, v[136:137]
	v_ashrrev_i32_e32 v130, 4, v68
	v_lshlrev_b64 v[66:67], 14, v[126:127]
	v_and_b32_e32 v68, -16, v68
	v_ashrrev_i32_e32 v131, 31, v130
	v_lshl_add_u64 v[66:67], s[12:13], 0, v[66:67]
	v_sub_u32_e32 v137, v0, v68
	v_lshl_add_u64 v[120:121], s[24:25], 0, v[130:131]
	v_lshl_add_u64 v[66:67], v[66:67], 0, s[16:17]
	v_lshlrev_b64 v[68:69], 14, v[120:121]
	v_lshlrev_b32_e32 v70, 3, v137
	v_lshl_add_u64 v[66:67], v[66:67], 0, v[128:129]
	v_lshl_add_u64 v[68:69], s[12:13], 0, v[68:69]
	v_ashrrev_i32_e32 v71, 31, v70
	v_add_co_u32_e32 v66, vcc, s48, v66
	v_lshl_add_u64 v[68:69], v[68:69], 0, s[16:17]
	v_lshlrev_b64 v[122:123], 1, v[70:71]
	v_addc_co_u32_e32 v67, vcc, 0, v67, vcc
	v_lshl_add_u64 v[68:69], v[68:69], 0, v[122:123]
	v_add_co_u32_e32 v68, vcc, s48, v68
	v_add_u32_e32 v0, 0x100, v156
	s_nop 0
	v_addc_co_u32_e32 v69, vcc, 0, v69, vcc
	global_load_dwordx4 v[86:89], v[66:67], off
	global_load_dwordx4 v[82:85], v[68:69], off
	v_ashrrev_i32_e32 v66, 31, v0
	v_lshrrev_b32_e32 v66, 28, v66
	v_add_u32_e32 v66, v0, v66
	v_ashrrev_i32_e32 v124, 4, v66
	v_and_b32_e32 v66, -16, v66
	v_sub_u32_e32 v131, v0, v66
	v_lshlrev_b32_e32 v68, 3, v131
	v_ashrrev_i32_e32 v69, 31, v68
	v_add_u32_e32 v0, 0x140, v156
	v_lshlrev_b64 v[116:117], 1, v[68:69]
	v_ashrrev_i32_e32 v68, 31, v0
	v_lshrrev_b32_e32 v68, 28, v68
	v_ashrrev_i32_e32 v125, 31, v124
	v_add_u32_e32 v68, v0, v68
	v_lshl_add_u64 v[114:115], s[24:25], 0, v[124:125]
	v_ashrrev_i32_e32 v118, 4, v68
	v_lshlrev_b64 v[66:67], 14, v[114:115]
	v_and_b32_e32 v68, -16, v68
	v_ashrrev_i32_e32 v119, 31, v118
	v_lshl_add_u64 v[66:67], s[12:13], 0, v[66:67]
	v_sub_u32_e32 v125, v0, v68
	v_lshl_add_u64 v[108:109], s[24:25], 0, v[118:119]
	v_lshl_add_u64 v[66:67], v[66:67], 0, s[16:17]
	v_lshlrev_b64 v[68:69], 14, v[108:109]
	v_lshlrev_b32_e32 v70, 3, v125
	v_lshl_add_u64 v[66:67], v[66:67], 0, v[116:117]
	v_lshl_add_u64 v[68:69], s[12:13], 0, v[68:69]
	v_ashrrev_i32_e32 v71, 31, v70
	v_add_co_u32_e32 v66, vcc, s48, v66
	v_lshl_add_u64 v[68:69], v[68:69], 0, s[16:17]
	v_lshlrev_b64 v[110:111], 1, v[70:71]
	v_addc_co_u32_e32 v67, vcc, 0, v67, vcc
	v_lshl_add_u64 v[68:69], v[68:69], 0, v[110:111]
	v_add_co_u32_e32 v68, vcc, s48, v68
	v_add_u32_e32 v0, 0x180, v156
	s_nop 0
	v_addc_co_u32_e32 v69, vcc, 0, v69, vcc
	global_load_dwordx4 v[78:81], v[66:67], off
	global_load_dwordx4 v[74:77], v[68:69], off
	v_ashrrev_i32_e32 v66, 31, v0
	v_lshrrev_b32_e32 v66, 28, v66
	v_add_u32_e32 v66, v0, v66
	v_ashrrev_i32_e32 v112, 4, v66
	v_and_b32_e32 v66, -16, v66
	v_sub_u32_e32 v119, v0, v66
	v_lshlrev_b32_e32 v68, 3, v119
	v_ashrrev_i32_e32 v69, 31, v68
	v_add_u32_e32 v0, 0x1c0, v156
	v_lshlrev_b64 v[104:105], 1, v[68:69]
	v_ashrrev_i32_e32 v68, 31, v0
	v_lshrrev_b32_e32 v68, 28, v68
	v_ashrrev_i32_e32 v113, 31, v112
	v_add_u32_e32 v68, v0, v68
	v_lshl_add_u64 v[102:103], s[24:25], 0, v[112:113]
	v_ashrrev_i32_e32 v106, 4, v68
	v_lshlrev_b64 v[66:67], 14, v[102:103]
	v_and_b32_e32 v68, -16, v68
	v_ashrrev_i32_e32 v107, 31, v106
	s_and_b32 s0, s49, 7
	v_lshl_add_u64 v[66:67], s[12:13], 0, v[66:67]
	v_sub_u32_e32 v0, v0, v68
	v_lshl_add_u64 v[98:99], s[24:25], 0, v[106:107]
	s_lshl_b32 s7, s0, 8
	s_lshl_b32 s6, s0, 10
	v_lshl_add_u64 v[66:67], v[66:67], 0, s[16:17]
	v_lshlrev_b64 v[68:69], 14, v[98:99]
	v_lshlrev_b32_e32 v70, 3, v0
	v_div_scale_f32 v107, s[0:1], v146, v146, 1.0
	v_lshl_add_u64 v[66:67], v[66:67], 0, v[104:105]
	v_lshl_add_u64 v[68:69], s[12:13], 0, v[68:69]
	v_ashrrev_i32_e32 v71, 31, v70
	v_rcp_f32_e32 v113, v107
	v_add_co_u32_e32 v66, vcc, s48, v66
	v_lshl_add_u64 v[68:69], v[68:69], 0, s[16:17]
	v_lshlrev_b64 v[100:101], 1, v[70:71]
	v_addc_co_u32_e32 v67, vcc, 0, v67, vcc
	v_lshl_add_u64 v[68:69], v[68:69], 0, v[100:101]
	v_add_co_u32_e32 v68, vcc, s48, v68
	v_fma_f32 v148, -v107, v113, 1.0
	s_nop 0
	v_addc_co_u32_e32 v69, vcc, 0, v69, vcc
	v_fmac_f32_e32 v113, v148, v113
	v_div_scale_f32 v148, vcc, 1.0, v146, 1.0
	v_mul_f32_e32 v149, v148, v113
	v_fma_f32 v150, -v107, v149, v148
	v_fmac_f32_e32 v149, v150, v113
	v_fma_f32 v107, -v107, v149, v148
	v_div_fmas_f32 v107, v107, v113, v149
	v_div_fixup_f32 v146, v107, v146, 1.0
	v_pk_mul_f32 v[50:51], v[50:51], v[146:147] op_sel_hi:[1,0]
	v_pk_mul_f32 v[52:53], v[52:53], v[146:147] op_sel_hi:[1,0]
	s_mulk_i32 s33, 0x110
	v_and_b32_e32 v107, 31, v156
	v_cvt_pk_bf16_f32 v50, v50, v51
	v_cvt_pk_bf16_f32 v51, v52, v53
	v_ashrrev_i32_e32 v52, 2, v156
	v_pk_mul_f32 v[2:3], v[2:3], v[146:147] op_sel_hi:[1,0]
	v_pk_mul_f32 v[4:5], v[4:5], v[146:147] op_sel_hi:[1,0]
	s_add_i32 s4, s33, 0
	v_mul_u32_u24_e32 v107, 0x110, v107
	v_and_b32_e32 v52, -8, v52
	v_cvt_pk_bf16_f32 v2, v2, v3
	v_cvt_pk_bf16_f32 v3, v4, v5
	v_pk_mul_f32 v[4:5], v[6:7], v[146:147] op_sel_hi:[1,0]
	v_pk_mul_f32 v[6:7], v[8:9], v[146:147] op_sel_hi:[1,0]
	v_add3_u32 v107, s4, v107, v52
	v_cvt_pk_bf16_f32 v4, v4, v5
	v_cvt_pk_bf16_f32 v5, v6, v7
	global_load_dwordx4 v[70:73], v[66:67], off
	s_nop 0
	global_load_dwordx4 v[66:69], v[68:69], off
	v_pk_mul_f32 v[34:35], v[34:35], v[146:147] op_sel_hi:[1,0]
	v_pk_mul_f32 v[36:37], v[36:37], v[146:147] op_sel_hi:[1,0]
	v_pk_mul_f32 v[18:19], v[18:19], v[146:147] op_sel_hi:[1,0]
	v_pk_mul_f32 v[20:21], v[20:21], v[146:147] op_sel_hi:[1,0]
	ds_write2_b64 v107, v[2:3], v[4:5] offset0:24 offset1:26
	v_pk_mul_f32 v[2:3], v[10:11], v[146:147] op_sel_hi:[1,0]
	v_pk_mul_f32 v[4:5], v[12:13], v[146:147] op_sel_hi:[1,0]
	v_pk_mul_f32 v[52:53], v[54:55], v[146:147] op_sel_hi:[1,0]
	v_pk_mul_f32 v[54:55], v[56:57], v[146:147] op_sel_hi:[1,0]
	v_cvt_pk_bf16_f32 v34, v34, v35
	v_cvt_pk_bf16_f32 v35, v36, v37
	v_pk_mul_f32 v[36:37], v[38:39], v[146:147] op_sel_hi:[1,0]
	v_pk_mul_f32 v[38:39], v[40:41], v[146:147] op_sel_hi:[1,0]
	v_cvt_pk_bf16_f32 v18, v18, v19
	v_cvt_pk_bf16_f32 v19, v20, v21
	v_pk_mul_f32 v[20:21], v[22:23], v[146:147] op_sel_hi:[1,0]
	v_pk_mul_f32 v[22:23], v[24:25], v[146:147] op_sel_hi:[1,0]
	v_cvt_pk_bf16_f32 v2, v2, v3
	v_cvt_pk_bf16_f32 v3, v4, v5
	v_pk_mul_f32 v[4:5], v[14:15], v[146:147] op_sel_hi:[1,0]
	v_pk_mul_f32 v[6:7], v[16:17], v[146:147] op_sel_hi:[1,0]
	v_cvt_pk_bf16_f32 v52, v52, v53
	v_cvt_pk_bf16_f32 v53, v54, v55
	v_cvt_pk_bf16_f32 v36, v36, v37
	v_cvt_pk_bf16_f32 v37, v38, v39
	v_cvt_pk_bf16_f32 v20, v20, v21
	v_cvt_pk_bf16_f32 v21, v22, v23
	v_cvt_pk_bf16_f32 v4, v4, v5
	v_cvt_pk_bf16_f32 v5, v6, v7
	ds_write2_b64 v107, v[50:51], v[52:53] offset1:2
	v_pk_mul_f32 v[50:51], v[58:59], v[146:147] op_sel_hi:[1,0]
	v_pk_mul_f32 v[52:53], v[60:61], v[146:147] op_sel_hi:[1,0]
	ds_write2_b64 v107, v[34:35], v[36:37] offset0:8 offset1:10
	v_pk_mul_f32 v[34:35], v[42:43], v[146:147] op_sel_hi:[1,0]
	v_pk_mul_f32 v[36:37], v[44:45], v[146:147] op_sel_hi:[1,0]
	ds_write2_b64 v107, v[18:19], v[20:21] offset0:16 offset1:18
	v_pk_mul_f32 v[18:19], v[26:27], v[146:147] op_sel_hi:[1,0]
	v_pk_mul_f32 v[20:21], v[28:29], v[146:147] op_sel_hi:[1,0]
	ds_write2_b64 v107, v[2:3], v[4:5] offset0:28 offset1:30
	v_mul_lo_u32 v2, v144, s45
	v_lshlrev_b32_e32 v3, 4, v147
	s_waitcnt vmcnt(7)
	v_lshlrev_b32_e32 v10, 16, v94
	v_cvt_pk_bf16_f32 v50, v50, v51
	v_cvt_pk_bf16_f32 v51, v52, v53
	v_pk_mul_f32 v[52:53], v[62:63], v[146:147] op_sel_hi:[1,0]
	v_pk_mul_f32 v[54:55], v[64:65], v[146:147] op_sel_hi:[1,0]
	v_cvt_pk_bf16_f32 v34, v34, v35
	v_cvt_pk_bf16_f32 v35, v36, v37
	v_pk_mul_f32 v[36:37], v[46:47], v[146:147] op_sel_hi:[1,0]
	v_pk_mul_f32 v[38:39], v[48:49], v[146:147] op_sel_hi:[1,0]
	v_cvt_pk_bf16_f32 v18, v18, v19
	v_cvt_pk_bf16_f32 v19, v20, v21
	v_pk_mul_f32 v[20:21], v[30:31], v[146:147] op_sel_hi:[1,0]
	v_pk_mul_f32 v[22:23], v[32:33], v[146:147] op_sel_hi:[1,0]
	v_add3_u32 v2, s4, v2, v3
	v_and_b32_e32 v13, 0xffff0000, v94
	v_mul_f32_e32 v3, 0xbfb8aa3b, v10
	v_cvt_pk_bf16_f32 v52, v52, v53
	v_cvt_pk_bf16_f32 v53, v54, v55
	v_cvt_pk_bf16_f32 v36, v36, v37
	v_cvt_pk_bf16_f32 v37, v38, v39
	v_cvt_pk_bf16_f32 v20, v20, v21
	v_cvt_pk_bf16_f32 v21, v22, v23
	v_exp_f32_e32 v6, v3
	v_mul_f32_e32 v3, 0xbfb8aa3b, v13
	ds_write2_b64 v107, v[50:51], v[52:53] offset0:4 offset1:6
	ds_write2_b64 v107, v[34:35], v[36:37] offset0:12 offset1:14
	ds_write2_b64 v107, v[18:19], v[20:21] offset0:20 offset1:22
	v_exp_f32_e32 v7, v3
	s_waitcnt lgkmcnt(0)
	ds_read_b128 v[2:5], v2
	v_add_f32_e32 v6, 1.0, v6
	v_rcp_f32_e32 v14, v6
	v_add_f32_e32 v6, 1.0, v7
	v_rcp_f32_e32 v15, v6
	v_mul_lo_u32 v6, v142, s45
	v_lshlrev_b32_e32 v7, 4, v145
	v_add3_u32 v6, s4, v6, v7
	ds_read_b128 v[6:9], v6
	s_waitcnt lgkmcnt(1)
	v_and_b32_e32 v11, 0xffff0000, v2
	v_lshlrev_b32_e32 v12, 16, v2
	v_pk_mul_f32 v[10:11], v[12:13], v[10:11]
	v_lshlrev_b32_e32 v12, 16, v95
	v_pk_mul_f32 v[10:11], v[14:15], v[10:11]
	v_and_b32_e32 v15, 0xffff0000, v95
	v_mul_f32_e32 v2, 0xbfb8aa3b, v12
	v_exp_f32_e32 v13, v2
	v_mul_f32_e32 v2, 0xbfb8aa3b, v15
	v_exp_f32_e32 v14, v2
	v_cvt_pk_bf16_f32 v2, v10, v11
	v_add_f32_e32 v10, 1.0, v13
	v_rcp_f32_e32 v10, v10
	v_add_f32_e32 v11, 1.0, v14
	v_rcp_f32_e32 v11, v11
	v_and_b32_e32 v13, 0xffff0000, v3
	v_lshlrev_b32_e32 v14, 16, v3
	v_pk_mul_f32 v[12:13], v[14:15], v[12:13]
	v_and_b32_e32 v15, 0xffff0000, v96
	v_pk_mul_f32 v[10:11], v[10:11], v[12:13]
	v_lshlrev_b32_e32 v12, 16, v96
	v_mul_f32_e32 v3, 0xbfb8aa3b, v12
	v_exp_f32_e32 v13, v3
	v_mul_f32_e32 v3, 0xbfb8aa3b, v15
	v_exp_f32_e32 v14, v3
	v_cvt_pk_bf16_f32 v3, v10, v11
	v_add_f32_e32 v10, 1.0, v13
	v_rcp_f32_e32 v10, v10
	v_add_f32_e32 v11, 1.0, v14
	v_rcp_f32_e32 v11, v11
	v_and_b32_e32 v13, 0xffff0000, v4
	v_lshlrev_b32_e32 v14, 16, v4
	v_pk_mul_f32 v[12:13], v[14:15], v[12:13]
	v_and_b32_e32 v15, 0xffff0000, v97
	v_pk_mul_f32 v[10:11], v[10:11], v[12:13]
	v_lshlrev_b32_e32 v12, 16, v97
	v_mul_f32_e32 v4, 0xbfb8aa3b, v12
	v_exp_f32_e32 v13, v4
	v_mul_f32_e32 v4, 0xbfb8aa3b, v15
	v_exp_f32_e32 v14, v4
	v_cvt_pk_bf16_f32 v4, v10, v11
	v_add_f32_e32 v10, 1.0, v13
	v_rcp_f32_e32 v10, v10
	v_add_f32_e32 v11, 1.0, v14
	v_rcp_f32_e32 v11, v11
	v_and_b32_e32 v13, 0xffff0000, v5
	v_lshlrev_b32_e32 v14, 16, v5
	v_pk_mul_f32 v[12:13], v[14:15], v[12:13]
	s_waitcnt vmcnt(6)
	v_and_b32_e32 v15, 0xffff0000, v90
	v_pk_mul_f32 v[10:11], v[10:11], v[12:13]
	v_lshlrev_b32_e32 v12, 16, v90
	s_addk_i32 s6, 0x400
	v_mul_f32_e32 v13, 0xbfb8aa3b, v12
	v_mul_f32_e32 v14, 0xbfb8aa3b, v15
	s_add_u32 s0, s36, s16
	v_exp_f32_e32 v13, v13
	v_exp_f32_e32 v14, v14
	s_addc_u32 s1, s37, 0
	v_cvt_pk_bf16_f32 v5, v10, v11
	v_lshlrev_b64 v[10:11], 12, v[138:139]
	v_lshl_add_u64 v[10:11], s[0:1], 0, v[10:11]
	v_lshl_add_u64 v[10:11], v[10:11], 0, v[140:141]
	global_store_dwordx4 v[10:11], v[2:5], off
	v_and_b32_e32 v11, 0xffff0000, v91
	s_waitcnt lgkmcnt(0)
	v_lshlrev_b32_e32 v10, 16, v7
	v_add_f32_e32 v2, 1.0, v13
	v_add_f32_e32 v3, 1.0, v14
	v_rcp_f32_e32 v2, v2
	v_rcp_f32_e32 v3, v3
	v_and_b32_e32 v13, 0xffff0000, v6
	v_lshlrev_b32_e32 v14, 16, v6
	v_pk_mul_f32 v[4:5], v[14:15], v[12:13]
	v_mul_f32_e32 v6, 0xbfb8aa3b, v11
	v_pk_mul_f32 v[2:3], v[2:3], v[4:5]
	v_lshlrev_b32_e32 v4, 16, v91
	v_mul_f32_e32 v5, 0xbfb8aa3b, v4
	v_exp_f32_e32 v5, v5
	v_exp_f32_e32 v6, v6
	v_cvt_pk_bf16_f32 v2, v2, v3
	v_lshlrev_b32_e32 v0, 4, v0
	v_add_f32_e32 v3, 1.0, v5
	v_rcp_f32_e32 v12, v3
	v_add_f32_e32 v3, 1.0, v6
	v_and_b32_e32 v5, 0xffff0000, v7
	v_lshlrev_b32_e32 v6, 16, v92
	v_rcp_f32_e32 v13, v3
	v_pk_mul_f32 v[4:5], v[10:11], v[4:5]
	v_and_b32_e32 v11, 0xffff0000, v92
	v_mul_f32_e32 v3, 0xbfb8aa3b, v6
	v_exp_f32_e32 v7, v3
	v_mul_f32_e32 v3, 0xbfb8aa3b, v11
	v_exp_f32_e32 v10, v3
	v_pk_mul_f32 v[4:5], v[12:13], v[4:5]
	v_mov_b32_e32 v28, v255
	v_cvt_pk_bf16_f32 v3, v4, v5
	v_add_f32_e32 v4, 1.0, v7
	v_add_f32_e32 v5, 1.0, v10
	v_rcp_f32_e32 v4, v4
	v_rcp_f32_e32 v5, v5
	v_and_b32_e32 v7, 0xffff0000, v8
	v_lshlrev_b32_e32 v10, 16, v8
	v_pk_mul_f32 v[6:7], v[10:11], v[6:7]
	v_and_b32_e32 v11, 0xffff0000, v93
	v_pk_mul_f32 v[4:5], v[4:5], v[6:7]
	v_lshlrev_b32_e32 v6, 16, v93
	v_mul_f32_e32 v7, 0xbfb8aa3b, v6
	v_exp_f32_e32 v7, v7
	v_mul_f32_e32 v8, 0xbfb8aa3b, v11
	v_exp_f32_e32 v8, v8
	v_cvt_pk_bf16_f32 v4, v4, v5
	v_add_f32_e32 v5, 1.0, v7
	v_rcp_f32_e32 v12, v5
	v_add_f32_e32 v5, 1.0, v8
	v_rcp_f32_e32 v13, v5
	v_and_b32_e32 v7, 0xffff0000, v9
	v_lshlrev_b32_e32 v10, 16, v9
	v_pk_mul_f32 v[6:7], v[10:11], v[6:7]
	s_waitcnt vmcnt(6)
	v_lshlrev_b32_e32 v10, 16, v86
	v_pk_mul_f32 v[6:7], v[12:13], v[6:7]
	v_and_b32_e32 v13, 0xffff0000, v86
	v_cvt_pk_bf16_f32 v5, v6, v7
	v_lshlrev_b64 v[6:7], 12, v[132:133]
	v_lshl_add_u64 v[6:7], s[0:1], 0, v[6:7]
	v_lshl_add_u64 v[6:7], v[6:7], 0, v[134:135]
	global_store_dwordx4 v[6:7], v[2:5], off
	s_lshl_b32 s27, s50, 8
	s_or_b32 s5, s22, s27
	v_mul_lo_u32 v2, v136, s45
	v_lshlrev_b32_e32 v3, 4, v143
	v_add3_u32 v2, s4, v2, v3
	v_mul_f32_e32 v3, 0xbfb8aa3b, v10
	v_exp_f32_e32 v6, v3
	v_mul_f32_e32 v3, 0xbfb8aa3b, v13
	v_exp_f32_e32 v7, v3
	ds_read_b128 v[2:5], v2
	v_add_f32_e32 v6, 1.0, v6
	v_rcp_f32_e32 v14, v6
	v_add_f32_e32 v6, 1.0, v7
	v_rcp_f32_e32 v15, v6
	v_mul_lo_u32 v6, v130, s45
	v_lshlrev_b32_e32 v7, 4, v137
	v_add3_u32 v6, s4, v6, v7
	ds_read_b128 v[6:9], v6
	s_waitcnt lgkmcnt(1)
	v_and_b32_e32 v11, 0xffff0000, v2
	v_lshlrev_b32_e32 v12, 16, v2
	v_pk_mul_f32 v[10:11], v[12:13], v[10:11]
	v_lshlrev_b32_e32 v12, 16, v87
	v_pk_mul_f32 v[10:11], v[14:15], v[10:11]
	v_and_b32_e32 v15, 0xffff0000, v87
	v_mul_f32_e32 v2, 0xbfb8aa3b, v12
	v_exp_f32_e32 v13, v2
	v_mul_f32_e32 v2, 0xbfb8aa3b, v15
	v_exp_f32_e32 v14, v2
	v_cvt_pk_bf16_f32 v2, v10, v11
	v_add_f32_e32 v10, 1.0, v13
	v_rcp_f32_e32 v10, v10
	v_add_f32_e32 v11, 1.0, v14
	v_rcp_f32_e32 v11, v11
	v_and_b32_e32 v13, 0xffff0000, v3
	v_lshlrev_b32_e32 v14, 16, v3
	v_pk_mul_f32 v[12:13], v[14:15], v[12:13]
	v_and_b32_e32 v15, 0xffff0000, v88
	v_pk_mul_f32 v[10:11], v[10:11], v[12:13]
	v_lshlrev_b32_e32 v12, 16, v88
	v_mul_f32_e32 v3, 0xbfb8aa3b, v12
	v_exp_f32_e32 v13, v3
	v_mul_f32_e32 v3, 0xbfb8aa3b, v15
	v_exp_f32_e32 v14, v3
	v_cvt_pk_bf16_f32 v3, v10, v11
	v_add_f32_e32 v10, 1.0, v13
	v_rcp_f32_e32 v10, v10
	v_add_f32_e32 v11, 1.0, v14
	v_rcp_f32_e32 v11, v11
	v_and_b32_e32 v13, 0xffff0000, v4
	v_lshlrev_b32_e32 v14, 16, v4
	v_pk_mul_f32 v[12:13], v[14:15], v[12:13]
	v_and_b32_e32 v15, 0xffff0000, v89
	v_pk_mul_f32 v[10:11], v[10:11], v[12:13]
	v_lshlrev_b32_e32 v12, 16, v89
	v_mul_f32_e32 v4, 0xbfb8aa3b, v12
	v_exp_f32_e32 v13, v4
	v_mul_f32_e32 v4, 0xbfb8aa3b, v15
	v_exp_f32_e32 v14, v4
	v_cvt_pk_bf16_f32 v4, v10, v11
	v_add_f32_e32 v10, 1.0, v13
	v_rcp_f32_e32 v10, v10
	v_add_f32_e32 v11, 1.0, v14
	v_rcp_f32_e32 v11, v11
	v_and_b32_e32 v13, 0xffff0000, v5
	v_lshlrev_b32_e32 v14, 16, v5
	v_pk_mul_f32 v[12:13], v[14:15], v[12:13]
	s_waitcnt vmcnt(6)
	v_and_b32_e32 v15, 0xffff0000, v82
	v_pk_mul_f32 v[10:11], v[10:11], v[12:13]
	v_lshlrev_b32_e32 v12, 16, v82
	v_mul_f32_e32 v13, 0xbfb8aa3b, v12
	v_mul_f32_e32 v14, 0xbfb8aa3b, v15
	v_exp_f32_e32 v13, v13
	v_exp_f32_e32 v14, v14
	v_cvt_pk_bf16_f32 v5, v10, v11
	v_lshlrev_b64 v[10:11], 12, v[126:127]
	v_lshl_add_u64 v[10:11], s[0:1], 0, v[10:11]
	v_lshl_add_u64 v[10:11], v[10:11], 0, v[128:129]
	global_store_dwordx4 v[10:11], v[2:5], off
	v_and_b32_e32 v11, 0xffff0000, v83
	s_waitcnt lgkmcnt(0)
	v_lshlrev_b32_e32 v10, 16, v7
	v_add_f32_e32 v2, 1.0, v13
	v_add_f32_e32 v3, 1.0, v14
	v_rcp_f32_e32 v2, v2
	v_rcp_f32_e32 v3, v3
	v_and_b32_e32 v13, 0xffff0000, v6
	v_lshlrev_b32_e32 v14, 16, v6
	v_pk_mul_f32 v[4:5], v[14:15], v[12:13]
	v_mul_f32_e32 v6, 0xbfb8aa3b, v11
	v_pk_mul_f32 v[2:3], v[2:3], v[4:5]
	v_lshlrev_b32_e32 v4, 16, v83
	v_mul_f32_e32 v5, 0xbfb8aa3b, v4
	v_exp_f32_e32 v5, v5
	v_exp_f32_e32 v6, v6
	v_cvt_pk_bf16_f32 v2, v2, v3
	s_lshl_b32 s33, s50, 2
	v_add_f32_e32 v3, 1.0, v5
	v_rcp_f32_e32 v12, v3
	v_add_f32_e32 v3, 1.0, v6
	v_and_b32_e32 v5, 0xffff0000, v7
	v_lshlrev_b32_e32 v6, 16, v84
	v_rcp_f32_e32 v13, v3
	v_pk_mul_f32 v[4:5], v[10:11], v[4:5]
	v_and_b32_e32 v11, 0xffff0000, v84
	v_mul_f32_e32 v3, 0xbfb8aa3b, v6
	v_exp_f32_e32 v7, v3
	v_mul_f32_e32 v3, 0xbfb8aa3b, v11
	v_exp_f32_e32 v10, v3
	v_pk_mul_f32 v[4:5], v[12:13], v[4:5]
	s_mov_b32 s24, 0
	v_cvt_pk_bf16_f32 v3, v4, v5
	v_add_f32_e32 v4, 1.0, v7
	v_add_f32_e32 v5, 1.0, v10
	v_rcp_f32_e32 v4, v4
	v_rcp_f32_e32 v5, v5
	v_and_b32_e32 v7, 0xffff0000, v8
	v_lshlrev_b32_e32 v10, 16, v8
	v_pk_mul_f32 v[6:7], v[10:11], v[6:7]
	v_and_b32_e32 v11, 0xffff0000, v85
	v_pk_mul_f32 v[4:5], v[4:5], v[6:7]
	v_lshlrev_b32_e32 v6, 16, v85
	v_mul_f32_e32 v7, 0xbfb8aa3b, v6
	v_exp_f32_e32 v7, v7
	v_mul_f32_e32 v8, 0xbfb8aa3b, v11
	v_exp_f32_e32 v8, v8
	v_cvt_pk_bf16_f32 v4, v4, v5
	v_add_f32_e32 v5, 1.0, v7
	v_rcp_f32_e32 v12, v5
	v_add_f32_e32 v5, 1.0, v8
	v_rcp_f32_e32 v13, v5
	v_and_b32_e32 v7, 0xffff0000, v9
	v_lshlrev_b32_e32 v10, 16, v9
	v_pk_mul_f32 v[6:7], v[10:11], v[6:7]
	s_waitcnt vmcnt(6)
	v_lshlrev_b32_e32 v10, 16, v78
	v_pk_mul_f32 v[6:7], v[12:13], v[6:7]
	v_and_b32_e32 v13, 0xffff0000, v78
	v_cvt_pk_bf16_f32 v5, v6, v7
	v_lshlrev_b64 v[6:7], 12, v[120:121]
	v_lshl_add_u64 v[6:7], s[0:1], 0, v[6:7]
	v_lshl_add_u64 v[6:7], v[6:7], 0, v[122:123]
	global_store_dwordx4 v[6:7], v[2:5], off
	s_mov_b32 s25, 2
	s_mov_b32 s26, 63
	v_mul_lo_u32 v2, v124, s45
	v_lshlrev_b32_e32 v3, 4, v131
	v_add3_u32 v2, s4, v2, v3
	v_mul_f32_e32 v3, 0xbfb8aa3b, v10
	v_exp_f32_e32 v6, v3
	v_mul_f32_e32 v3, 0xbfb8aa3b, v13
	v_exp_f32_e32 v7, v3
	ds_read_b128 v[2:5], v2
	v_add_f32_e32 v6, 1.0, v6
	v_rcp_f32_e32 v14, v6
	v_add_f32_e32 v6, 1.0, v7
	v_rcp_f32_e32 v15, v6
	v_mul_lo_u32 v6, v118, s45
	v_lshlrev_b32_e32 v7, 4, v125
	v_add3_u32 v6, s4, v6, v7
	ds_read_b128 v[6:9], v6
	s_waitcnt lgkmcnt(1)
	v_and_b32_e32 v11, 0xffff0000, v2
	v_lshlrev_b32_e32 v12, 16, v2
	v_pk_mul_f32 v[10:11], v[12:13], v[10:11]
	v_lshlrev_b32_e32 v12, 16, v79
	v_pk_mul_f32 v[10:11], v[14:15], v[10:11]
	v_and_b32_e32 v15, 0xffff0000, v79
	v_mul_f32_e32 v2, 0xbfb8aa3b, v12
	v_exp_f32_e32 v13, v2
	v_mul_f32_e32 v2, 0xbfb8aa3b, v15
	v_exp_f32_e32 v14, v2
	v_cvt_pk_bf16_f32 v2, v10, v11
	v_add_f32_e32 v10, 1.0, v13
	v_rcp_f32_e32 v10, v10
	v_add_f32_e32 v11, 1.0, v14
	v_rcp_f32_e32 v11, v11
	v_and_b32_e32 v13, 0xffff0000, v3
	v_lshlrev_b32_e32 v14, 16, v3
	v_pk_mul_f32 v[12:13], v[14:15], v[12:13]
	v_and_b32_e32 v15, 0xffff0000, v80
	v_pk_mul_f32 v[10:11], v[10:11], v[12:13]
	v_lshlrev_b32_e32 v12, 16, v80
	v_mul_f32_e32 v3, 0xbfb8aa3b, v12
	v_exp_f32_e32 v13, v3
	v_mul_f32_e32 v3, 0xbfb8aa3b, v15
	v_exp_f32_e32 v14, v3
	v_cvt_pk_bf16_f32 v3, v10, v11
	v_add_f32_e32 v10, 1.0, v13
	v_rcp_f32_e32 v10, v10
	v_add_f32_e32 v11, 1.0, v14
	v_rcp_f32_e32 v11, v11
	v_and_b32_e32 v13, 0xffff0000, v4
	v_lshlrev_b32_e32 v14, 16, v4
	v_pk_mul_f32 v[12:13], v[14:15], v[12:13]
	v_and_b32_e32 v15, 0xffff0000, v81
	v_pk_mul_f32 v[10:11], v[10:11], v[12:13]
	v_lshlrev_b32_e32 v12, 16, v81
	v_mul_f32_e32 v4, 0xbfb8aa3b, v12
	v_exp_f32_e32 v13, v4
	v_mul_f32_e32 v4, 0xbfb8aa3b, v15
	v_exp_f32_e32 v14, v4
	v_cvt_pk_bf16_f32 v4, v10, v11
	v_add_f32_e32 v10, 1.0, v13
	v_rcp_f32_e32 v10, v10
	v_add_f32_e32 v11, 1.0, v14
	v_rcp_f32_e32 v11, v11
	v_and_b32_e32 v13, 0xffff0000, v5
	v_lshlrev_b32_e32 v14, 16, v5
	v_pk_mul_f32 v[12:13], v[14:15], v[12:13]
	s_waitcnt vmcnt(6)
	v_and_b32_e32 v15, 0xffff0000, v74
	v_pk_mul_f32 v[10:11], v[10:11], v[12:13]
	v_lshlrev_b32_e32 v12, 16, v74
	v_mul_f32_e32 v13, 0xbfb8aa3b, v12
	v_mul_f32_e32 v14, 0xbfb8aa3b, v15
	v_exp_f32_e32 v13, v13
	v_exp_f32_e32 v14, v14
	v_cvt_pk_bf16_f32 v5, v10, v11
	v_lshlrev_b64 v[10:11], 12, v[114:115]
	v_lshl_add_u64 v[10:11], s[0:1], 0, v[10:11]
	v_lshl_add_u64 v[10:11], v[10:11], 0, v[116:117]
	global_store_dwordx4 v[10:11], v[2:5], off
	v_and_b32_e32 v11, 0xffff0000, v75
	s_waitcnt lgkmcnt(0)
	v_lshlrev_b32_e32 v10, 16, v7
	v_add_f32_e32 v2, 1.0, v13
	v_add_f32_e32 v3, 1.0, v14
	v_rcp_f32_e32 v2, v2
	v_rcp_f32_e32 v3, v3
	v_and_b32_e32 v13, 0xffff0000, v6
	v_lshlrev_b32_e32 v14, 16, v6
	v_pk_mul_f32 v[4:5], v[14:15], v[12:13]
	v_mul_f32_e32 v6, 0xbfb8aa3b, v11
	v_pk_mul_f32 v[2:3], v[2:3], v[4:5]
	v_lshlrev_b32_e32 v4, 16, v75
	v_mul_f32_e32 v5, 0xbfb8aa3b, v4
	v_exp_f32_e32 v5, v5
	v_exp_f32_e32 v6, v6
	v_cvt_pk_bf16_f32 v2, v2, v3
	v_mov_b32_e32 v196, 0
	v_add_f32_e32 v3, 1.0, v5
	v_rcp_f32_e32 v12, v3
	v_add_f32_e32 v3, 1.0, v6
	v_and_b32_e32 v5, 0xffff0000, v7
	v_lshlrev_b32_e32 v6, 16, v76
	v_rcp_f32_e32 v13, v3
	v_pk_mul_f32 v[4:5], v[10:11], v[4:5]
	v_and_b32_e32 v11, 0xffff0000, v76
	v_mul_f32_e32 v3, 0xbfb8aa3b, v6
	v_exp_f32_e32 v7, v3
	v_mul_f32_e32 v3, 0xbfb8aa3b, v11
	v_exp_f32_e32 v10, v3
	v_pk_mul_f32 v[4:5], v[12:13], v[4:5]
	v_mov_b32_e32 v197, 0xf149f2ca
	v_cvt_pk_bf16_f32 v3, v4, v5
	v_add_f32_e32 v4, 1.0, v7
	v_add_f32_e32 v5, 1.0, v10
	v_rcp_f32_e32 v4, v4
	v_rcp_f32_e32 v5, v5
	v_and_b32_e32 v7, 0xffff0000, v8
	v_lshlrev_b32_e32 v10, 16, v8
	v_pk_mul_f32 v[6:7], v[10:11], v[6:7]
	v_and_b32_e32 v11, 0xffff0000, v77
	v_pk_mul_f32 v[4:5], v[4:5], v[6:7]
	v_lshlrev_b32_e32 v6, 16, v77
	v_mul_f32_e32 v7, 0xbfb8aa3b, v6
	v_exp_f32_e32 v7, v7
	v_mul_f32_e32 v8, 0xbfb8aa3b, v11
	v_exp_f32_e32 v8, v8
	v_cvt_pk_bf16_f32 v4, v4, v5
	v_add_f32_e32 v5, 1.0, v7
	v_rcp_f32_e32 v12, v5
	v_add_f32_e32 v5, 1.0, v8
	v_rcp_f32_e32 v13, v5
	v_and_b32_e32 v7, 0xffff0000, v9
	v_lshlrev_b32_e32 v10, 16, v9
	v_pk_mul_f32 v[6:7], v[10:11], v[6:7]
	s_waitcnt vmcnt(6)
	v_lshlrev_b32_e32 v10, 16, v70
	v_pk_mul_f32 v[6:7], v[12:13], v[6:7]
	v_and_b32_e32 v13, 0xffff0000, v70
	v_cvt_pk_bf16_f32 v5, v6, v7
	v_lshlrev_b64 v[6:7], 12, v[108:109]
	v_lshl_add_u64 v[6:7], s[0:1], 0, v[6:7]
	v_lshl_add_u64 v[6:7], v[6:7], 0, v[110:111]
	global_store_dwordx4 v[6:7], v[2:5], off
	s_nop 1
	v_mul_lo_u32 v2, v112, s45
	v_lshlrev_b32_e32 v3, 4, v119
	v_add3_u32 v2, s4, v2, v3
	v_mul_f32_e32 v3, 0xbfb8aa3b, v10
	v_exp_f32_e32 v6, v3
	v_mul_f32_e32 v3, 0xbfb8aa3b, v13
	v_exp_f32_e32 v7, v3
	ds_read_b128 v[2:5], v2
	v_add_f32_e32 v6, 1.0, v6
	v_rcp_f32_e32 v14, v6
	v_add_f32_e32 v6, 1.0, v7
	v_rcp_f32_e32 v15, v6
	v_mul_lo_u32 v6, v106, s45
	v_add3_u32 v0, s4, v6, v0
	ds_read_b128 v[6:9], v0
	s_waitcnt lgkmcnt(1)
	v_and_b32_e32 v11, 0xffff0000, v2
	v_lshlrev_b32_e32 v12, 16, v2
	v_pk_mul_f32 v[10:11], v[12:13], v[10:11]
	v_lshlrev_b32_e32 v12, 16, v71
	v_pk_mul_f32 v[10:11], v[14:15], v[10:11]
	v_and_b32_e32 v15, 0xffff0000, v71
	v_mul_f32_e32 v0, 0xbfb8aa3b, v12
	v_exp_f32_e32 v0, v0
	v_mul_f32_e32 v2, 0xbfb8aa3b, v15
	v_exp_f32_e32 v13, v2
	v_cvt_pk_bf16_f32 v2, v10, v11
	v_add_f32_e32 v0, 1.0, v0
	v_rcp_f32_e32 v10, v0
	v_add_f32_e32 v0, 1.0, v13
	v_rcp_f32_e32 v11, v0
	v_and_b32_e32 v13, 0xffff0000, v3
	v_lshlrev_b32_e32 v14, 16, v3
	v_pk_mul_f32 v[12:13], v[14:15], v[12:13]
	v_and_b32_e32 v15, 0xffff0000, v72
	v_pk_mul_f32 v[10:11], v[10:11], v[12:13]
	v_lshlrev_b32_e32 v12, 16, v72
	v_mul_f32_e32 v0, 0xbfb8aa3b, v12
	v_exp_f32_e32 v0, v0
	v_mul_f32_e32 v3, 0xbfb8aa3b, v15
	v_exp_f32_e32 v13, v3
	v_cvt_pk_bf16_f32 v3, v10, v11
	v_add_f32_e32 v0, 1.0, v0
	v_rcp_f32_e32 v10, v0
	v_add_f32_e32 v0, 1.0, v13
	v_rcp_f32_e32 v11, v0
	v_and_b32_e32 v13, 0xffff0000, v4
	v_lshlrev_b32_e32 v14, 16, v4
	v_pk_mul_f32 v[12:13], v[14:15], v[12:13]
	v_and_b32_e32 v15, 0xffff0000, v73
	v_pk_mul_f32 v[10:11], v[10:11], v[12:13]
	v_lshlrev_b32_e32 v12, 16, v73
	v_mul_f32_e32 v0, 0xbfb8aa3b, v12
	v_exp_f32_e32 v0, v0
	v_mul_f32_e32 v4, 0xbfb8aa3b, v15
	v_exp_f32_e32 v13, v4
	v_cvt_pk_bf16_f32 v4, v10, v11
	v_add_f32_e32 v0, 1.0, v0
	v_rcp_f32_e32 v10, v0
	v_add_f32_e32 v0, 1.0, v13
	v_rcp_f32_e32 v11, v0
	v_and_b32_e32 v13, 0xffff0000, v5
	v_lshlrev_b32_e32 v14, 16, v5
	v_pk_mul_f32 v[12:13], v[14:15], v[12:13]
	s_waitcnt vmcnt(6)
	v_and_b32_e32 v15, 0xffff0000, v66
	v_pk_mul_f32 v[10:11], v[10:11], v[12:13]
	v_lshlrev_b32_e32 v12, 16, v66
	v_mul_f32_e32 v0, 0xbfb8aa3b, v12
	v_exp_f32_e32 v0, v0
	v_mul_f32_e32 v13, 0xbfb8aa3b, v15
	v_exp_f32_e32 v13, v13
	v_cvt_pk_bf16_f32 v5, v10, v11
	v_lshlrev_b64 v[10:11], 12, v[102:103]
	v_lshl_add_u64 v[10:11], s[0:1], 0, v[10:11]
	v_lshl_add_u64 v[10:11], v[10:11], 0, v[104:105]
	v_add_f32_e32 v0, 1.0, v0
	global_store_dwordx4 v[10:11], v[2:5], off
	s_waitcnt lgkmcnt(0)
	v_lshlrev_b32_e32 v14, 16, v6
	v_and_b32_e32 v11, 0xffff0000, v67
	v_rcp_f32_e32 v2, v0
	v_add_f32_e32 v0, 1.0, v13
	v_rcp_f32_e32 v3, v0
	v_and_b32_e32 v13, 0xffff0000, v6
	v_pk_mul_f32 v[4:5], v[14:15], v[12:13]
	v_lshlrev_b32_e32 v10, 16, v7
	v_pk_mul_f32 v[2:3], v[2:3], v[4:5]
	v_lshlrev_b32_e32 v4, 16, v67
	v_mul_f32_e32 v0, 0xbfb8aa3b, v4
	v_exp_f32_e32 v0, v0
	v_mul_f32_e32 v5, 0xbfb8aa3b, v11
	v_exp_f32_e32 v5, v5
	v_lshlrev_b32_e32 v6, 16, v68
	v_add_f32_e32 v0, 1.0, v0
	v_rcp_f32_e32 v12, v0
	v_add_f32_e32 v0, 1.0, v5
	v_and_b32_e32 v5, 0xffff0000, v7
	v_rcp_f32_e32 v13, v0
	v_pk_mul_f32 v[4:5], v[10:11], v[4:5]
	v_and_b32_e32 v11, 0xffff0000, v68
	v_mul_f32_e32 v0, 0xbfb8aa3b, v6
	v_cvt_pk_bf16_f32 v2, v2, v3
	v_exp_f32_e32 v0, v0
	v_mul_f32_e32 v3, 0xbfb8aa3b, v11
	v_exp_f32_e32 v7, v3
	v_pk_mul_f32 v[4:5], v[12:13], v[4:5]
	v_add_f32_e32 v0, 1.0, v0
	v_cvt_pk_bf16_f32 v3, v4, v5
	v_rcp_f32_e32 v4, v0
	v_add_f32_e32 v0, 1.0, v7
	v_rcp_f32_e32 v5, v0
	v_and_b32_e32 v7, 0xffff0000, v8
	v_lshlrev_b32_e32 v10, 16, v8
	v_pk_mul_f32 v[6:7], v[10:11], v[6:7]
	v_and_b32_e32 v11, 0xffff0000, v69
	v_pk_mul_f32 v[4:5], v[4:5], v[6:7]
	v_lshlrev_b32_e32 v6, 16, v69
	v_mul_f32_e32 v0, 0xbfb8aa3b, v6
	v_exp_f32_e32 v0, v0
	v_mul_f32_e32 v7, 0xbfb8aa3b, v11
	v_exp_f32_e32 v7, v7
	v_lshlrev_b32_e32 v10, 16, v9
	v_add_f32_e32 v0, 1.0, v0
	v_rcp_f32_e32 v12, v0
	v_add_f32_e32 v0, 1.0, v7
	v_rcp_f32_e32 v13, v0
	v_and_b32_e32 v7, 0xffff0000, v9
	v_pk_mul_f32 v[6:7], v[10:11], v[6:7]
	v_cvt_pk_bf16_f32 v4, v4, v5
	v_pk_mul_f32 v[6:7], v[12:13], v[6:7]
	s_nop 0
	v_cvt_pk_bf16_f32 v5, v6, v7
	v_lshlrev_b64 v[6:7], 12, v[98:99]
	v_lshl_add_u64 v[6:7], s[0:1], 0, v[6:7]
	v_lshl_add_u64 v[6:7], v[6:7], 0, v[100:101]
	global_store_dwordx4 v[6:7], v[2:5], off
	s_barrier
	s_nop 0
	v_ashrrev_i32_e32 v0, 31, v28
	v_lshrrev_b32_e32 v0, 28, v0
	v_add_u32_e32 v0, v28, v0
	v_ashrrev_i32_e32 v146, 4, v0
	v_and_b32_e32 v0, -16, v0
	v_sub_u32_e32 v29, v28, v0
	v_ashrrev_i32_e32 v147, 31, v146
	v_lshlrev_b32_e32 v4, 3, v29
	v_lshlrev_b64 v[2:3], 14, v[146:147]
	v_ashrrev_i32_e32 v5, 31, v4
	v_lshl_add_u64 v[2:3], s[20:21], 0, v[2:3]
	v_lshlrev_b64 v[18:19], 1, v[4:5]
	v_lshl_add_u64 v[20:21], v[2:3], 0, v[18:19]
	v_add_co_u32_e32 v6, vcc, s43, v20
	v_add_u32_e32 v0, 0x200, v28
	s_nop 0
	v_addc_co_u32_e32 v7, vcc, 0, v21, vcc
	global_load_dwordx4 v[2:5], v[6:7], off offset:-4096
	s_nop 0
	global_load_dwordx4 v[6:9], v[6:7], off
	v_ashrrev_i32_e32 v10, 31, v0
	v_readfirstlane_b32 s4, v28
	v_lshrrev_b32_e32 v10, 28, v10
	s_ashr_i32 s22, s4, 1
	v_add_u32_e32 v10, v0, v10
	s_andn2_b32 s22, s22, 31
	v_ashrrev_i32_e32 v148, 4, v10
	v_and_b32_e32 v10, -16, v10
	s_ashr_i32 s34, s22, 31
	v_sub_u32_e32 v30, v0, v10
	s_add_u32 s4, s5, s22
	v_ashrrev_i32_e32 v149, 31, v148
	v_lshlrev_b32_e32 v12, 3, v30
	v_and_b32_e32 v31, 31, v28
	s_addc_u32 s5, s23, s34
	v_lshlrev_b64 v[10:11], 14, v[148:149]
	v_ashrrev_i32_e32 v13, 31, v12
	v_or_b32_e32 v26, s4, v31
	v_mov_b32_e32 v27, s5
	v_lshl_add_u64 v[10:11], s[20:21], 0, v[10:11]
	v_lshlrev_b64 v[22:23], 1, v[12:13]
	v_lshlrev_b64 v[26:27], 14, v[26:27]
	v_lshl_add_u64 v[24:25], v[10:11], 0, v[22:23]
	v_bfe_u32 v32, v28, 5, 1
	v_lshl_add_u64 v[26:27], s[12:13], 0, v[26:27]
	v_add_co_u32_e32 v14, vcc, s43, v24
	v_lshl_add_u64 v[26:27], v[26:27], 0, s[16:17]
	v_lshlrev_b32_e32 v0, 4, v32
	v_addc_co_u32_e32 v15, vcc, 0, v25, vcc
	v_lshl_add_u64 v[26:27], v[26:27], 0, v[0:1]
	v_mul_lo_u32 v149, v146, s45
	v_lshlrev_b32_e32 v156, 4, v29
	global_load_dwordx4 v[10:13], v[14:15], off offset:-4096
	s_nop 0
	global_load_dwordx4 v[14:17], v[14:15], off
	s_nop 0
	global_load_dwordx4 v[98:101], v[26:27], off
	global_load_dwordx4 v[102:105], v[26:27], off offset:32
	global_load_dwordx4 v[106:109], v[26:27], off offset:64
	global_load_dwordx4 v[110:113], v[26:27], off offset:96
	global_load_dwordx4 v[114:117], v[26:27], off offset:128
	global_load_dwordx4 v[118:121], v[26:27], off offset:160
	global_load_dwordx4 v[122:125], v[26:27], off offset:192
	global_load_dwordx4 v[126:129], v[26:27], off offset:224
	v_add3_u32 v26, 0, v149, v156
	s_waitcnt vmcnt(0)
	v_mul_lo_u32 v158, v148, s45
	v_lshlrev_b32_e32 v159, 4, v30
	v_lshlrev_b32_e32 v163, 2, v32
	v_add_u32_e32 v161, 0, v0
	s_add_i32 s7, s7, s22
	v_and_b32_e32 v147, 63, v28
	v_mad_u32_u24 v162, v31, s45, v161
	v_lshl_add_u64 v[150:151], s[20:21], 0, v[18:19]
	v_lshl_add_u64 v[152:153], s[20:21], 0, v[22:23]
	v_or_b32_e32 v195, s7, v31
	s_add_i32 s23, s33, 4
	v_mul_lo_u32 v157, v146, s46
	v_mul_lo_u32 v160, v148, s46
	s_add_i32 s27, s22, s27
	s_or_b32 s33, s33, 3
	v_or_b32_e32 v165, 32, v163
	v_or_b32_e32 v166, 33, v163
	v_or_b32_e32 v167, 2, v163
	v_or_b32_e32 v168, 34, v163
	v_or_b32_e32 v169, 3, v163
	v_or_b32_e32 v170, 35, v163
	v_or_b32_e32 v171, 8, v163
	v_or_b32_e32 v172, 40, v163
	v_or_b32_e32 v173, 9, v163
	v_or_b32_e32 v174, 41, v163
	v_or_b32_e32 v175, 10, v163
	v_or_b32_e32 v176, 42, v163
	v_or_b32_e32 v177, 11, v163
	v_or_b32_e32 v178, 43, v163
	v_or_b32_e32 v179, 16, v163
	v_or_b32_e32 v180, 48, v163
	v_or_b32_e32 v181, 17, v163
	v_or_b32_e32 v182, 49, v163
	v_or_b32_e32 v183, 18, v163
	v_or_b32_e32 v184, 50, v163
	v_or_b32_e32 v185, 19, v163
	v_or_b32_e32 v186, 51, v163
	v_or_b32_e32 v187, 24, v163
	v_or_b32_e32 v188, 56, v163
	ds_write_b128 v26, v[2:5]
	v_mad_u64_u32 v[2:3], s[34:35], v146, 48, v[26:27]
	ds_write_b128 v2, v[6:9] offset:34816
	v_add_co_u32_e32 v2, vcc, s47, v20
	v_mov_b32_e32 v4, v1
	s_nop 0
	v_addc_co_u32_e32 v3, vcc, 0, v21, vcc
	global_load_dwordx4 v[130:133], v[2:3], off offset:-4096
	global_load_dwordx4 v[134:137], v[2:3], off
	v_add_co_u32_e32 v2, vcc, s47, v24
	v_mov_b32_e32 v5, v1
	s_nop 0
	v_addc_co_u32_e32 v3, vcc, 0, v25, vcc
	global_load_dwordx4 v[138:141], v[2:3], off offset:-4096
	global_load_dwordx4 v[142:145], v[2:3], off
	v_add3_u32 v2, 0, v158, v159
	v_mov_b32_e32 v6, v1
	v_mov_b32_e32 v7, v1
	v_mov_b32_e32 v8, v1
	v_mov_b32_e32 v9, v1
	v_or_b32_e32 v189, 25, v163
	v_or_b32_e32 v190, 57, v163
	v_or_b32_e32 v191, 26, v163
	v_or_b32_e32 v192, 58, v163
	v_or_b32_e32 v193, 27, v163
	v_or_b32_e32 v194, 59, v163
	ds_write_b128 v2, v[10:13]
	v_mad_u64_u32 v[2:3], s[34:35], v148, 48, v[2:3]
	ds_write_b128 v2, v[14:17] offset:34816
	v_lshrrev_b32_e32 v2, 2, v28
	v_and_or_b32 v0, v2, 3, v163
	v_lshlrev_b32_e32 v2, 1, v28
	v_lshlrev_b32_e32 v3, 3, v28
	v_mad_u32_u24 v0, v0, s46, 0
	v_and_b32_e32 v2, 32, v2
	v_and_b32_e32 v3, 24, v3
	v_mov_b32_e32 v14, v1
	v_mov_b32_e32 v15, v1
	v_add3_u32 v164, v0, v2, v3
	v_mov_b32_e32 v0, v1
	v_mov_b32_e32 v2, v1
	v_mov_b32_e32 v3, v1
	v_mov_b32_e32 v10, v1
	v_mov_b32_e32 v11, v1
	v_mov_b32_e32 v12, v1
	v_mov_b32_e32 v13, v1
	v_mov_b64_e32 v[64:65], v[14:15]
	v_mov_b64_e32 v[48:49], v[14:15]
	v_mov_b64_e32 v[32:33], v[14:15]
	v_mov_b64_e32 v[62:63], v[12:13]
	v_mov_b64_e32 v[60:61], v[10:11]
	v_mov_b64_e32 v[58:59], v[8:9]
	v_mov_b64_e32 v[56:57], v[6:7]
	v_mov_b64_e32 v[54:55], v[4:5]
	v_mov_b64_e32 v[52:53], v[2:3]
	v_mov_b64_e32 v[50:51], v[0:1]
	v_mov_b64_e32 v[46:47], v[12:13]
	v_mov_b64_e32 v[44:45], v[10:11]
	v_mov_b64_e32 v[42:43], v[8:9]
	v_mov_b64_e32 v[40:41], v[6:7]
	v_mov_b64_e32 v[38:39], v[4:5]
	v_mov_b64_e32 v[36:37], v[2:3]
	v_mov_b64_e32 v[34:35], v[0:1]
	v_mov_b64_e32 v[30:31], v[12:13]
	v_mov_b64_e32 v[28:29], v[10:11]
	v_mov_b64_e32 v[26:27], v[8:9]
	v_mov_b64_e32 v[24:25], v[6:7]
	v_mov_b64_e32 v[22:23], v[4:5]
	v_mov_b64_e32 v[20:21], v[2:3]
	v_mov_b64_e32 v[18:19], v[0:1]
	v_mov_b64_e32 v[16:17], v[14:15]
	v_mov_b64_e32 v[14:15], v[12:13]
	v_mov_b64_e32 v[12:13], v[10:11]
	v_mov_b64_e32 v[10:11], v[8:9]
	v_mov_b64_e32 v[8:9], v[6:7]
	v_mov_b64_e32 v[6:7], v[4:5]
	v_mov_b64_e32 v[4:5], v[2:3]
	v_mov_b64_e32 v[2:3], v[0:1]
	s_waitcnt lgkmcnt(0)
	s_movk_i32 s68, 0x5000
	s_mov_b32 s69, 0
	s_mov_b32 s70, 0xe800
	s_mov_b32 s72, 0
	s_barrier
	s_branch .LBB0_657
.LBB0_657:
	s_add_i32 s7, s25, -2
	s_and_b32 s7, s7, 1
	s_xor_b32 s20, s7, 1
	s_mul_i32 s21, s20, 0x4400
	s_add_i32 s21, s21, 0
	s_mulk_i32 s20, 0xc00
	s_add_i32 s20, s21, s20
	v_add3_u32 v0, s21, v149, v156
	s_waitcnt vmcnt(3)
	ds_write_b128 v0, v[130:133]
	v_add3_u32 v0, s68, v157, v156
	s_waitcnt vmcnt(2)
	ds_write_b128 v0, v[134:137] offset:34816
	v_add3_u32 v0, s21, v158, v159
	s_cmp_lt_u32 s25, s23
	s_waitcnt vmcnt(1)
	ds_write_b128 v0, v[138:141]
	v_add3_u32 v0, s68, v160, v159
	s_cselect_b32 s20, s25, s33
	s_lshl_b32 s20, s20, 6
	v_add_u32_e32 v250, s20, v146
	v_ashrrev_i32_e32 v251, 31, v250
	v_lshlrev_b64 v[250:251], 14, v[250:251]
	v_lshl_add_u64 v[250:251], v[150:151], 0, v[250:251]
	v_add_co_u32_e32 v252, vcc, s42, v250
	s_waitcnt vmcnt(0)
	ds_write_b128 v0, v[142:145] offset:34816
	v_addc_co_u32_e32 v253, vcc, 0, v251, vcc
	v_add_co_u32_e32 v250, vcc, 0x2000, v250
	s_nop 1
	v_addc_co_u32_e32 v251, vcc, 0, v251, vcc
	global_load_dwordx4 v[130:133], v[252:253], off
	global_load_dwordx4 v[134:137], v[250:251], off
	v_add_u32_e32 v250, s20, v148
	v_ashrrev_i32_e32 v251, 31, v250
	v_lshlrev_b64 v[250:251], 14, v[250:251]
	v_lshl_add_u64 v[250:251], v[152:153], 0, v[250:251]
	v_add_co_u32_e32 v252, vcc, 0x1000, v250
	s_sub_i32 s20, s26, 63
	s_nop 0
	v_addc_co_u32_e32 v253, vcc, 0, v251, vcc
	v_add_co_u32_e32 v250, vcc, 0x2000, v250
	s_cmp_gt_i32 s20, s27
	s_nop 0
	v_addc_co_u32_e32 v251, vcc, 0, v251, vcc
	global_load_dwordx4 v[138:141], v[252:253], off
	global_load_dwordx4 v[142:145], v[250:251], off
	s_sub_i32 s20, s26, 63
	s_cmp_gt_i32 s20, s27
	s_cbranch_scc1 .Lff2_inact
	s_cmp_eq_u32 s72, 0
	s_cbranch_scc1 .Lff2_first
	s_mul_i32 s20, s7, 0x4400
	v_add_u32_e32 v0, s20, v162
	ds_read_b128 v[198:201], v0
	ds_read_b128 v[202:205], v0 offset:32
	ds_read_b128 v[206:209], v0 offset:8704
	ds_read_b128 v[210:213], v0 offset:8736
	v_add_u32_e32 v246, s24, v161
	v_add_u32_e32 v234, 0x12800, v246
	v_add_u32_e32 v235, 0x12880, v246
	v_add_u32_e32 v238, 0x12820, v246
	v_add_u32_e32 v239, 0x128a0, v246
	v_add_u32_e32 v242, 0x12840, v246
	v_add_u32_e32 v243, 0x128c0, v246
	v_add_u32_e32 v247, 0x12860, v246
	v_add_u32_e32 v246, 0x128e0, v246
	ds_read_b128 v[218:221], v234
	ds_read_b128 v[234:237], v235
	ds_read_b128 v[222:225], v238
	ds_read_b128 v[238:241], v239
	ds_read_b128 v[226:229], v242
	ds_read_b128 v[242:245], v243
	ds_read_b128 v[230:233], v247
	ds_read_b128 v[246:249], v246
	s_waitcnt lgkmcnt(1)
	v_mfma_f32_32x32x16_bf16 v[218:233], v[198:201], v[98:101], v[218:233]
	v_sub_f32_e32 v82, v82, v197
	v_sub_f32_e32 v83, v83, v197
	v_sub_f32_e32 v84, v84, v197
	v_sub_f32_e32 v85, v85, v197
	v_exp_f32_e32 v82, v82
	v_exp_f32_e32 v83, v83
	v_exp_f32_e32 v84, v84
	v_exp_f32_e32 v85, v85
	s_waitcnt lgkmcnt(0)
	v_mfma_f32_32x32x16_bf16 v[234:249], v[206:209], v[98:101], v[234:249]
	v_sub_f32_e32 v86, v86, v197
	v_sub_f32_e32 v87, v87, v197
	v_sub_f32_e32 v88, v88, v197
	v_sub_f32_e32 v89, v89, v197
	v_exp_f32_e32 v86, v86
	v_exp_f32_e32 v87, v87
	v_exp_f32_e32 v88, v88
	v_exp_f32_e32 v89, v89
	v_mfma_f32_32x32x16_bf16 v[218:233], v[202:205], v[102:105], v[218:233]
	v_sub_f32_e32 v66, v66, v197
	v_sub_f32_e32 v67, v67, v197
	v_sub_f32_e32 v68, v68, v197
	v_sub_f32_e32 v69, v69, v197
	v_exp_f32_e32 v66, v66
	v_exp_f32_e32 v67, v67
	v_exp_f32_e32 v68, v68
	v_exp_f32_e32 v69, v69
	ds_read_b128 v[198:201], v0 offset:64
	ds_read_b128 v[202:205], v0 offset:96
	ds_read_b128 v[206:209], v0 offset:8768
	ds_read_b128 v[214:217], v0 offset:8800
	v_mfma_f32_32x32x16_bf16 v[234:249], v[210:213], v[102:105], v[234:249]
	v_add_f32_e32 v250, v82, v86
	v_add_f32_e32 v251, v83, v87
	v_add_f32_e32 v252, v84, v88
	v_add_f32_e32 v253, v85, v89
	v_sub_f32_e32 v70, v70, v197
	v_sub_f32_e32 v71, v71, v197
	v_sub_f32_e32 v72, v72, v197
	v_sub_f32_e32 v73, v73, v197
	s_waitcnt lgkmcnt(3)
	v_mfma_f32_32x32x16_bf16 v[218:233], v[198:201], v[106:109], v[218:233]
	v_exp_f32_e32 v70, v70
	v_exp_f32_e32 v71, v71
	v_exp_f32_e32 v72, v72
	v_exp_f32_e32 v73, v73
	v_add_f32_e32 v250, v250, v66
	v_add_f32_e32 v251, v251, v67
	v_add_f32_e32 v252, v252, v68
	v_add_f32_e32 v253, v253, v69
	s_waitcnt lgkmcnt(1)
	v_mfma_f32_32x32x16_bf16 v[234:249], v[206:209], v[106:109], v[234:249]
	v_sub_f32_e32 v90, v90, v197
	v_sub_f32_e32 v91, v91, v197
	v_sub_f32_e32 v92, v92, v197
	v_sub_f32_e32 v93, v93, v197
	v_exp_f32_e32 v90, v90
	v_exp_f32_e32 v91, v91
	v_exp_f32_e32 v92, v92
	v_exp_f32_e32 v93, v93
	v_mfma_f32_32x32x16_bf16 v[218:233], v[202:205], v[110:113], v[218:233]
	v_add_f32_e32 v250, v250, v70
	v_add_f32_e32 v251, v251, v71
	v_add_f32_e32 v252, v252, v72
	v_add_f32_e32 v253, v253, v73
	v_sub_f32_e32 v94, v94, v197
	v_sub_f32_e32 v95, v95, v197
	v_sub_f32_e32 v96, v96, v197
	v_sub_f32_e32 v97, v97, v197
	ds_read_b128 v[198:201], v0 offset:128
	ds_read_b128 v[202:205], v0 offset:160
	ds_read_b128 v[206:209], v0 offset:8832
	ds_read_b128 v[210:213], v0 offset:8864
	s_waitcnt lgkmcnt(4)
	v_mfma_f32_32x32x16_bf16 v[234:249], v[214:217], v[110:113], v[234:249]
	v_exp_f32_e32 v94, v94
	v_exp_f32_e32 v95, v95
	v_exp_f32_e32 v96, v96
	v_exp_f32_e32 v97, v97
	v_add_f32_e32 v250, v250, v90
	v_add_f32_e32 v251, v251, v91
	v_add_f32_e32 v252, v252, v92
	v_add_f32_e32 v253, v253, v93
	s_waitcnt lgkmcnt(3)
	v_mfma_f32_32x32x16_bf16 v[218:233], v[198:201], v[114:117], v[218:233]
	v_sub_f32_e32 v74, v74, v197
	v_sub_f32_e32 v75, v75, v197
	v_sub_f32_e32 v76, v76, v197
	v_sub_f32_e32 v77, v77, v197
	v_exp_f32_e32 v74, v74
	v_exp_f32_e32 v75, v75
	v_exp_f32_e32 v76, v76
	v_exp_f32_e32 v77, v77
	s_waitcnt lgkmcnt(1)
	v_mfma_f32_32x32x16_bf16 v[234:249], v[206:209], v[114:117], v[234:249]
	v_add_f32_e32 v250, v250, v94
	v_add_f32_e32 v251, v251, v95
	v_add_f32_e32 v252, v252, v96
	v_add_f32_e32 v253, v253, v97
	v_sub_f32_e32 v78, v78, v197
	v_sub_f32_e32 v79, v79, v197
	v_sub_f32_e32 v80, v80, v197
	v_sub_f32_e32 v81, v81, v197
	v_mfma_f32_32x32x16_bf16 v[218:233], v[202:205], v[118:121], v[218:233]
	v_exp_f32_e32 v78, v78
	v_exp_f32_e32 v79, v79
	v_exp_f32_e32 v80, v80
	v_exp_f32_e32 v81, v81
	v_add_f32_e32 v250, v250, v74
	v_add_f32_e32 v251, v251, v75
	v_add_f32_e32 v252, v252, v76
	v_add_f32_e32 v253, v253, v77
	ds_read_b128 v[198:201], v0 offset:192
	ds_read_b128 v[202:205], v0 offset:224
	ds_read_b128 v[206:209], v0 offset:8896
	ds_read_b128 v[214:217], v0 offset:8928
	s_waitcnt lgkmcnt(4)
	v_mfma_f32_32x32x16_bf16 v[234:249], v[210:213], v[118:121], v[234:249]
	v_add_f32_e32 v250, v250, v78
	v_add_f32_e32 v251, v251, v79
	v_add_f32_e32 v252, v252, v80
	v_add_f32_e32 v253, v253, v81
	v_add_f32_e32 v250, v250, v251
	v_add_f32_e32 v252, v252, v253
	v_add_f32_e32 v250, v250, v252
	v_add_f32_e32 v196, v196, v250
	s_waitcnt lgkmcnt(3)
	v_mfma_f32_32x32x16_bf16 v[218:233], v[198:201], v[122:125], v[218:233]
	v_cvt_pk_bf16_f32 v73, v72, v73
	v_cvt_pk_bf16_f32 v72, v70, v71
	v_cvt_pk_bf16_f32 v71, v68, v69
	v_cvt_pk_bf16_f32 v70, v66, v67
	v_cvt_pk_bf16_f32 v66, v82, v83
	v_cvt_pk_bf16_f32 v67, v84, v85
	v_cvt_pk_bf16_f32 v68, v86, v87
	v_cvt_pk_bf16_f32 v69, v88, v89
	s_waitcnt lgkmcnt(1)
	v_mfma_f32_32x32x16_bf16 v[234:249], v[206:209], v[122:125], v[234:249]
	v_cvt_pk_bf16_f32 v81, v80, v81
	v_cvt_pk_bf16_f32 v80, v78, v79
	v_cvt_pk_bf16_f32 v79, v76, v77
	v_cvt_pk_bf16_f32 v78, v74, v75
	v_cvt_pk_bf16_f32 v74, v90, v91
	v_cvt_pk_bf16_f32 v75, v92, v93
	v_cvt_pk_bf16_f32 v76, v94, v95
	v_cvt_pk_bf16_f32 v77, v96, v97
	v_mfma_f32_32x32x16_bf16 v[218:233], v[202:205], v[126:129], v[218:233]
	s_waitcnt lgkmcnt(0)
	v_mfma_f32_32x32x16_bf16 v[234:249], v[214:217], v[126:129], v[234:249]
	s_cmp_le_i32 s26, s27
	s_cbranch_scc1 .Lff2_z2
	v_cmp_le_i32_e32 vcc, v165, v195
	s_nop 8
	v_cndmask_b32_e32 v234, v155, v234, vcc
	v_cmp_lt_i32_e32 vcc, v163, v195
	s_nop 1
	v_cndmask_b32_e32 v219, v155, v219, vcc
	v_cmp_le_i32_e32 vcc, v163, v195
	s_nop 1
	v_cndmask_b32_e32 v218, v155, v218, vcc
	v_cmp_le_i32_e32 vcc, v166, v195
	s_nop 1
	v_cndmask_b32_e32 v235, v155, v235, vcc
	v_cmp_le_i32_e32 vcc, v167, v195
	s_nop 1
	v_cndmask_b32_e32 v220, v155, v220, vcc
	v_cmp_le_i32_e32 vcc, v168, v195
	s_nop 1
	v_cndmask_b32_e32 v236, v155, v236, vcc
	v_cmp_le_i32_e32 vcc, v169, v195
	s_nop 1
	v_cndmask_b32_e32 v221, v155, v221, vcc
	v_cmp_le_i32_e32 vcc, v170, v195
	s_nop 1
	v_cndmask_b32_e32 v237, v155, v237, vcc
	v_cmp_le_i32_e32 vcc, v171, v195
	s_nop 1
	v_cndmask_b32_e32 v222, v155, v222, vcc
	v_cmp_le_i32_e32 vcc, v172, v195
	s_nop 1
	v_cndmask_b32_e32 v238, v155, v238, vcc
	v_cmp_le_i32_e32 vcc, v173, v195
	s_nop 1
	v_cndmask_b32_e32 v223, v155, v223, vcc
	v_cmp_le_i32_e32 vcc, v174, v195
	s_nop 1
	v_cndmask_b32_e32 v239, v155, v239, vcc
	v_cmp_le_i32_e32 vcc, v175, v195
	s_nop 1
	v_cndmask_b32_e32 v224, v155, v224, vcc
	v_cmp_le_i32_e32 vcc, v176, v195
	s_nop 1
	v_cndmask_b32_e32 v240, v155, v240, vcc
	v_cmp_le_i32_e32 vcc, v177, v195
	s_nop 1
	v_cndmask_b32_e32 v225, v155, v225, vcc
	v_cmp_le_i32_e32 vcc, v178, v195
	s_nop 1
	v_cndmask_b32_e32 v241, v155, v241, vcc
	v_cmp_le_i32_e32 vcc, v179, v195
	s_nop 1
	v_cndmask_b32_e32 v226, v155, v226, vcc
	v_cmp_le_i32_e32 vcc, v180, v195
	s_nop 1
	v_cndmask_b32_e32 v242, v155, v242, vcc
	v_cmp_le_i32_e32 vcc, v181, v195
	s_nop 1
	v_cndmask_b32_e32 v227, v155, v227, vcc
	v_cmp_le_i32_e32 vcc, v182, v195
	s_nop 1
	v_cndmask_b32_e32 v243, v155, v243, vcc
	v_cmp_le_i32_e32 vcc, v183, v195
	s_nop 1
	v_cndmask_b32_e32 v228, v155, v228, vcc
	v_cmp_le_i32_e32 vcc, v184, v195
	s_nop 1
	v_cndmask_b32_e32 v244, v155, v244, vcc
	v_cmp_le_i32_e32 vcc, v185, v195
	s_nop 1
	v_cndmask_b32_e32 v229, v155, v229, vcc
	v_cmp_le_i32_e32 vcc, v186, v195
	s_nop 1
	v_cndmask_b32_e32 v245, v155, v245, vcc
	v_cmp_le_i32_e32 vcc, v187, v195
	s_nop 1
	v_cndmask_b32_e32 v230, v155, v230, vcc
	v_cmp_le_i32_e32 vcc, v188, v195
	s_nop 1
	v_cndmask_b32_e32 v246, v155, v246, vcc
	v_cmp_le_i32_e32 vcc, v189, v195
	s_nop 1
	v_cndmask_b32_e32 v231, v155, v231, vcc
	v_cmp_le_i32_e32 vcc, v190, v195
	s_nop 1
	v_cndmask_b32_e32 v247, v155, v247, vcc
	v_cmp_le_i32_e32 vcc, v191, v195
	s_nop 1
	v_cndmask_b32_e32 v232, v155, v232, vcc
	v_cmp_le_i32_e32 vcc, v192, v195
	s_nop 1
	v_cndmask_b32_e32 v248, v155, v248, vcc
	v_cmp_le_i32_e32 vcc, v193, v195
	s_nop 1
	v_cndmask_b32_e32 v233, v155, v233, vcc
	v_cmp_le_i32_e32 vcc, v194, v195
	s_nop 1
	v_cndmask_b32_e32 v249, v155, v249, vcc

.Lff2_first:
	s_mul_i32 s20, s7, 0x4400
	v_add_u32_e32 v0, s20, v162
	ds_read_b128 v[198:201], v0
	ds_read_b128 v[202:205], v0 offset:32
	ds_read_b128 v[206:209], v0 offset:8704
	ds_read_b128 v[210:213], v0 offset:8736
	v_add_u32_e32 v246, s24, v161
	v_add_u32_e32 v234, 0x12800, v246
	v_add_u32_e32 v235, 0x12880, v246
	v_add_u32_e32 v238, 0x12820, v246
	v_add_u32_e32 v239, 0x128a0, v246
	v_add_u32_e32 v242, 0x12840, v246
	v_add_u32_e32 v243, 0x128c0, v246
	v_add_u32_e32 v247, 0x12860, v246
	v_add_u32_e32 v246, 0x128e0, v246
	ds_read_b128 v[218:221], v234
	ds_read_b128 v[234:237], v235
	ds_read_b128 v[222:225], v238
	ds_read_b128 v[238:241], v239
	ds_read_b128 v[226:229], v242
	ds_read_b128 v[242:245], v243
	ds_read_b128 v[230:233], v247
	ds_read_b128 v[246:249], v246
	s_waitcnt lgkmcnt(1)
	v_mfma_f32_32x32x16_bf16 v[218:233], v[198:201], v[98:101], v[218:233]
	s_waitcnt lgkmcnt(0)
	v_mfma_f32_32x32x16_bf16 v[234:249], v[206:209], v[98:101], v[234:249]
	v_mfma_f32_32x32x16_bf16 v[218:233], v[202:205], v[102:105], v[218:233]
	ds_read_b128 v[198:201], v0 offset:64
	ds_read_b128 v[202:205], v0 offset:96
	ds_read_b128 v[206:209], v0 offset:8768
	ds_read_b128 v[214:217], v0 offset:8800
	v_mfma_f32_32x32x16_bf16 v[234:249], v[210:213], v[102:105], v[234:249]
	s_waitcnt lgkmcnt(3)
	v_mfma_f32_32x32x16_bf16 v[218:233], v[198:201], v[106:109], v[218:233]
	s_waitcnt lgkmcnt(1)
	v_mfma_f32_32x32x16_bf16 v[234:249], v[206:209], v[106:109], v[234:249]
	v_mfma_f32_32x32x16_bf16 v[218:233], v[202:205], v[110:113], v[218:233]
	ds_read_b128 v[198:201], v0 offset:128
	ds_read_b128 v[202:205], v0 offset:160
	ds_read_b128 v[206:209], v0 offset:8832
	ds_read_b128 v[210:213], v0 offset:8864
	s_waitcnt lgkmcnt(4)
	v_mfma_f32_32x32x16_bf16 v[234:249], v[214:217], v[110:113], v[234:249]
	s_waitcnt lgkmcnt(3)
	v_mfma_f32_32x32x16_bf16 v[218:233], v[198:201], v[114:117], v[218:233]
	s_waitcnt lgkmcnt(1)
	v_mfma_f32_32x32x16_bf16 v[234:249], v[206:209], v[114:117], v[234:249]
	v_mfma_f32_32x32x16_bf16 v[218:233], v[202:205], v[118:121], v[218:233]
	ds_read_b128 v[198:201], v0 offset:192
	ds_read_b128 v[202:205], v0 offset:224
	ds_read_b128 v[206:209], v0 offset:8896
	ds_read_b128 v[214:217], v0 offset:8928
	s_waitcnt lgkmcnt(4)
	v_mfma_f32_32x32x16_bf16 v[234:249], v[210:213], v[118:121], v[234:249]
	s_waitcnt lgkmcnt(3)
	v_mfma_f32_32x32x16_bf16 v[218:233], v[198:201], v[122:125], v[218:233]
	s_waitcnt lgkmcnt(1)
	v_mfma_f32_32x32x16_bf16 v[234:249], v[206:209], v[122:125], v[234:249]
	v_mfma_f32_32x32x16_bf16 v[218:233], v[202:205], v[126:129], v[218:233]
	s_waitcnt lgkmcnt(0)
	v_mfma_f32_32x32x16_bf16 v[234:249], v[214:217], v[126:129], v[234:249]
	s_cmp_le_i32 s26, s27
	s_cbranch_scc1 .Lff2_m1
	v_cmp_le_i32_e32 vcc, v165, v195
	s_nop 8
	v_cndmask_b32_e32 v234, v155, v234, vcc
	v_cmp_lt_i32_e32 vcc, v163, v195
	s_nop 1
	v_cndmask_b32_e32 v219, v155, v219, vcc
	v_cmp_le_i32_e32 vcc, v163, v195
	s_nop 1
	v_cndmask_b32_e32 v218, v155, v218, vcc
	v_cmp_le_i32_e32 vcc, v166, v195
	s_nop 1
	v_cndmask_b32_e32 v235, v155, v235, vcc
	v_cmp_le_i32_e32 vcc, v167, v195
	s_nop 1
	v_cndmask_b32_e32 v220, v155, v220, vcc
	v_cmp_le_i32_e32 vcc, v168, v195
	s_nop 1
	v_cndmask_b32_e32 v236, v155, v236, vcc
	v_cmp_le_i32_e32 vcc, v169, v195
	s_nop 1
	v_cndmask_b32_e32 v221, v155, v221, vcc
	v_cmp_le_i32_e32 vcc, v170, v195
	s_nop 1
	v_cndmask_b32_e32 v237, v155, v237, vcc
	v_cmp_le_i32_e32 vcc, v171, v195
	s_nop 1
	v_cndmask_b32_e32 v222, v155, v222, vcc
	v_cmp_le_i32_e32 vcc, v172, v195
	s_nop 1
	v_cndmask_b32_e32 v238, v155, v238, vcc
	v_cmp_le_i32_e32 vcc, v173, v195
	s_nop 1
	v_cndmask_b32_e32 v223, v155, v223, vcc
	v_cmp_le_i32_e32 vcc, v174, v195
	s_nop 1
	v_cndmask_b32_e32 v239, v155, v239, vcc
	v_cmp_le_i32_e32 vcc, v175, v195
	s_nop 1
	v_cndmask_b32_e32 v224, v155, v224, vcc
	v_cmp_le_i32_e32 vcc, v176, v195
	s_nop 1
	v_cndmask_b32_e32 v240, v155, v240, vcc
	v_cmp_le_i32_e32 vcc, v177, v195
	s_nop 1
	v_cndmask_b32_e32 v225, v155, v225, vcc
	v_cmp_le_i32_e32 vcc, v178, v195
	s_nop 1
	v_cndmask_b32_e32 v241, v155, v241, vcc
	v_cmp_le_i32_e32 vcc, v179, v195
	s_nop 1
	v_cndmask_b32_e32 v226, v155, v226, vcc
	v_cmp_le_i32_e32 vcc, v180, v195
	s_nop 1
	v_cndmask_b32_e32 v242, v155, v242, vcc
	v_cmp_le_i32_e32 vcc, v181, v195
	s_nop 1
	v_cndmask_b32_e32 v227, v155, v227, vcc
	v_cmp_le_i32_e32 vcc, v182, v195
	s_nop 1
	v_cndmask_b32_e32 v243, v155, v243, vcc
	v_cmp_le_i32_e32 vcc, v183, v195
	s_nop 1
	v_cndmask_b32_e32 v228, v155, v228, vcc
	v_cmp_le_i32_e32 vcc, v184, v195
	s_nop 1
	v_cndmask_b32_e32 v244, v155, v244, vcc
	v_cmp_le_i32_e32 vcc, v185, v195
	s_nop 1
	v_cndmask_b32_e32 v229, v155, v229, vcc
	v_cmp_le_i32_e32 vcc, v186, v195
	s_nop 1
	v_cndmask_b32_e32 v245, v155, v245, vcc
	v_cmp_le_i32_e32 vcc, v187, v195
	s_nop 1
	v_cndmask_b32_e32 v230, v155, v230, vcc
	v_cmp_le_i32_e32 vcc, v188, v195
	s_nop 1
	v_cndmask_b32_e32 v246, v155, v246, vcc
	v_cmp_le_i32_e32 vcc, v189, v195
	s_nop 1
	v_cndmask_b32_e32 v231, v155, v231, vcc
	v_cmp_le_i32_e32 vcc, v190, v195
	s_nop 1
	v_cndmask_b32_e32 v247, v155, v247, vcc
	v_cmp_le_i32_e32 vcc, v191, v195
	s_nop 1
	v_cndmask_b32_e32 v232, v155, v232, vcc
	v_cmp_le_i32_e32 vcc, v192, v195
	s_nop 1
	v_cndmask_b32_e32 v248, v155, v248, vcc
	v_cmp_le_i32_e32 vcc, v193, v195
	s_nop 1
	v_cndmask_b32_e32 v233, v155, v233, vcc
	v_cmp_le_i32_e32 vcc, v194, v195
	s_nop 1
	v_cndmask_b32_e32 v249, v155, v249, vcc

.Lff2_bar:
	s_waitcnt lgkmcnt(0)
	s_barrier
	s_mov_b32 s71, s70
	s_mov_b32 s70, s69
	s_mov_b32 s69, s68
	s_mov_b32 s68, s71
	s_addk_i32 s24, 0x100
	s_add_i32 s26, s26, 64
	s_add_i32 s25, s25, 1
	s_cmp_lg_u32 s6, s24
	v_subrev_u32_e32 v195, 64, v195
	s_cbranch_scc0 .Lff2_exit
	s_branch .LBB0_657

.LBB0_662:
	s_cmp_gt_i32 s57, 8
	s_cselect_b64 s[0:1], -1, 0
	s_and_b64 s[4:5], s[10:11], s[0:1]
	s_andn2_b64 vcc, exec, s[4:5]
	s_cbranch_vccnz .LBB0_716
	s_waitcnt vmcnt(0)
	s_barrier
	s_and_saveexec_b64 s[4:5], s[8:9]
	s_cbranch_execz .LBB0_715
	s_add_i32 s6, 0, 0x23000
	v_mov_b32_e32 v0, s6
	s_waitcnt vmcnt(0) expcnt(0) lgkmcnt(0)
	ds_read_b32 v2, v0
	s_add_i32 s6, 0, 0x23004
	v_mov_b32_e32 v0, s6
	ds_read_b32 v0, v0
	s_waitcnt lgkmcnt(1)
	v_cmp_ne_u32_e32 vcc, 0, v2
	s_cbranch_vccnz .LBB0_679
	v_readlane_b32 s6, v254, 0
	s_mul_i32 s33, s59, s6
	s_add_u32 s6, s54, 0x80200
	s_addc_u32 s7, s55, 0
	s_add_u32 s10, s54, 0x80400
	s_addc_u32 s11, s55, 0
	s_add_u32 s12, s54, 0x80500
	s_addc_u32 s13, s55, 0
	s_add_u32 s14, s54, 0x80600
	s_addc_u32 s15, s55, 0
	s_add_u32 s16, s54, 0x80700
	s_addc_u32 s17, s55, 0
	s_add_u32 s18, s54, 0x80800
	s_addc_u32 s19, s55, 0
	s_add_u32 s20, s54, 0x80900
	s_addc_u32 s21, s55, 0
	s_add_u32 s22, s54, 0x80a00
	s_addc_u32 s23, s55, 0
	s_add_u32 s24, s54, 0x80b00
	s_addc_u32 s25, s55, 0
	s_add_u32 s26, s54, 0x80c00
	s_addc_u32 s27, s55, 0
	s_add_u32 s34, s54, 0x80d00
	s_addc_u32 s35, s55, 0
	s_add_u32 s36, s54, 0x80e00
	s_addc_u32 s37, s55, 0
	s_add_u32 s38, s54, 0x80f00
	s_addc_u32 s39, s55, 0
	s_add_u32 s40, s54, 0x81000
	s_addc_u32 s41, s55, 0
	s_add_u32 s42, s54, 0x81100
	s_addc_u32 s43, s55, 0
	s_add_u32 s44, s54, 0x81200
	s_addc_u32 s45, s55, 0
	s_add_u32 s46, s54, 0x81300
	s_mul_i32 s33, s33, s58
	s_addc_u32 s47, s55, 0
	s_mov_b32 s57, 1
	v_mov_b32_e32 v16, 0
	s_branch .LBB0_667

.LBB0_716:
	s_cmp_lt_i32 s56, 9
	s_cselect_b64 s[4:5], -1, 0
	s_and_b64 s[0:1], s[4:5], s[0:1]
	s_andn2_b64 vcc, exec, s[0:1]
	s_cbranch_vccnz .LBB0_885
	s_add_u32 s60, s54, 0x1b600000
	s_addc_u32 s61, s55, 0
	s_add_u32 s62, s54, 0x4500000
	s_addc_u32 s63, s55, 0
	s_add_u32 s10, s54, 0x5600000
	s_addc_u32 s11, s55, 0
	s_add_u32 s12, s54, 0x20000
	s_addc_u32 s13, s55, 0
	s_mov_b64 s[0:1], -1
	s_and_b64 vcc, exec, s[30:31]
	s_cbranch_vccz .LBB0_840
	s_cmpk_lt_i32 s2, 0x200
	s_cselect_b64 s[0:1], -1, 0
	s_cmpk_gt_i32 s2, 0x1ff
	v_readfirstlane_b32 s4, v255
	s_cbranch_scc1 .LBB0_720
	s_ashr_i32 s5, s2, 31
	s_lshr_b32 s5, s5, 29
	s_add_i32 s5, s2, s5
	s_ashr_i32 s34, s5, 3
	s_and_b32 s5, s5, -8
	s_sub_i32 s6, s2, s5
.LBB0_720:
	s_andn2_b64 vcc, exec, s[0:1]
	s_cbranch_vccnz .LBB0_784
	v_lshrrev_b32_e32 v2, 1, v255
	v_lshrrev_b32_e32 v3, 5, v255
	v_and_b32_e32 v2, 24, v2
	v_and_b32_e32 v3, 4, v3
	v_bfe_u32 v4, v255, 2, 2
	v_lshlrev_b32_e32 v0, 4, v255
	v_and_b32_e32 v1, 32, v255
	s_waitcnt vmcnt(4)
	v_bfe_u32 v10, v255, 2, 4
	v_or3_b32 v2, v3, v4, v2
	v_lshrrev_b32_e32 v3, 3, v255
	s_movk_i32 s1, 0x70
	v_bitop3_b32 v8, v0, v1, 48 bitop3:0x6c
	v_and_b32_e32 v9, 64, v255
	v_and_or_b32 v4, v3, s1, v10
	s_movk_i32 s1, 0x60
	s_waitcnt vmcnt(3)
	v_add_u32_e32 v11, 0x2000, v0
	v_or_b32_e32 v1, v8, v9
	v_and_or_b32 v3, v3, s1, v2
	v_lshrrev_b32_e32 v0, 7, v11
	s_movk_i32 s1, 0xf0
	v_lshl_or_b32 v158, v3, 12, v1
	v_and_or_b32 v3, v0, s1, v10
	s_movk_i32 s1, 0xe0
	v_and_or_b32 v0, v0, s1, v2
	s_lshr_b32 s1, s4, 6
	s_ashr_i32 s35, s34, 31
	s_ashr_i32 s7, s6, 31
	s_lshr_b32 s0, s4, 8
	s_lshl_b32 s33, s1, 10
	s_lshl_b64 s[14:15], s[34:35], 20
	s_lshl_b64 s[16:17], s[6:7], 20
	s_add_u32 s38, s62, s16
	s_addc_u32 s39, s63, s17
	s_add_i32 s42, s33, 0
	s_add_i32 m0, s42, 0x10000
	v_lshl_or_b32 v162, v0, 12, v1
	global_load_lds_dwordx4 v158, s[38:39]
	s_add_i32 m0, s42, 0x12000
	s_add_u32 s16, s38, 0x80000
	global_load_lds_dwordx4 v162, s[38:39]
	s_addc_u32 s17, s39, 0
	s_add_i32 m0, s42, 0x14000
	v_lshl_or_b32 v156, v4, 12, v1
	global_load_lds_dwordx4 v158, s[16:17]
	s_add_i32 m0, s42, 0x16000
	s_add_u32 s36, s60, s14
	s_addc_u32 s37, s61, s15
	s_add_i32 s43, s42, 0x2000
	global_load_lds_dwordx4 v162, s[16:17]
	s_mov_b32 m0, s42
	s_add_u32 s14, s36, 0x80000
	v_lshl_or_b32 v160, v3, 12, v1
	global_load_lds_dwordx4 v156, s[36:37]
	s_mov_b32 m0, s43
	s_addc_u32 s15, s37, 0
	s_add_i32 s44, s42, 0x4000
	global_load_lds_dwordx4 v160, s[36:37]
	s_mov_b32 m0, s44
	s_add_i32 s45, s42, 0x6000
	global_load_lds_dwordx4 v156, s[14:15]
	s_mov_b32 m0, s45
	v_mov_b32_e32 v159, 0
	global_load_lds_dwordx4 v160, s[14:15]
	v_mov_b32_e32 v163, v159
	v_mov_b32_e32 v157, v159
	v_mov_b32_e32 v161, v159
	s_cmp_eq_u32 s0, 1
	s_mov_b32 s46, 0
	v_lshl_add_u64 v[6:7], s[38:39], 0, v[158:159]
	v_lshl_add_u64 v[4:5], s[38:39], 0, v[162:163]
	v_lshl_add_u64 v[0:1], s[36:37], 0, v[156:157]
	s_cselect_b64 s[14:15], -1, 0
	s_cmp_lg_u32 s0, 1
	v_lshl_add_u64 v[2:3], s[36:37], 0, v[160:161]
	s_cbranch_scc1 .LBB0_723
	s_barrier
.LBB0_723:
	s_lshl_b32 s1, s1, 5
	s_mov_b64 s[16:17], 0x80
	s_and_b32 s7, s1, 0x60
	s_add_i32 m0, s42, 0x18000
	v_lshl_add_u64 v[6:7], v[6:7], 0, s[16:17]
	s_lshl_b32 s5, s0, 13
	s_lshl_b32 s1, s7, 7
	s_waitcnt vmcnt(2)
	s_barrier
	global_load_lds_dwordx4 v[6:7], off
	v_lshl_add_u64 v[4:5], v[4:5], 0, s[16:17]
	s_add_i32 m0, s42, 0x1a000
	s_add_i32 s47, s42, 0x8000
	s_add_i32 s48, s42, 0xa000
	global_load_lds_dwordx4 v[4:5], off
	v_lshl_add_u64 v[0:1], v[0:1], 0, s[16:17]
	s_mov_b32 m0, s47
	s_add_u32 s18, s38, 0x80080
	global_load_lds_dwordx4 v[0:1], off
	v_lshl_add_u64 v[0:1], v[2:3], 0, s[16:17]
	s_mov_b32 m0, s48
	s_addc_u32 s19, s39, 0
	global_load_lds_dwordx4 v[0:1], off
	s_add_i32 m0, s42, 0x1c000
	v_lshl_add_u64 v[0:1], s[18:19], 0, v[158:159]
	global_load_lds_dwordx4 v[0:1], off
	v_lshl_add_u64 v[0:1], s[18:19], 0, v[162:163]
	s_add_i32 m0, s42, 0x1e000
	v_lshlrev_b32_e32 v3, 2, v255
	global_load_lds_dwordx4 v[0:1], off
	v_and_b32_e32 v0, 15, v255
	v_bfe_u32 v1, v255, 4, 2
	v_lshl_or_b32 v190, s0, 6, v0
	v_lshlrev_b32_e32 v2, 4, v1
	v_lshlrev_b32_e32 v4, 6, v255
	s_movk_i32 s0, 0x3c0
	v_lshl_or_b32 v0, v0, 6, v2
	v_and_b32_e32 v3, 32, v3
	v_and_or_b32 v2, v4, s0, v2
	v_bitop3_b32 v191, s1, v2, v3 bitop3:0xf6
	v_cmp_eq_u32_e64 s[0:1], 0, v1
	v_lshl_or_b32 v192, v1, 3, s7
	v_lshlrev_b32_e32 v1, 9, v255
	v_and_b32_e32 v1, 0x70000, v1
	v_lshlrev_b32_e32 v2, 12, v10
	s_cmpk_lt_u32 s4, 0x100
	v_or3_b32 v1, v8, v1, v2
	s_cselect_b64 s[18:19], -1, 0
	s_ashr_i32 s49, s58, 31
	s_ashr_i32 s51, s2, 31
	v_add_u32_e32 v164, v1, v9
	v_lshlrev_b32_e32 v1, 5, v11
	v_bitop3_b32 v0, v0, s5, v3 bitop3:0xde
	s_waitcnt vmcnt(6)
	s_cmp_lg_u64 s[52:53], 0
	v_and_b32_e32 v1, 0xf0000, v1
	s_cselect_b64 s[20:21], -1, 0
	v_or3_b32 v1, v8, v1, v2
	s_add_i32 s56, 0, 0x10000
	s_add_i32 s57, 0, 0x14000
	v_add_u32_e32 v195, 0, v0
	v_mbcnt_lo_u32_b32 v0, -1, 0
	s_mov_b32 s50, s58
	v_mov_b32_e32 v165, v159
	v_add_u32_e32 v166, v1, v9
	v_mov_b32_e32 v167, v159
	v_mov_b64_e32 v[168:169], 0x200
	v_mov_b64_e32 v[170:171], 0x1ff
	v_add_u32_e32 v193, s56, v191
	v_add_u32_e32 v194, s57, v191
	v_mbcnt_hi_u32_b32 v196, -1, v0
	s_barrier
	s_branch .LBB0_726

.LBB0_784:
	s_waitcnt vmcnt(0)
	s_waitcnt lgkmcnt(0)
	s_barrier
	s_and_saveexec_b64 s[0:1], s[8:9]
	s_cbranch_execz .LBB0_836
	s_add_i32 s4, 0, 0x23000
	v_mov_b32_e32 v0, s4
	s_waitcnt vmcnt(0) expcnt(0) lgkmcnt(0)
	ds_read_b32 v2, v0
	s_add_i32 s4, 0, 0x23004
	v_mov_b32_e32 v0, s4
	ds_read_b32 v0, v0
	s_waitcnt lgkmcnt(1)
	v_cmp_ne_u32_e32 vcc, 0, v2
	s_cbranch_vccnz .LBB0_800
	v_readlane_b32 s4, v254, 0
	s_mul_i32 s33, s59, s4
	s_add_u32 s4, s54, 0x80200
	s_addc_u32 s5, s55, 0
	s_add_u32 s6, s54, 0x80400
	s_addc_u32 s7, s55, 0
	s_add_u32 s14, s54, 0x80500
	s_addc_u32 s15, s55, 0
	s_add_u32 s16, s54, 0x80600
	s_addc_u32 s17, s55, 0
	s_add_u32 s18, s54, 0x80700
	s_addc_u32 s19, s55, 0
	s_add_u32 s20, s54, 0x80800
	s_addc_u32 s21, s55, 0
	s_add_u32 s22, s54, 0x80900
	s_addc_u32 s23, s55, 0
	s_add_u32 s24, s54, 0x80a00
	s_addc_u32 s25, s55, 0
	s_add_u32 s26, s54, 0x80b00
	s_addc_u32 s27, s55, 0
	s_add_u32 s30, s54, 0x80c00
	s_addc_u32 s31, s55, 0
	s_add_u32 s34, s54, 0x80d00
	s_addc_u32 s35, s55, 0
	s_add_u32 s36, s54, 0x80e00
	s_addc_u32 s37, s55, 0
	s_add_u32 s38, s54, 0x80f00
	s_addc_u32 s39, s55, 0
	s_add_u32 s40, s54, 0x81000
	s_addc_u32 s41, s55, 0
	s_add_u32 s42, s54, 0x81100
	s_addc_u32 s43, s55, 0
	s_add_u32 s44, s54, 0x81200
	s_addc_u32 s45, s55, 0
	s_add_u32 s46, s54, 0x81300
	s_mul_i32 s33, s33, s58
	s_addc_u32 s47, s55, 0
	s_mov_b32 s59, 1
	v_mov_b32_e32 v16, 0
	s_branch .LBB0_788

.LBB0_836:
	s_or_b64 exec, exec, s[0:1]
	s_waitcnt lgkmcnt(0)
	v_lshrrev_b32_e32 v0, 6, v255
	v_lshl_add_u32 v0, s2, 3, v0
	s_movk_i32 s0, 0x4000
	v_cmp_gt_i32_e32 vcc, s0, v0
	s_barrier
	s_and_saveexec_b64 s[4:5], vcc
	s_cbranch_execz .LBB0_839
	v_and_b32_e32 v1, 63, v255
	v_lshlrev_b32_e32 v14, 4, v1
	v_mov_b32_e32 v15, 0
	v_lshl_add_u64 v[2:3], s[66:67], 0, v[14:15]
	s_mov_b64 s[14:15], 0x1400
	v_ashrrev_i32_e32 v1, 31, v0
	v_lshl_add_u64 v[6:7], v[2:3], 0, s[14:15]
	s_mov_b64 s[14:15], 0x1800
	v_lshlrev_b64 v[16:17], 13, v[0:1]
	s_lshl_b32 s6, s58, 3
	v_lshl_add_u64 v[8:9], v[2:3], 0, s[14:15]
	s_mov_b64 s[14:15], 0x1c00
	v_or_b32_e32 v16, v16, v14
	s_mov_b64 s[0:1], 0x1000
	s_waitcnt vmcnt(3)
	v_lshl_add_u64 v[10:11], v[2:3], 0, s[14:15]
	v_lshl_add_u64 v[12:13], v[0:1], 2, s[54:55]
	s_mov_b64 s[14:15], 0x20000
	s_ashr_i32 s7, s6, 31
	v_lshl_add_u64 v[14:15], s[52:53], 0, v[16:17]
	v_lshl_add_u64 v[4:5], v[2:3], 0, s[0:1]
	v_lshl_add_u64 v[12:13], v[12:13], 0, s[14:15]
	s_lshl_b64 s[14:15], s[6:7], 2
	v_lshl_add_u64 v[14:15], v[14:15], 0, s[0:1]
	s_lshl_b64 s[16:17], s[6:7], 13
	s_mov_b64 s[18:19], 0
	v_mov_b32_e32 v1, 0x358637bd
	s_mov_b32 s3, 0xf800000
	v_mov_b32_e32 v16, 0x260
	s_movk_i32 s7, 0x3fff

.LBB0_840:
	s_and_b64 vcc, exec, s[0:1]
	s_cbranch_vccz .LBB0_885
	s_cmpk_lt_i32 s2, 0x200
	s_cselect_b64 s[0:1], -1, 0
	s_cmpk_gt_i32 s2, 0x1ff
	v_readfirstlane_b32 s4, v255
	s_cbranch_scc1 .LBB0_843
	s_ashr_i32 s3, s2, 31
	s_lshr_b32 s3, s3, 29
	s_add_i32 s3, s2, s3
	s_ashr_i32 s6, s3, 3
	s_and_b32 s3, s3, -8
	s_sub_i32 s28, s2, s3
.LBB0_843:
	s_andn2_b64 vcc, exec, s[0:1]
	s_cbranch_vccnz .LBB0_885
	v_lshrrev_b32_e32 v2, 1, v255
	v_lshrrev_b32_e32 v3, 5, v255
	v_and_b32_e32 v2, 24, v2
	v_and_b32_e32 v3, 4, v3
	v_bfe_u32 v4, v255, 2, 2
	v_lshlrev_b32_e32 v0, 4, v255
	v_and_b32_e32 v1, 32, v255
	s_waitcnt vmcnt(4)
	v_bfe_u32 v10, v255, 2, 4
	v_or3_b32 v2, v3, v4, v2
	v_lshrrev_b32_e32 v3, 3, v255
	s_movk_i32 s1, 0x70
	v_bitop3_b32 v8, v0, v1, 48 bitop3:0x6c
	v_and_b32_e32 v9, 64, v255
	v_and_or_b32 v4, v3, s1, v10
	s_movk_i32 s1, 0x60
	s_waitcnt vmcnt(3)
	v_add_u32_e32 v11, 0x2000, v0
	v_or_b32_e32 v1, v8, v9
	v_and_or_b32 v3, v3, s1, v2
	v_lshrrev_b32_e32 v0, 7, v11
	s_movk_i32 s1, 0xf0
	v_lshl_or_b32 v154, v3, 12, v1
	v_and_or_b32 v3, v0, s1, v10
	s_movk_i32 s1, 0xe0
	v_and_or_b32 v0, v0, s1, v2
	s_lshr_b32 s1, s4, 6
	s_ashr_i32 s7, s6, 31
	s_ashr_i32 s29, s28, 31
	s_lshr_b32 s0, s4, 8
	s_lshl_b32 s3, s1, 10
	s_lshl_b64 s[14:15], s[6:7], 20
	s_lshl_b64 s[16:17], s[28:29], 20
	s_add_u32 s34, s62, s16
	s_addc_u32 s35, s63, s17
	s_add_i32 s33, s3, 0
	s_add_i32 m0, s33, 0x10000
	v_lshl_or_b32 v158, v0, 12, v1
	global_load_lds_dwordx4 v154, s[34:35]
	s_add_i32 m0, s33, 0x12000
	s_add_u32 s16, s34, 0x80000
	global_load_lds_dwordx4 v158, s[34:35]
	s_addc_u32 s17, s35, 0
	s_add_i32 m0, s33, 0x14000
	v_lshl_or_b32 v152, v4, 12, v1
	global_load_lds_dwordx4 v154, s[16:17]
	s_add_i32 m0, s33, 0x16000
	s_add_u32 s30, s60, s14
	s_addc_u32 s31, s61, s15
	s_add_i32 s38, s33, 0x2000
	global_load_lds_dwordx4 v158, s[16:17]
	s_mov_b32 m0, s33
	s_add_u32 s14, s30, 0x80000
	v_lshl_or_b32 v156, v3, 12, v1
	global_load_lds_dwordx4 v152, s[30:31]
	s_mov_b32 m0, s38
	s_addc_u32 s15, s31, 0
	s_add_i32 s39, s33, 0x4000
	global_load_lds_dwordx4 v156, s[30:31]
	s_mov_b32 m0, s39
	s_add_i32 s40, s33, 0x6000
	global_load_lds_dwordx4 v152, s[14:15]
	s_mov_b32 m0, s40
	v_mov_b32_e32 v155, 0
	global_load_lds_dwordx4 v156, s[14:15]
	v_mov_b32_e32 v159, v155
	v_mov_b32_e32 v153, v155
	v_mov_b32_e32 v157, v155
	s_cmp_eq_u32 s0, 1
	s_mov_b32 s41, 0
	v_lshl_add_u64 v[6:7], s[34:35], 0, v[154:155]
	v_lshl_add_u64 v[4:5], s[34:35], 0, v[158:159]
	v_lshl_add_u64 v[0:1], s[30:31], 0, v[152:153]
	s_cselect_b64 s[14:15], -1, 0
	s_cmp_lg_u32 s0, 1
	v_lshl_add_u64 v[2:3], s[30:31], 0, v[156:157]
	s_cbranch_scc1 .LBB0_846
	s_barrier
.LBB0_846:
	s_add_u32 s42, s54, 0x50000
	s_addc_u32 s43, s55, 0
	s_lshl_b32 s1, s1, 5
	s_mov_b64 s[16:17], 0x80
	s_and_b32 s7, s1, 0x60
	s_add_i32 m0, s33, 0x18000
	v_lshl_add_u64 v[6:7], v[6:7], 0, s[16:17]
	s_lshl_b32 s5, s0, 13
	s_lshl_b32 s1, s7, 7
	s_waitcnt vmcnt(2)
	s_barrier
	global_load_lds_dwordx4 v[6:7], off
	v_lshl_add_u64 v[4:5], v[4:5], 0, s[16:17]
	s_add_i32 m0, s33, 0x1a000
	s_add_i32 s44, s33, 0x8000
	s_add_i32 s45, s33, 0xa000
	global_load_lds_dwordx4 v[4:5], off
	v_lshl_add_u64 v[0:1], v[0:1], 0, s[16:17]
	s_mov_b32 m0, s44
	s_add_u32 s18, s34, 0x80080
	global_load_lds_dwordx4 v[0:1], off
	v_lshl_add_u64 v[0:1], v[2:3], 0, s[16:17]
	s_mov_b32 m0, s45
	s_addc_u32 s19, s35, 0
	global_load_lds_dwordx4 v[0:1], off
	s_add_i32 m0, s33, 0x1c000
	v_lshl_add_u64 v[0:1], s[18:19], 0, v[154:155]
	global_load_lds_dwordx4 v[0:1], off
	v_lshl_add_u64 v[0:1], s[18:19], 0, v[158:159]
	s_add_i32 m0, s33, 0x1e000
	v_lshlrev_b32_e32 v3, 2, v255
	global_load_lds_dwordx4 v[0:1], off
	v_and_b32_e32 v0, 15, v255
	v_bfe_u32 v1, v255, 4, 2
	v_lshl_or_b32 v206, s0, 6, v0
	v_lshlrev_b32_e32 v2, 4, v1
	v_lshlrev_b32_e32 v4, 6, v255
	s_movk_i32 s0, 0x3c0
	v_lshl_or_b32 v0, v0, 6, v2
	v_and_b32_e32 v3, 32, v3
	v_and_or_b32 v2, v4, s0, v2
	v_bitop3_b32 v207, s1, v2, v3 bitop3:0xf6
	v_cmp_eq_u32_e64 s[0:1], 0, v1
	v_lshl_or_b32 v208, v1, 3, s7
	v_lshlrev_b32_e32 v1, 9, v255
	v_and_b32_e32 v1, 0x70000, v1
	v_lshlrev_b32_e32 v2, 12, v10
	v_or3_b32 v1, v8, v1, v2
	v_add_u32_e32 v160, v1, v9
	v_lshlrev_b32_e32 v1, 5, v11
	v_bitop3_b32 v0, v0, s5, v3 bitop3:0xde
	s_waitcnt vmcnt(6)
	s_cmpk_lt_u32 s4, 0x100
	v_and_b32_e32 v1, 0xf0000, v1
	s_cselect_b64 s[18:19], -1, 0
	v_or3_b32 v1, v8, v1, v2
	s_add_i32 s48, 0, 0x10000
	s_add_i32 s49, 0, 0x14000
	v_add_u32_e32 v211, 0, v0
	v_mbcnt_lo_u32_b32 v0, -1, 0
	s_ashr_i32 s46, s58, 31
	s_ashr_i32 s47, s2, 31
	v_mov_b32_e32 v161, v155
	v_add_u32_e32 v162, v1, v9
	v_mov_b32_e32 v163, v155
	v_mov_b64_e32 v[164:165], 0x200
	v_mov_b64_e32 v[166:167], 0x1ff
	v_add_u32_e32 v209, s48, v207
	v_add_u32_e32 v210, s49, v207
	v_mbcnt_hi_u32_b32 v212, -1, v0
	v_mov_b32_e32 v213, 0x358637bd
	s_mov_b32 s50, 0xf800000
	v_mov_b32_e32 v214, 0x260
	s_barrier
	s_branch .LBB0_849

	.amdhsa_kernel _Z4mega4Args
		.amdhsa_group_segment_fixed_size 0
		.amdhsa_private_segment_fixed_size 0
		.amdhsa_kernarg_size 440
		.amdhsa_user_sgpr_count 2
		.amdhsa_user_sgpr_dispatch_ptr 0
		.amdhsa_user_sgpr_queue_ptr 0
		.amdhsa_user_sgpr_kernarg_segment_ptr 1
		.amdhsa_user_sgpr_dispatch_id 0
		.amdhsa_user_sgpr_kernarg_preload_length 0
		.amdhsa_user_sgpr_kernarg_preload_offset 0
		.amdhsa_user_sgpr_private_segment_size 0
		.amdhsa_uses_dynamic_stack 0
		.amdhsa_enable_private_segment 0
		.amdhsa_system_sgpr_workgroup_id_x 1
		.amdhsa_system_sgpr_workgroup_id_y 0
		.amdhsa_system_sgpr_workgroup_id_z 0
		.amdhsa_system_sgpr_workgroup_info 0
		.amdhsa_system_vgpr_workitem_id 2
		.amdhsa_next_free_vgpr 256
		.amdhsa_next_free_sgpr 98
		.amdhsa_accum_offset 256
		.amdhsa_reserve_vcc 1
		.amdhsa_float_round_mode_32 0
		.amdhsa_float_round_mode_16_64 0
		.amdhsa_float_denorm_mode_32 3
		.amdhsa_float_denorm_mode_16_64 3
		.amdhsa_dx10_clamp 1
		.amdhsa_ieee_mode 1
		.amdhsa_fp16_overflow 0
		.amdhsa_tg_split 0
		.amdhsa_exception_fp_ieee_invalid_op 0
		.amdhsa_exception_fp_denorm_src 0
		.amdhsa_exception_fp_ieee_div_zero 0
		.amdhsa_exception_fp_ieee_overflow 0
		.amdhsa_exception_fp_ieee_underflow 0
		.amdhsa_exception_fp_ieee_inexact 0
		.amdhsa_exception_int_div_zero 0
	.end_amdhsa_kernel

amdhsa.kernels:
  - .agpr_count:     0
    .args:
      - .offset:         0
        .size:           184
        .value_kind:     by_value
      - .offset:         184
        .size:           4
        .value_kind:     hidden_block_count_x
      - .offset:         188
        .size:           4
        .value_kind:     hidden_block_count_y
      - .offset:         192
        .size:           4
        .value_kind:     hidden_block_count_z
      - .offset:         196
        .size:           2
        .value_kind:     hidden_group_size_x
      - .offset:         198
        .size:           2
        .value_kind:     hidden_group_size_y
      - .offset:         200
        .size:           2
        .value_kind:     hidden_group_size_z
      - .offset:         202
        .size:           2
        .value_kind:     hidden_remainder_x
      - .offset:         204
        .size:           2
        .value_kind:     hidden_remainder_y
      - .offset:         206
        .size:           2
        .value_kind:     hidden_remainder_z
      - .offset:         224
        .size:           8
        .value_kind:     hidden_global_offset_x
      - .offset:         232
        .size:           8
        .value_kind:     hidden_global_offset_y
      - .offset:         240
        .size:           8
        .value_kind:     hidden_global_offset_z
      - .offset:         248
        .size:           2
        .value_kind:     hidden_grid_dims
      - .offset:         272
        .size:           8
        .value_kind:     hidden_multigrid_sync_arg
      - .offset:         304
        .size:           4
        .value_kind:     hidden_dynamic_lds_size
    .group_segment_fixed_size: 0
    .kernarg_segment_align: 8
    .kernarg_segment_size: 440
    .language:       OpenCL C
    .language_version:
      - 2
      - 0
    .max_flat_workgroup_size: 512
    .name:           _Z4mega4Args
    .private_segment_fixed_size: 0
    .sgpr_count:     104
    .sgpr_spill_count: 1
    .symbol:         _Z4mega4Args.kd
    .uniform_work_group_size: 1
    .uses_dynamic_stack: false
    .vgpr_count:     256
    .vgpr_spill_count: 0
    .wavefront_size: 64
